# adds batched adaLN GEMV (48 loads in flight) and hand-written RMSNorm row passes (3 rows prefetched, DPP reduction) on top of the scan loop rewrite
# speedup vs baseline: 1.0030x; 1.0030x over previous
.LBB0_129:
	s_cmp_gt_i32 s42, 1
	s_waitcnt lgkmcnt(0)
	s_cselect_b64 s[0:1], -1, 0
	s_cmp_lt_i32 s43, 2
	s_cselect_b64 s[2:3], -1, 0
	s_or_b64 s[0:1], s[0:1], s[2:3]
	s_and_b64 vcc, exec, s[0:1]
	s_cbranch_vccnz .LBB0_191
	s_lshl_b32 s0, s80, 3
	s_abs_i32 s5, s0
	v_cvt_f32_u32_e32 v0, s5
	v_readlane_b32 s2, v254, 0
	v_readlane_b32 s3, v254, 1
	v_readlane_b32 s4, v254, 2
	v_rcp_iflag_f32_e32 v0, v0
	s_add_i32 s1, s0, 0x7fff
	v_mul_f32_e32 v0, 0x4f7ffffe, v0
	v_cvt_u32_f32_e32 v0, v0
	v_mbcnt_lo_u32_b32 v16, -1, 0
	v_mbcnt_hi_u32_b32 v16, -1, v16
	s_nop 0
	v_lshl_add_u32 v1, s4, 6, v16
	s_xor_b32 s4, s1, s0
	s_sub_i32 s0, 0xffff8001, s0
	s_max_i32 s0, s1, s0
	s_sub_i32 s1, 0, s5
	v_readfirstlane_b32 s6, v0
	s_mul_i32 s1, s1, s6
	s_mul_hi_u32 s1, s6, s1
	s_add_i32 s6, s6, s1
	s_mul_hi_u32 s1, s0, s6
	s_mul_i32 s6, s1, s5
	s_sub_i32 s0, s0, s6
	s_ashr_i32 s4, s4, 31
	s_add_i32 s6, s1, 1
	s_sub_i32 s7, s0, s5
	s_cmp_ge_u32 s0, s5
	s_cselect_b32 s1, s6, s1
	s_cselect_b32 s0, s7, s0
	s_add_i32 s6, s1, 1
	s_cmp_ge_u32 s0, s5
	s_cselect_b32 s0, s6, s1
	v_ashrrev_i32_e32 v1, 6, v1
	s_xor_b32 s0, s0, s4
	v_lshl_add_u32 v1, s82, 3, v1
	s_sub_i32 s0, s0, s4
	v_mul_lo_u32 v48, v1, s0
	v_add_u32_e32 v0, s0, v48
	v_min_i32_e32 v76, 0x8000, v0
	v_cmp_lt_i32_e32 vcc, v48, v76
	s_and_saveexec_b64 s[0:1], vcc
	s_cbranch_execz .LBB0_137
	s_cmp_lg_u32 s80, 0x100
	s_cbranch_scc1 .Lnorm_orig_0
	v_readlane_b32 s2, v254, 0
	v_readlane_b32 s3, v254, 1
	v_readfirstlane_b32 s10, v48
	s_nop 3
	s_load_dwordx2 s[4:5], s[2:3], 0x0
	s_load_dwordx2 s[8:9], s[2:3], 0x20
	s_load_dwordx2 s[6:7], s[2:3], 0xe0
	v_mbcnt_lo_u32_b32 v66, -1, 0
	v_mbcnt_hi_u32_b32 v66, -1, v66
	v_lshlrev_b32_e32 v67, 3, v66
	v_lshlrev_b32_e32 v66, 4, v66
	v_mov_b32_e32 v74, 0x358637bd
	s_waitcnt lgkmcnt(0)
	s_mov_b32 s2, s10
	s_add_u32 s3, s2, 0
	s_lshl_b32 s3, s3, 12
	s_add_u32 s4, s4, s3
	s_addc_u32 s5, s5, 0
	global_load_dwordx4 v[50:53], v66, s[8:9] offset:0
	global_load_dwordx4 v[54:57], v66, s[8:9] offset:1024
	global_load_dwordx4 v[58:61], v66, s[8:9] offset:2048
	global_load_dwordx4 v[62:65], v66, s[8:9] offset:3072
	s_add_u32 s3, s2, 0
	s_lshr_b32 s3, s3, 12
	s_mul_i32 s3, s3, 0x6000
	s_add_u32 s10, s6, s3
	s_addc_u32 s11, s7, 0
	s_add_u32 s10, s10, 0x780000
	s_addc_u32 s11, s11, 0
	s_add_u32 s8, s10, 4096
	s_addc_u32 s9, s11, 0
	global_load_dwordx4 v[32:35], v66, s[8:9] offset:0
	global_load_dwordx4 v[36:39], v66, s[8:9] offset:1024
	global_load_dwordx4 v[40:43], v66, s[8:9] offset:2048
	global_load_dwordx4 v[44:47], v66, s[8:9] offset:3072
	s_add_u32 s10, s10, 0
	s_addc_u32 s11, s11, 0
	global_load_dwordx4 v[78:81], v66, s[10:11] offset:0
	global_load_dwordx4 v[82:85], v66, s[10:11] offset:1024
	global_load_dwordx4 v[86:89], v66, s[10:11] offset:2048
	global_load_dwordx4 v[90:93], v66, s[10:11] offset:3072
	s_add_u32 s6, s6, 0x2d00000
	s_addc_u32 s7, s7, 0
	s_lshl_b32 s3, s2, 11
	s_add_u32 s6, s6, s3
	s_addc_u32 s7, s7, 0
	global_load_dwordx4 v[0:3], v66, s[4:5] offset:0
	global_load_dwordx4 v[4:7], v66, s[4:5] offset:1024
	global_load_dwordx4 v[8:11], v66, s[4:5] offset:2048
	global_load_dwordx4 v[12:15], v66, s[4:5] offset:3072
	s_add_u32 s4, s4, 0x1000
	s_addc_u32 s5, s5, 0
	global_load_dwordx4 v[16:19], v66, s[4:5] offset:0
	global_load_dwordx4 v[20:23], v66, s[4:5] offset:1024
	global_load_dwordx4 v[24:27], v66, s[4:5] offset:2048
	global_load_dwordx4 v[28:31], v66, s[4:5] offset:3072
	s_add_u32 s4, s4, 0x1000
	s_addc_u32 s5, s5, 0
	s_waitcnt vmcnt(8)
	v_pk_add_f32 v[32:33], v[32:33], 1.0 op_sel_hi:[1,0]
	v_pk_add_f32 v[34:35], v[34:35], 1.0 op_sel_hi:[1,0]
	v_pk_add_f32 v[36:37], v[36:37], 1.0 op_sel_hi:[1,0]
	v_pk_add_f32 v[38:39], v[38:39], 1.0 op_sel_hi:[1,0]
	v_pk_add_f32 v[40:41], v[40:41], 1.0 op_sel_hi:[1,0]
	v_pk_add_f32 v[42:43], v[42:43], 1.0 op_sel_hi:[1,0]
	v_pk_add_f32 v[44:45], v[44:45], 1.0 op_sel_hi:[1,0]
	v_pk_add_f32 v[46:47], v[46:47], 1.0 op_sel_hi:[1,0]
	v_pk_mul_f32 v[50:51], v[50:51], v[32:33]
	v_pk_mul_f32 v[52:53], v[52:53], v[34:35]
	v_pk_mul_f32 v[54:55], v[54:55], v[36:37]
	v_pk_mul_f32 v[56:57], v[56:57], v[38:39]
	v_pk_mul_f32 v[58:59], v[58:59], v[40:41]
	v_pk_mul_f32 v[60:61], v[60:61], v[42:43]
	v_pk_mul_f32 v[62:63], v[62:63], v[44:45]
	v_pk_mul_f32 v[64:65], v[64:65], v[46:47]
	global_load_dwordx4 v[32:35], v66, s[4:5] offset:0
	global_load_dwordx4 v[36:39], v66, s[4:5] offset:1024
	global_load_dwordx4 v[40:43], v66, s[4:5] offset:2048
	global_load_dwordx4 v[44:47], v66, s[4:5] offset:3072
	s_add_u32 s4, s4, 0x1000
	s_addc_u32 s5, s5, 0
	s_waitcnt vmcnt(8)
	v_pk_mul_f32 v[70:71], v[0:1], v[0:1]
	v_pk_mul_f32 v[72:73], v[2:3], v[2:3]
	v_pk_fma_f32 v[70:71], v[4:5], v[4:5], v[70:71]
	v_pk_fma_f32 v[72:73], v[6:7], v[6:7], v[72:73]
	v_pk_fma_f32 v[70:71], v[8:9], v[8:9], v[70:71]
	v_pk_fma_f32 v[72:73], v[10:11], v[10:11], v[72:73]
	v_pk_fma_f32 v[70:71], v[12:13], v[12:13], v[70:71]
	v_pk_fma_f32 v[72:73], v[14:15], v[14:15], v[72:73]
	s_nop 0
	v_pk_add_f32 v[70:71], v[70:71], v[72:73]
	s_nop 0
	v_add_f32_e32 v68, v70, v71
	s_nop 1
	v_add_f32_dpp v68, v68, v68 quad_perm:[1,0,3,2] row_mask:0xf bank_mask:0xf bound_ctrl:1
	s_nop 1
	v_add_f32_dpp v68, v68, v68 quad_perm:[2,3,0,1] row_mask:0xf bank_mask:0xf bound_ctrl:1
	s_nop 1
	v_add_f32_dpp v68, v68, v68 row_half_mirror row_mask:0xf bank_mask:0xf bound_ctrl:1
	s_nop 1
	v_add_f32_dpp v68, v68, v68 row_mirror row_mask:0xf bank_mask:0xf bound_ctrl:1
	s_nop 1
	v_add_f32_dpp v68, v68, v68 row_bcast:15 row_mask:0xa bank_mask:0xf
	s_nop 1
	v_add_f32_dpp v68, v68, v68 row_bcast:31 row_mask:0xc bank_mask:0xf
	s_nop 1
	v_readlane_b32 s3, v68, 63
	s_nop 3
	v_mov_b32_e32 v68, s3
	v_fmamk_f32 v68, v68, 0x3a800000, v74
	v_rsq_f32_e32 v68, v68
	s_nop 0
	v_pk_mul_f32 v[0:1], v[0:1], v[68:69] op_sel_hi:[1,0]
	v_pk_mul_f32 v[2:3], v[2:3], v[68:69] op_sel_hi:[1,0]
	v_pk_mul_f32 v[4:5], v[4:5], v[68:69] op_sel_hi:[1,0]
	v_pk_mul_f32 v[6:7], v[6:7], v[68:69] op_sel_hi:[1,0]
	v_pk_mul_f32 v[8:9], v[8:9], v[68:69] op_sel_hi:[1,0]
	v_pk_mul_f32 v[10:11], v[10:11], v[68:69] op_sel_hi:[1,0]
	v_pk_mul_f32 v[12:13], v[12:13], v[68:69] op_sel_hi:[1,0]
	v_pk_mul_f32 v[14:15], v[14:15], v[68:69] op_sel_hi:[1,0]
	v_pk_fma_f32 v[0:1], v[50:51], v[0:1], v[78:79]
	v_pk_fma_f32 v[2:3], v[52:53], v[2:3], v[80:81]
	v_pk_fma_f32 v[4:5], v[54:55], v[4:5], v[82:83]
	v_pk_fma_f32 v[6:7], v[56:57], v[6:7], v[84:85]
	v_pk_fma_f32 v[8:9], v[58:59], v[8:9], v[86:87]
	v_pk_fma_f32 v[10:11], v[60:61], v[10:11], v[88:89]
	v_pk_fma_f32 v[12:13], v[62:63], v[12:13], v[90:91]
	v_pk_fma_f32 v[14:15], v[64:65], v[14:15], v[92:93]
	v_cvt_pk_bf16_f32 v0, v0, v1
	v_cvt_pk_bf16_f32 v1, v2, v3
	v_cvt_pk_bf16_f32 v4, v4, v5
	v_cvt_pk_bf16_f32 v5, v6, v7
	v_cvt_pk_bf16_f32 v8, v8, v9
	v_cvt_pk_bf16_f32 v9, v10, v11
	v_cvt_pk_bf16_f32 v12, v12, v13
	v_cvt_pk_bf16_f32 v13, v14, v15
	global_store_dwordx2 v67, v[0:1], s[6:7] offset:0
	global_store_dwordx2 v67, v[4:5], s[6:7] offset:512
	global_store_dwordx2 v67, v[8:9], s[6:7] offset:1024
	global_store_dwordx2 v67, v[12:13], s[6:7] offset:1536
	s_add_u32 s6, s6, 0x800
	s_addc_u32 s7, s7, 0
	global_load_dwordx4 v[0:3], v66, s[4:5] offset:0
	global_load_dwordx4 v[4:7], v66, s[4:5] offset:1024
	global_load_dwordx4 v[8:11], v66, s[4:5] offset:2048
	global_load_dwordx4 v[12:15], v66, s[4:5] offset:3072
	s_add_u32 s4, s4, 0x1000
	s_addc_u32 s5, s5, 0
	s_waitcnt vmcnt(12)
	v_pk_mul_f32 v[70:71], v[16:17], v[16:17]
	v_pk_mul_f32 v[72:73], v[18:19], v[18:19]
	v_pk_fma_f32 v[70:71], v[20:21], v[20:21], v[70:71]
	v_pk_fma_f32 v[72:73], v[22:23], v[22:23], v[72:73]
	v_pk_fma_f32 v[70:71], v[24:25], v[24:25], v[70:71]
	v_pk_fma_f32 v[72:73], v[26:27], v[26:27], v[72:73]
	v_pk_fma_f32 v[70:71], v[28:29], v[28:29], v[70:71]
	v_pk_fma_f32 v[72:73], v[30:31], v[30:31], v[72:73]
	s_nop 0
	v_pk_add_f32 v[70:71], v[70:71], v[72:73]
	s_nop 0
	v_add_f32_e32 v68, v70, v71
	s_nop 1
	v_add_f32_dpp v68, v68, v68 quad_perm:[1,0,3,2] row_mask:0xf bank_mask:0xf bound_ctrl:1
	s_nop 1
	v_add_f32_dpp v68, v68, v68 quad_perm:[2,3,0,1] row_mask:0xf bank_mask:0xf bound_ctrl:1
	s_nop 1
	v_add_f32_dpp v68, v68, v68 row_half_mirror row_mask:0xf bank_mask:0xf bound_ctrl:1
	s_nop 1
	v_add_f32_dpp v68, v68, v68 row_mirror row_mask:0xf bank_mask:0xf bound_ctrl:1
	s_nop 1
	v_add_f32_dpp v68, v68, v68 row_bcast:15 row_mask:0xa bank_mask:0xf
	s_nop 1
	v_add_f32_dpp v68, v68, v68 row_bcast:31 row_mask:0xc bank_mask:0xf
	s_nop 1
	v_readlane_b32 s3, v68, 63
	s_nop 3
	v_mov_b32_e32 v68, s3
	v_fmamk_f32 v68, v68, 0x3a800000, v74
	v_rsq_f32_e32 v68, v68
	s_nop 0
	v_pk_mul_f32 v[16:17], v[16:17], v[68:69] op_sel_hi:[1,0]
	v_pk_mul_f32 v[18:19], v[18:19], v[68:69] op_sel_hi:[1,0]
	v_pk_mul_f32 v[20:21], v[20:21], v[68:69] op_sel_hi:[1,0]
	v_pk_mul_f32 v[22:23], v[22:23], v[68:69] op_sel_hi:[1,0]
	v_pk_mul_f32 v[24:25], v[24:25], v[68:69] op_sel_hi:[1,0]
	v_pk_mul_f32 v[26:27], v[26:27], v[68:69] op_sel_hi:[1,0]
	v_pk_mul_f32 v[28:29], v[28:29], v[68:69] op_sel_hi:[1,0]
	v_pk_mul_f32 v[30:31], v[30:31], v[68:69] op_sel_hi:[1,0]
	v_pk_fma_f32 v[16:17], v[50:51], v[16:17], v[78:79]
	v_pk_fma_f32 v[18:19], v[52:53], v[18:19], v[80:81]
	v_pk_fma_f32 v[20:21], v[54:55], v[20:21], v[82:83]
	v_pk_fma_f32 v[22:23], v[56:57], v[22:23], v[84:85]
	v_pk_fma_f32 v[24:25], v[58:59], v[24:25], v[86:87]
	v_pk_fma_f32 v[26:27], v[60:61], v[26:27], v[88:89]
	v_pk_fma_f32 v[28:29], v[62:63], v[28:29], v[90:91]
	v_pk_fma_f32 v[30:31], v[64:65], v[30:31], v[92:93]
	v_cvt_pk_bf16_f32 v16, v16, v17
	v_cvt_pk_bf16_f32 v17, v18, v19
	v_cvt_pk_bf16_f32 v20, v20, v21
	v_cvt_pk_bf16_f32 v21, v22, v23
	v_cvt_pk_bf16_f32 v24, v24, v25
	v_cvt_pk_bf16_f32 v25, v26, v27
	v_cvt_pk_bf16_f32 v28, v28, v29
	v_cvt_pk_bf16_f32 v29, v30, v31
	global_store_dwordx2 v67, v[16:17], s[6:7] offset:0
	global_store_dwordx2 v67, v[20:21], s[6:7] offset:512
	global_store_dwordx2 v67, v[24:25], s[6:7] offset:1024
	global_store_dwordx2 v67, v[28:29], s[6:7] offset:1536
	s_add_u32 s6, s6, 0x800
	s_addc_u32 s7, s7, 0
	global_load_dwordx4 v[16:19], v66, s[4:5] offset:0
	global_load_dwordx4 v[20:23], v66, s[4:5] offset:1024
	global_load_dwordx4 v[24:27], v66, s[4:5] offset:2048
	global_load_dwordx4 v[28:31], v66, s[4:5] offset:3072
	s_add_u32 s4, s4, 0x1000
	s_addc_u32 s5, s5, 0
	s_waitcnt vmcnt(16)
	v_pk_mul_f32 v[70:71], v[32:33], v[32:33]
	v_pk_mul_f32 v[72:73], v[34:35], v[34:35]
	v_pk_fma_f32 v[70:71], v[36:37], v[36:37], v[70:71]
	v_pk_fma_f32 v[72:73], v[38:39], v[38:39], v[72:73]
	v_pk_fma_f32 v[70:71], v[40:41], v[40:41], v[70:71]
	v_pk_fma_f32 v[72:73], v[42:43], v[42:43], v[72:73]
	v_pk_fma_f32 v[70:71], v[44:45], v[44:45], v[70:71]
	v_pk_fma_f32 v[72:73], v[46:47], v[46:47], v[72:73]
	s_nop 0
	v_pk_add_f32 v[70:71], v[70:71], v[72:73]
	s_nop 0
	v_add_f32_e32 v68, v70, v71
	s_nop 1
	v_add_f32_dpp v68, v68, v68 quad_perm:[1,0,3,2] row_mask:0xf bank_mask:0xf bound_ctrl:1
	s_nop 1
	v_add_f32_dpp v68, v68, v68 quad_perm:[2,3,0,1] row_mask:0xf bank_mask:0xf bound_ctrl:1
	s_nop 1
	v_add_f32_dpp v68, v68, v68 row_half_mirror row_mask:0xf bank_mask:0xf bound_ctrl:1
	s_nop 1
	v_add_f32_dpp v68, v68, v68 row_mirror row_mask:0xf bank_mask:0xf bound_ctrl:1
	s_nop 1
	v_add_f32_dpp v68, v68, v68 row_bcast:15 row_mask:0xa bank_mask:0xf
	s_nop 1
	v_add_f32_dpp v68, v68, v68 row_bcast:31 row_mask:0xc bank_mask:0xf
	s_nop 1
	v_readlane_b32 s3, v68, 63
	s_nop 3
	v_mov_b32_e32 v68, s3
	v_fmamk_f32 v68, v68, 0x3a800000, v74
	v_rsq_f32_e32 v68, v68
	s_nop 0
	v_pk_mul_f32 v[32:33], v[32:33], v[68:69] op_sel_hi:[1,0]
	v_pk_mul_f32 v[34:35], v[34:35], v[68:69] op_sel_hi:[1,0]
	v_pk_mul_f32 v[36:37], v[36:37], v[68:69] op_sel_hi:[1,0]
	v_pk_mul_f32 v[38:39], v[38:39], v[68:69] op_sel_hi:[1,0]
	v_pk_mul_f32 v[40:41], v[40:41], v[68:69] op_sel_hi:[1,0]
	v_pk_mul_f32 v[42:43], v[42:43], v[68:69] op_sel_hi:[1,0]
	v_pk_mul_f32 v[44:45], v[44:45], v[68:69] op_sel_hi:[1,0]
	v_pk_mul_f32 v[46:47], v[46:47], v[68:69] op_sel_hi:[1,0]
	v_pk_fma_f32 v[32:33], v[50:51], v[32:33], v[78:79]
	v_pk_fma_f32 v[34:35], v[52:53], v[34:35], v[80:81]
	v_pk_fma_f32 v[36:37], v[54:55], v[36:37], v[82:83]
	v_pk_fma_f32 v[38:39], v[56:57], v[38:39], v[84:85]
	v_pk_fma_f32 v[40:41], v[58:59], v[40:41], v[86:87]
	v_pk_fma_f32 v[42:43], v[60:61], v[42:43], v[88:89]
	v_pk_fma_f32 v[44:45], v[62:63], v[44:45], v[90:91]
	v_pk_fma_f32 v[46:47], v[64:65], v[46:47], v[92:93]
	v_cvt_pk_bf16_f32 v32, v32, v33
	v_cvt_pk_bf16_f32 v33, v34, v35
	v_cvt_pk_bf16_f32 v36, v36, v37
	v_cvt_pk_bf16_f32 v37, v38, v39
	v_cvt_pk_bf16_f32 v40, v40, v41
	v_cvt_pk_bf16_f32 v41, v42, v43
	v_cvt_pk_bf16_f32 v44, v44, v45
	v_cvt_pk_bf16_f32 v45, v46, v47
	global_store_dwordx2 v67, v[32:33], s[6:7] offset:0
	global_store_dwordx2 v67, v[36:37], s[6:7] offset:512
	global_store_dwordx2 v67, v[40:41], s[6:7] offset:1024
	global_store_dwordx2 v67, v[44:45], s[6:7] offset:1536
	s_add_u32 s6, s6, 0x800
	s_addc_u32 s7, s7, 0
	global_load_dwordx4 v[32:35], v66, s[4:5] offset:0
	global_load_dwordx4 v[36:39], v66, s[4:5] offset:1024
	global_load_dwordx4 v[40:43], v66, s[4:5] offset:2048
	global_load_dwordx4 v[44:47], v66, s[4:5] offset:3072
	s_add_u32 s4, s4, 0x1000
	s_addc_u32 s5, s5, 0
	s_waitcnt vmcnt(16)
	v_pk_mul_f32 v[70:71], v[0:1], v[0:1]
	v_pk_mul_f32 v[72:73], v[2:3], v[2:3]
	v_pk_fma_f32 v[70:71], v[4:5], v[4:5], v[70:71]
	v_pk_fma_f32 v[72:73], v[6:7], v[6:7], v[72:73]
	v_pk_fma_f32 v[70:71], v[8:9], v[8:9], v[70:71]
	v_pk_fma_f32 v[72:73], v[10:11], v[10:11], v[72:73]
	v_pk_fma_f32 v[70:71], v[12:13], v[12:13], v[70:71]
	v_pk_fma_f32 v[72:73], v[14:15], v[14:15], v[72:73]
	s_nop 0
	v_pk_add_f32 v[70:71], v[70:71], v[72:73]
	s_nop 0
	v_add_f32_e32 v68, v70, v71
	s_nop 1
	v_add_f32_dpp v68, v68, v68 quad_perm:[1,0,3,2] row_mask:0xf bank_mask:0xf bound_ctrl:1
	s_nop 1
	v_add_f32_dpp v68, v68, v68 quad_perm:[2,3,0,1] row_mask:0xf bank_mask:0xf bound_ctrl:1
	s_nop 1
	v_add_f32_dpp v68, v68, v68 row_half_mirror row_mask:0xf bank_mask:0xf bound_ctrl:1
	s_nop 1
	v_add_f32_dpp v68, v68, v68 row_mirror row_mask:0xf bank_mask:0xf bound_ctrl:1
	s_nop 1
	v_add_f32_dpp v68, v68, v68 row_bcast:15 row_mask:0xa bank_mask:0xf
	s_nop 1
	v_add_f32_dpp v68, v68, v68 row_bcast:31 row_mask:0xc bank_mask:0xf
	s_nop 1
	v_readlane_b32 s3, v68, 63
	s_nop 3
	v_mov_b32_e32 v68, s3
	v_fmamk_f32 v68, v68, 0x3a800000, v74
	v_rsq_f32_e32 v68, v68
	s_nop 0
	v_pk_mul_f32 v[0:1], v[0:1], v[68:69] op_sel_hi:[1,0]
	v_pk_mul_f32 v[2:3], v[2:3], v[68:69] op_sel_hi:[1,0]
	v_pk_mul_f32 v[4:5], v[4:5], v[68:69] op_sel_hi:[1,0]
	v_pk_mul_f32 v[6:7], v[6:7], v[68:69] op_sel_hi:[1,0]
	v_pk_mul_f32 v[8:9], v[8:9], v[68:69] op_sel_hi:[1,0]
	v_pk_mul_f32 v[10:11], v[10:11], v[68:69] op_sel_hi:[1,0]
	v_pk_mul_f32 v[12:13], v[12:13], v[68:69] op_sel_hi:[1,0]
	v_pk_mul_f32 v[14:15], v[14:15], v[68:69] op_sel_hi:[1,0]
	v_pk_fma_f32 v[0:1], v[50:51], v[0:1], v[78:79]
	v_pk_fma_f32 v[2:3], v[52:53], v[2:3], v[80:81]
	v_pk_fma_f32 v[4:5], v[54:55], v[4:5], v[82:83]
	v_pk_fma_f32 v[6:7], v[56:57], v[6:7], v[84:85]
	v_pk_fma_f32 v[8:9], v[58:59], v[8:9], v[86:87]
	v_pk_fma_f32 v[10:11], v[60:61], v[10:11], v[88:89]
	v_pk_fma_f32 v[12:13], v[62:63], v[12:13], v[90:91]
	v_pk_fma_f32 v[14:15], v[64:65], v[14:15], v[92:93]
	v_cvt_pk_bf16_f32 v0, v0, v1
	v_cvt_pk_bf16_f32 v1, v2, v3
	v_cvt_pk_bf16_f32 v4, v4, v5
	v_cvt_pk_bf16_f32 v5, v6, v7
	v_cvt_pk_bf16_f32 v8, v8, v9
	v_cvt_pk_bf16_f32 v9, v10, v11
	v_cvt_pk_bf16_f32 v12, v12, v13
	v_cvt_pk_bf16_f32 v13, v14, v15
	global_store_dwordx2 v67, v[0:1], s[6:7] offset:0
	global_store_dwordx2 v67, v[4:5], s[6:7] offset:512
	global_store_dwordx2 v67, v[8:9], s[6:7] offset:1024
	global_store_dwordx2 v67, v[12:13], s[6:7] offset:1536
	s_add_u32 s6, s6, 0x800
	s_addc_u32 s7, s7, 0
	global_load_dwordx4 v[0:3], v66, s[4:5] offset:0
	global_load_dwordx4 v[4:7], v66, s[4:5] offset:1024
	global_load_dwordx4 v[8:11], v66, s[4:5] offset:2048
	global_load_dwordx4 v[12:15], v66, s[4:5] offset:3072
	s_add_u32 s4, s4, 0x1000
	s_addc_u32 s5, s5, 0
	s_waitcnt vmcnt(16)
	v_pk_mul_f32 v[70:71], v[16:17], v[16:17]
	v_pk_mul_f32 v[72:73], v[18:19], v[18:19]
	v_pk_fma_f32 v[70:71], v[20:21], v[20:21], v[70:71]
	v_pk_fma_f32 v[72:73], v[22:23], v[22:23], v[72:73]
	v_pk_fma_f32 v[70:71], v[24:25], v[24:25], v[70:71]
	v_pk_fma_f32 v[72:73], v[26:27], v[26:27], v[72:73]
	v_pk_fma_f32 v[70:71], v[28:29], v[28:29], v[70:71]
	v_pk_fma_f32 v[72:73], v[30:31], v[30:31], v[72:73]
	s_nop 0
	v_pk_add_f32 v[70:71], v[70:71], v[72:73]
	s_nop 0
	v_add_f32_e32 v68, v70, v71
	s_nop 1
	v_add_f32_dpp v68, v68, v68 quad_perm:[1,0,3,2] row_mask:0xf bank_mask:0xf bound_ctrl:1
	s_nop 1
	v_add_f32_dpp v68, v68, v68 quad_perm:[2,3,0,1] row_mask:0xf bank_mask:0xf bound_ctrl:1
	s_nop 1
	v_add_f32_dpp v68, v68, v68 row_half_mirror row_mask:0xf bank_mask:0xf bound_ctrl:1
	s_nop 1
	v_add_f32_dpp v68, v68, v68 row_mirror row_mask:0xf bank_mask:0xf bound_ctrl:1
	s_nop 1
	v_add_f32_dpp v68, v68, v68 row_bcast:15 row_mask:0xa bank_mask:0xf
	s_nop 1
	v_add_f32_dpp v68, v68, v68 row_bcast:31 row_mask:0xc bank_mask:0xf
	s_nop 1
	v_readlane_b32 s3, v68, 63
	s_nop 3
	v_mov_b32_e32 v68, s3
	v_fmamk_f32 v68, v68, 0x3a800000, v74
	v_rsq_f32_e32 v68, v68
	s_nop 0
	v_pk_mul_f32 v[16:17], v[16:17], v[68:69] op_sel_hi:[1,0]
	v_pk_mul_f32 v[18:19], v[18:19], v[68:69] op_sel_hi:[1,0]
	v_pk_mul_f32 v[20:21], v[20:21], v[68:69] op_sel_hi:[1,0]
	v_pk_mul_f32 v[22:23], v[22:23], v[68:69] op_sel_hi:[1,0]
	v_pk_mul_f32 v[24:25], v[24:25], v[68:69] op_sel_hi:[1,0]
	v_pk_mul_f32 v[26:27], v[26:27], v[68:69] op_sel_hi:[1,0]
	v_pk_mul_f32 v[28:29], v[28:29], v[68:69] op_sel_hi:[1,0]
	v_pk_mul_f32 v[30:31], v[30:31], v[68:69] op_sel_hi:[1,0]
	v_pk_fma_f32 v[16:17], v[50:51], v[16:17], v[78:79]
	v_pk_fma_f32 v[18:19], v[52:53], v[18:19], v[80:81]
	v_pk_fma_f32 v[20:21], v[54:55], v[20:21], v[82:83]
	v_pk_fma_f32 v[22:23], v[56:57], v[22:23], v[84:85]
	v_pk_fma_f32 v[24:25], v[58:59], v[24:25], v[86:87]
	v_pk_fma_f32 v[26:27], v[60:61], v[26:27], v[88:89]
	v_pk_fma_f32 v[28:29], v[62:63], v[28:29], v[90:91]
	v_pk_fma_f32 v[30:31], v[64:65], v[30:31], v[92:93]
	v_cvt_pk_bf16_f32 v16, v16, v17
	v_cvt_pk_bf16_f32 v17, v18, v19
	v_cvt_pk_bf16_f32 v20, v20, v21
	v_cvt_pk_bf16_f32 v21, v22, v23
	v_cvt_pk_bf16_f32 v24, v24, v25
	v_cvt_pk_bf16_f32 v25, v26, v27
	v_cvt_pk_bf16_f32 v28, v28, v29
	v_cvt_pk_bf16_f32 v29, v30, v31
	global_store_dwordx2 v67, v[16:17], s[6:7] offset:0
	global_store_dwordx2 v67, v[20:21], s[6:7] offset:512
	global_store_dwordx2 v67, v[24:25], s[6:7] offset:1024
	global_store_dwordx2 v67, v[28:29], s[6:7] offset:1536
	s_add_u32 s6, s6, 0x800
	s_addc_u32 s7, s7, 0
	global_load_dwordx4 v[16:19], v66, s[4:5] offset:0
	global_load_dwordx4 v[20:23], v66, s[4:5] offset:1024
	global_load_dwordx4 v[24:27], v66, s[4:5] offset:2048
	global_load_dwordx4 v[28:31], v66, s[4:5] offset:3072
	s_add_u32 s4, s4, 0x1000
	s_addc_u32 s5, s5, 0
	s_waitcnt vmcnt(16)
	v_pk_mul_f32 v[70:71], v[32:33], v[32:33]
	v_pk_mul_f32 v[72:73], v[34:35], v[34:35]
	v_pk_fma_f32 v[70:71], v[36:37], v[36:37], v[70:71]
	v_pk_fma_f32 v[72:73], v[38:39], v[38:39], v[72:73]
	v_pk_fma_f32 v[70:71], v[40:41], v[40:41], v[70:71]
	v_pk_fma_f32 v[72:73], v[42:43], v[42:43], v[72:73]
	v_pk_fma_f32 v[70:71], v[44:45], v[44:45], v[70:71]
	v_pk_fma_f32 v[72:73], v[46:47], v[46:47], v[72:73]
	s_nop 0
	v_pk_add_f32 v[70:71], v[70:71], v[72:73]
	s_nop 0
	v_add_f32_e32 v68, v70, v71
	s_nop 1
	v_add_f32_dpp v68, v68, v68 quad_perm:[1,0,3,2] row_mask:0xf bank_mask:0xf bound_ctrl:1
	s_nop 1
	v_add_f32_dpp v68, v68, v68 quad_perm:[2,3,0,1] row_mask:0xf bank_mask:0xf bound_ctrl:1
	s_nop 1
	v_add_f32_dpp v68, v68, v68 row_half_mirror row_mask:0xf bank_mask:0xf bound_ctrl:1
	s_nop 1
	v_add_f32_dpp v68, v68, v68 row_mirror row_mask:0xf bank_mask:0xf bound_ctrl:1
	s_nop 1
	v_add_f32_dpp v68, v68, v68 row_bcast:15 row_mask:0xa bank_mask:0xf
	s_nop 1
	v_add_f32_dpp v68, v68, v68 row_bcast:31 row_mask:0xc bank_mask:0xf
	s_nop 1
	v_readlane_b32 s3, v68, 63
	s_nop 3
	v_mov_b32_e32 v68, s3
	v_fmamk_f32 v68, v68, 0x3a800000, v74
	v_rsq_f32_e32 v68, v68
	s_nop 0
	v_pk_mul_f32 v[32:33], v[32:33], v[68:69] op_sel_hi:[1,0]
	v_pk_mul_f32 v[34:35], v[34:35], v[68:69] op_sel_hi:[1,0]
	v_pk_mul_f32 v[36:37], v[36:37], v[68:69] op_sel_hi:[1,0]
	v_pk_mul_f32 v[38:39], v[38:39], v[68:69] op_sel_hi:[1,0]
	v_pk_mul_f32 v[40:41], v[40:41], v[68:69] op_sel_hi:[1,0]
	v_pk_mul_f32 v[42:43], v[42:43], v[68:69] op_sel_hi:[1,0]
	v_pk_mul_f32 v[44:45], v[44:45], v[68:69] op_sel_hi:[1,0]
	v_pk_mul_f32 v[46:47], v[46:47], v[68:69] op_sel_hi:[1,0]
	v_pk_fma_f32 v[32:33], v[50:51], v[32:33], v[78:79]
	v_pk_fma_f32 v[34:35], v[52:53], v[34:35], v[80:81]
	v_pk_fma_f32 v[36:37], v[54:55], v[36:37], v[82:83]
	v_pk_fma_f32 v[38:39], v[56:57], v[38:39], v[84:85]
	v_pk_fma_f32 v[40:41], v[58:59], v[40:41], v[86:87]
	v_pk_fma_f32 v[42:43], v[60:61], v[42:43], v[88:89]
	v_pk_fma_f32 v[44:45], v[62:63], v[44:45], v[90:91]
	v_pk_fma_f32 v[46:47], v[64:65], v[46:47], v[92:93]
	v_cvt_pk_bf16_f32 v32, v32, v33
	v_cvt_pk_bf16_f32 v33, v34, v35
	v_cvt_pk_bf16_f32 v36, v36, v37
	v_cvt_pk_bf16_f32 v37, v38, v39
	v_cvt_pk_bf16_f32 v40, v40, v41
	v_cvt_pk_bf16_f32 v41, v42, v43
	v_cvt_pk_bf16_f32 v44, v44, v45
	v_cvt_pk_bf16_f32 v45, v46, v47
	global_store_dwordx2 v67, v[32:33], s[6:7] offset:0
	global_store_dwordx2 v67, v[36:37], s[6:7] offset:512
	global_store_dwordx2 v67, v[40:41], s[6:7] offset:1024
	global_store_dwordx2 v67, v[44:45], s[6:7] offset:1536
	s_add_u32 s6, s6, 0x800
	s_addc_u32 s7, s7, 0
	global_load_dwordx4 v[32:35], v66, s[4:5] offset:0
	global_load_dwordx4 v[36:39], v66, s[4:5] offset:1024
	global_load_dwordx4 v[40:43], v66, s[4:5] offset:2048
	global_load_dwordx4 v[44:47], v66, s[4:5] offset:3072
	s_add_u32 s4, s4, 0x1000
	s_addc_u32 s5, s5, 0
	s_waitcnt vmcnt(16)
	v_pk_mul_f32 v[70:71], v[0:1], v[0:1]
	v_pk_mul_f32 v[72:73], v[2:3], v[2:3]
	v_pk_fma_f32 v[70:71], v[4:5], v[4:5], v[70:71]
	v_pk_fma_f32 v[72:73], v[6:7], v[6:7], v[72:73]
	v_pk_fma_f32 v[70:71], v[8:9], v[8:9], v[70:71]
	v_pk_fma_f32 v[72:73], v[10:11], v[10:11], v[72:73]
	v_pk_fma_f32 v[70:71], v[12:13], v[12:13], v[70:71]
	v_pk_fma_f32 v[72:73], v[14:15], v[14:15], v[72:73]
	s_nop 0
	v_pk_add_f32 v[70:71], v[70:71], v[72:73]
	s_nop 0
	v_add_f32_e32 v68, v70, v71
	s_nop 1
	v_add_f32_dpp v68, v68, v68 quad_perm:[1,0,3,2] row_mask:0xf bank_mask:0xf bound_ctrl:1
	s_nop 1
	v_add_f32_dpp v68, v68, v68 quad_perm:[2,3,0,1] row_mask:0xf bank_mask:0xf bound_ctrl:1
	s_nop 1
	v_add_f32_dpp v68, v68, v68 row_half_mirror row_mask:0xf bank_mask:0xf bound_ctrl:1
	s_nop 1
	v_add_f32_dpp v68, v68, v68 row_mirror row_mask:0xf bank_mask:0xf bound_ctrl:1
	s_nop 1
	v_add_f32_dpp v68, v68, v68 row_bcast:15 row_mask:0xa bank_mask:0xf
	s_nop 1
	v_add_f32_dpp v68, v68, v68 row_bcast:31 row_mask:0xc bank_mask:0xf
	s_nop 1
	v_readlane_b32 s3, v68, 63
	s_nop 3
	v_mov_b32_e32 v68, s3
	v_fmamk_f32 v68, v68, 0x3a800000, v74
	v_rsq_f32_e32 v68, v68
	s_nop 0
	v_pk_mul_f32 v[0:1], v[0:1], v[68:69] op_sel_hi:[1,0]
	v_pk_mul_f32 v[2:3], v[2:3], v[68:69] op_sel_hi:[1,0]
	v_pk_mul_f32 v[4:5], v[4:5], v[68:69] op_sel_hi:[1,0]
	v_pk_mul_f32 v[6:7], v[6:7], v[68:69] op_sel_hi:[1,0]
	v_pk_mul_f32 v[8:9], v[8:9], v[68:69] op_sel_hi:[1,0]
	v_pk_mul_f32 v[10:11], v[10:11], v[68:69] op_sel_hi:[1,0]
	v_pk_mul_f32 v[12:13], v[12:13], v[68:69] op_sel_hi:[1,0]
	v_pk_mul_f32 v[14:15], v[14:15], v[68:69] op_sel_hi:[1,0]
	v_pk_fma_f32 v[0:1], v[50:51], v[0:1], v[78:79]
	v_pk_fma_f32 v[2:3], v[52:53], v[2:3], v[80:81]
	v_pk_fma_f32 v[4:5], v[54:55], v[4:5], v[82:83]
	v_pk_fma_f32 v[6:7], v[56:57], v[6:7], v[84:85]
	v_pk_fma_f32 v[8:9], v[58:59], v[8:9], v[86:87]
	v_pk_fma_f32 v[10:11], v[60:61], v[10:11], v[88:89]
	v_pk_fma_f32 v[12:13], v[62:63], v[12:13], v[90:91]
	v_pk_fma_f32 v[14:15], v[64:65], v[14:15], v[92:93]
	v_cvt_pk_bf16_f32 v0, v0, v1
	v_cvt_pk_bf16_f32 v1, v2, v3
	v_cvt_pk_bf16_f32 v4, v4, v5
	v_cvt_pk_bf16_f32 v5, v6, v7
	v_cvt_pk_bf16_f32 v8, v8, v9
	v_cvt_pk_bf16_f32 v9, v10, v11
	v_cvt_pk_bf16_f32 v12, v12, v13
	v_cvt_pk_bf16_f32 v13, v14, v15
	global_store_dwordx2 v67, v[0:1], s[6:7] offset:0
	global_store_dwordx2 v67, v[4:5], s[6:7] offset:512
	global_store_dwordx2 v67, v[8:9], s[6:7] offset:1024
	global_store_dwordx2 v67, v[12:13], s[6:7] offset:1536
	s_add_u32 s6, s6, 0x800
	s_addc_u32 s7, s7, 0
	global_load_dwordx4 v[0:3], v66, s[4:5] offset:0
	global_load_dwordx4 v[4:7], v66, s[4:5] offset:1024
	global_load_dwordx4 v[8:11], v66, s[4:5] offset:2048
	global_load_dwordx4 v[12:15], v66, s[4:5] offset:3072
	s_add_u32 s4, s4, 0x1000
	s_addc_u32 s5, s5, 0
	s_waitcnt vmcnt(16)
	v_pk_mul_f32 v[70:71], v[16:17], v[16:17]
	v_pk_mul_f32 v[72:73], v[18:19], v[18:19]
	v_pk_fma_f32 v[70:71], v[20:21], v[20:21], v[70:71]
	v_pk_fma_f32 v[72:73], v[22:23], v[22:23], v[72:73]
	v_pk_fma_f32 v[70:71], v[24:25], v[24:25], v[70:71]
	v_pk_fma_f32 v[72:73], v[26:27], v[26:27], v[72:73]
	v_pk_fma_f32 v[70:71], v[28:29], v[28:29], v[70:71]
	v_pk_fma_f32 v[72:73], v[30:31], v[30:31], v[72:73]
	s_nop 0
	v_pk_add_f32 v[70:71], v[70:71], v[72:73]
	s_nop 0
	v_add_f32_e32 v68, v70, v71
	s_nop 1
	v_add_f32_dpp v68, v68, v68 quad_perm:[1,0,3,2] row_mask:0xf bank_mask:0xf bound_ctrl:1
	s_nop 1
	v_add_f32_dpp v68, v68, v68 quad_perm:[2,3,0,1] row_mask:0xf bank_mask:0xf bound_ctrl:1
	s_nop 1
	v_add_f32_dpp v68, v68, v68 row_half_mirror row_mask:0xf bank_mask:0xf bound_ctrl:1
	s_nop 1
	v_add_f32_dpp v68, v68, v68 row_mirror row_mask:0xf bank_mask:0xf bound_ctrl:1
	s_nop 1
	v_add_f32_dpp v68, v68, v68 row_bcast:15 row_mask:0xa bank_mask:0xf
	s_nop 1
	v_add_f32_dpp v68, v68, v68 row_bcast:31 row_mask:0xc bank_mask:0xf
	s_nop 1
	v_readlane_b32 s3, v68, 63
	s_nop 3
	v_mov_b32_e32 v68, s3
	v_fmamk_f32 v68, v68, 0x3a800000, v74
	v_rsq_f32_e32 v68, v68
	s_nop 0
	v_pk_mul_f32 v[16:17], v[16:17], v[68:69] op_sel_hi:[1,0]
	v_pk_mul_f32 v[18:19], v[18:19], v[68:69] op_sel_hi:[1,0]
	v_pk_mul_f32 v[20:21], v[20:21], v[68:69] op_sel_hi:[1,0]
	v_pk_mul_f32 v[22:23], v[22:23], v[68:69] op_sel_hi:[1,0]
	v_pk_mul_f32 v[24:25], v[24:25], v[68:69] op_sel_hi:[1,0]
	v_pk_mul_f32 v[26:27], v[26:27], v[68:69] op_sel_hi:[1,0]
	v_pk_mul_f32 v[28:29], v[28:29], v[68:69] op_sel_hi:[1,0]
	v_pk_mul_f32 v[30:31], v[30:31], v[68:69] op_sel_hi:[1,0]
	v_pk_fma_f32 v[16:17], v[50:51], v[16:17], v[78:79]
	v_pk_fma_f32 v[18:19], v[52:53], v[18:19], v[80:81]
	v_pk_fma_f32 v[20:21], v[54:55], v[20:21], v[82:83]
	v_pk_fma_f32 v[22:23], v[56:57], v[22:23], v[84:85]
	v_pk_fma_f32 v[24:25], v[58:59], v[24:25], v[86:87]
	v_pk_fma_f32 v[26:27], v[60:61], v[26:27], v[88:89]
	v_pk_fma_f32 v[28:29], v[62:63], v[28:29], v[90:91]
	v_pk_fma_f32 v[30:31], v[64:65], v[30:31], v[92:93]
	v_cvt_pk_bf16_f32 v16, v16, v17
	v_cvt_pk_bf16_f32 v17, v18, v19
	v_cvt_pk_bf16_f32 v20, v20, v21
	v_cvt_pk_bf16_f32 v21, v22, v23
	v_cvt_pk_bf16_f32 v24, v24, v25
	v_cvt_pk_bf16_f32 v25, v26, v27
	v_cvt_pk_bf16_f32 v28, v28, v29
	v_cvt_pk_bf16_f32 v29, v30, v31
	global_store_dwordx2 v67, v[16:17], s[6:7] offset:0
	global_store_dwordx2 v67, v[20:21], s[6:7] offset:512
	global_store_dwordx2 v67, v[24:25], s[6:7] offset:1024
	global_store_dwordx2 v67, v[28:29], s[6:7] offset:1536
	s_add_u32 s6, s6, 0x800
	s_addc_u32 s7, s7, 0
	global_load_dwordx4 v[16:19], v66, s[4:5] offset:0
	global_load_dwordx4 v[20:23], v66, s[4:5] offset:1024
	global_load_dwordx4 v[24:27], v66, s[4:5] offset:2048
	global_load_dwordx4 v[28:31], v66, s[4:5] offset:3072
	s_add_u32 s4, s4, 0x1000
	s_addc_u32 s5, s5, 0
	s_waitcnt vmcnt(16)
	v_pk_mul_f32 v[70:71], v[32:33], v[32:33]
	v_pk_mul_f32 v[72:73], v[34:35], v[34:35]
	v_pk_fma_f32 v[70:71], v[36:37], v[36:37], v[70:71]
	v_pk_fma_f32 v[72:73], v[38:39], v[38:39], v[72:73]
	v_pk_fma_f32 v[70:71], v[40:41], v[40:41], v[70:71]
	v_pk_fma_f32 v[72:73], v[42:43], v[42:43], v[72:73]
	v_pk_fma_f32 v[70:71], v[44:45], v[44:45], v[70:71]
	v_pk_fma_f32 v[72:73], v[46:47], v[46:47], v[72:73]
	s_nop 0
	v_pk_add_f32 v[70:71], v[70:71], v[72:73]
	s_nop 0
	v_add_f32_e32 v68, v70, v71
	s_nop 1
	v_add_f32_dpp v68, v68, v68 quad_perm:[1,0,3,2] row_mask:0xf bank_mask:0xf bound_ctrl:1
	s_nop 1
	v_add_f32_dpp v68, v68, v68 quad_perm:[2,3,0,1] row_mask:0xf bank_mask:0xf bound_ctrl:1
	s_nop 1
	v_add_f32_dpp v68, v68, v68 row_half_mirror row_mask:0xf bank_mask:0xf bound_ctrl:1
	s_nop 1
	v_add_f32_dpp v68, v68, v68 row_mirror row_mask:0xf bank_mask:0xf bound_ctrl:1
	s_nop 1
	v_add_f32_dpp v68, v68, v68 row_bcast:15 row_mask:0xa bank_mask:0xf
	s_nop 1
	v_add_f32_dpp v68, v68, v68 row_bcast:31 row_mask:0xc bank_mask:0xf
	s_nop 1
	v_readlane_b32 s3, v68, 63
	s_nop 3
	v_mov_b32_e32 v68, s3
	v_fmamk_f32 v68, v68, 0x3a800000, v74
	v_rsq_f32_e32 v68, v68
	s_nop 0
	v_pk_mul_f32 v[32:33], v[32:33], v[68:69] op_sel_hi:[1,0]
	v_pk_mul_f32 v[34:35], v[34:35], v[68:69] op_sel_hi:[1,0]
	v_pk_mul_f32 v[36:37], v[36:37], v[68:69] op_sel_hi:[1,0]
	v_pk_mul_f32 v[38:39], v[38:39], v[68:69] op_sel_hi:[1,0]
	v_pk_mul_f32 v[40:41], v[40:41], v[68:69] op_sel_hi:[1,0]
	v_pk_mul_f32 v[42:43], v[42:43], v[68:69] op_sel_hi:[1,0]
	v_pk_mul_f32 v[44:45], v[44:45], v[68:69] op_sel_hi:[1,0]
	v_pk_mul_f32 v[46:47], v[46:47], v[68:69] op_sel_hi:[1,0]
	v_pk_fma_f32 v[32:33], v[50:51], v[32:33], v[78:79]
	v_pk_fma_f32 v[34:35], v[52:53], v[34:35], v[80:81]
	v_pk_fma_f32 v[36:37], v[54:55], v[36:37], v[82:83]
	v_pk_fma_f32 v[38:39], v[56:57], v[38:39], v[84:85]
	v_pk_fma_f32 v[40:41], v[58:59], v[40:41], v[86:87]
	v_pk_fma_f32 v[42:43], v[60:61], v[42:43], v[88:89]
	v_pk_fma_f32 v[44:45], v[62:63], v[44:45], v[90:91]
	v_pk_fma_f32 v[46:47], v[64:65], v[46:47], v[92:93]
	v_cvt_pk_bf16_f32 v32, v32, v33
	v_cvt_pk_bf16_f32 v33, v34, v35
	v_cvt_pk_bf16_f32 v36, v36, v37
	v_cvt_pk_bf16_f32 v37, v38, v39
	v_cvt_pk_bf16_f32 v40, v40, v41
	v_cvt_pk_bf16_f32 v41, v42, v43
	v_cvt_pk_bf16_f32 v44, v44, v45
	v_cvt_pk_bf16_f32 v45, v46, v47
	global_store_dwordx2 v67, v[32:33], s[6:7] offset:0
	global_store_dwordx2 v67, v[36:37], s[6:7] offset:512
	global_store_dwordx2 v67, v[40:41], s[6:7] offset:1024
	global_store_dwordx2 v67, v[44:45], s[6:7] offset:1536
	s_add_u32 s6, s6, 0x800
	s_addc_u32 s7, s7, 0
	global_load_dwordx4 v[32:35], v66, s[4:5] offset:0
	global_load_dwordx4 v[36:39], v66, s[4:5] offset:1024
	global_load_dwordx4 v[40:43], v66, s[4:5] offset:2048
	global_load_dwordx4 v[44:47], v66, s[4:5] offset:3072
	s_add_u32 s4, s4, 0x1000
	s_addc_u32 s5, s5, 0
	s_waitcnt vmcnt(16)
	v_pk_mul_f32 v[70:71], v[0:1], v[0:1]
	v_pk_mul_f32 v[72:73], v[2:3], v[2:3]
	v_pk_fma_f32 v[70:71], v[4:5], v[4:5], v[70:71]
	v_pk_fma_f32 v[72:73], v[6:7], v[6:7], v[72:73]
	v_pk_fma_f32 v[70:71], v[8:9], v[8:9], v[70:71]
	v_pk_fma_f32 v[72:73], v[10:11], v[10:11], v[72:73]
	v_pk_fma_f32 v[70:71], v[12:13], v[12:13], v[70:71]
	v_pk_fma_f32 v[72:73], v[14:15], v[14:15], v[72:73]
	s_nop 0
	v_pk_add_f32 v[70:71], v[70:71], v[72:73]
	s_nop 0
	v_add_f32_e32 v68, v70, v71
	s_nop 1
	v_add_f32_dpp v68, v68, v68 quad_perm:[1,0,3,2] row_mask:0xf bank_mask:0xf bound_ctrl:1
	s_nop 1
	v_add_f32_dpp v68, v68, v68 quad_perm:[2,3,0,1] row_mask:0xf bank_mask:0xf bound_ctrl:1
	s_nop 1
	v_add_f32_dpp v68, v68, v68 row_half_mirror row_mask:0xf bank_mask:0xf bound_ctrl:1
	s_nop 1
	v_add_f32_dpp v68, v68, v68 row_mirror row_mask:0xf bank_mask:0xf bound_ctrl:1
	s_nop 1
	v_add_f32_dpp v68, v68, v68 row_bcast:15 row_mask:0xa bank_mask:0xf
	s_nop 1
	v_add_f32_dpp v68, v68, v68 row_bcast:31 row_mask:0xc bank_mask:0xf
	s_nop 1
	v_readlane_b32 s3, v68, 63
	s_nop 3
	v_mov_b32_e32 v68, s3
	v_fmamk_f32 v68, v68, 0x3a800000, v74
	v_rsq_f32_e32 v68, v68
	s_nop 0
	v_pk_mul_f32 v[0:1], v[0:1], v[68:69] op_sel_hi:[1,0]
	v_pk_mul_f32 v[2:3], v[2:3], v[68:69] op_sel_hi:[1,0]
	v_pk_mul_f32 v[4:5], v[4:5], v[68:69] op_sel_hi:[1,0]
	v_pk_mul_f32 v[6:7], v[6:7], v[68:69] op_sel_hi:[1,0]
	v_pk_mul_f32 v[8:9], v[8:9], v[68:69] op_sel_hi:[1,0]
	v_pk_mul_f32 v[10:11], v[10:11], v[68:69] op_sel_hi:[1,0]
	v_pk_mul_f32 v[12:13], v[12:13], v[68:69] op_sel_hi:[1,0]
	v_pk_mul_f32 v[14:15], v[14:15], v[68:69] op_sel_hi:[1,0]
	v_pk_fma_f32 v[0:1], v[50:51], v[0:1], v[78:79]
	v_pk_fma_f32 v[2:3], v[52:53], v[2:3], v[80:81]
	v_pk_fma_f32 v[4:5], v[54:55], v[4:5], v[82:83]
	v_pk_fma_f32 v[6:7], v[56:57], v[6:7], v[84:85]
	v_pk_fma_f32 v[8:9], v[58:59], v[8:9], v[86:87]
	v_pk_fma_f32 v[10:11], v[60:61], v[10:11], v[88:89]
	v_pk_fma_f32 v[12:13], v[62:63], v[12:13], v[90:91]
	v_pk_fma_f32 v[14:15], v[64:65], v[14:15], v[92:93]
	v_cvt_pk_bf16_f32 v0, v0, v1
	v_cvt_pk_bf16_f32 v1, v2, v3
	v_cvt_pk_bf16_f32 v4, v4, v5
	v_cvt_pk_bf16_f32 v5, v6, v7
	v_cvt_pk_bf16_f32 v8, v8, v9
	v_cvt_pk_bf16_f32 v9, v10, v11
	v_cvt_pk_bf16_f32 v12, v12, v13
	v_cvt_pk_bf16_f32 v13, v14, v15
	global_store_dwordx2 v67, v[0:1], s[6:7] offset:0
	global_store_dwordx2 v67, v[4:5], s[6:7] offset:512
	global_store_dwordx2 v67, v[8:9], s[6:7] offset:1024
	global_store_dwordx2 v67, v[12:13], s[6:7] offset:1536
	s_add_u32 s6, s6, 0x800
	s_addc_u32 s7, s7, 0
	global_load_dwordx4 v[0:3], v66, s[4:5] offset:0
	global_load_dwordx4 v[4:7], v66, s[4:5] offset:1024
	global_load_dwordx4 v[8:11], v66, s[4:5] offset:2048
	global_load_dwordx4 v[12:15], v66, s[4:5] offset:3072
	s_add_u32 s4, s4, 0x1000
	s_addc_u32 s5, s5, 0
	s_waitcnt vmcnt(16)
	v_pk_mul_f32 v[70:71], v[16:17], v[16:17]
	v_pk_mul_f32 v[72:73], v[18:19], v[18:19]
	v_pk_fma_f32 v[70:71], v[20:21], v[20:21], v[70:71]
	v_pk_fma_f32 v[72:73], v[22:23], v[22:23], v[72:73]
	v_pk_fma_f32 v[70:71], v[24:25], v[24:25], v[70:71]
	v_pk_fma_f32 v[72:73], v[26:27], v[26:27], v[72:73]
	v_pk_fma_f32 v[70:71], v[28:29], v[28:29], v[70:71]
	v_pk_fma_f32 v[72:73], v[30:31], v[30:31], v[72:73]
	s_nop 0
	v_pk_add_f32 v[70:71], v[70:71], v[72:73]
	s_nop 0
	v_add_f32_e32 v68, v70, v71
	s_nop 1
	v_add_f32_dpp v68, v68, v68 quad_perm:[1,0,3,2] row_mask:0xf bank_mask:0xf bound_ctrl:1
	s_nop 1
	v_add_f32_dpp v68, v68, v68 quad_perm:[2,3,0,1] row_mask:0xf bank_mask:0xf bound_ctrl:1
	s_nop 1
	v_add_f32_dpp v68, v68, v68 row_half_mirror row_mask:0xf bank_mask:0xf bound_ctrl:1
	s_nop 1
	v_add_f32_dpp v68, v68, v68 row_mirror row_mask:0xf bank_mask:0xf bound_ctrl:1
	s_nop 1
	v_add_f32_dpp v68, v68, v68 row_bcast:15 row_mask:0xa bank_mask:0xf
	s_nop 1
	v_add_f32_dpp v68, v68, v68 row_bcast:31 row_mask:0xc bank_mask:0xf
	s_nop 1
	v_readlane_b32 s3, v68, 63
	s_nop 3
	v_mov_b32_e32 v68, s3
	v_fmamk_f32 v68, v68, 0x3a800000, v74
	v_rsq_f32_e32 v68, v68
	s_nop 0
	v_pk_mul_f32 v[16:17], v[16:17], v[68:69] op_sel_hi:[1,0]
	v_pk_mul_f32 v[18:19], v[18:19], v[68:69] op_sel_hi:[1,0]
	v_pk_mul_f32 v[20:21], v[20:21], v[68:69] op_sel_hi:[1,0]
	v_pk_mul_f32 v[22:23], v[22:23], v[68:69] op_sel_hi:[1,0]
	v_pk_mul_f32 v[24:25], v[24:25], v[68:69] op_sel_hi:[1,0]
	v_pk_mul_f32 v[26:27], v[26:27], v[68:69] op_sel_hi:[1,0]
	v_pk_mul_f32 v[28:29], v[28:29], v[68:69] op_sel_hi:[1,0]
	v_pk_mul_f32 v[30:31], v[30:31], v[68:69] op_sel_hi:[1,0]
	v_pk_fma_f32 v[16:17], v[50:51], v[16:17], v[78:79]
	v_pk_fma_f32 v[18:19], v[52:53], v[18:19], v[80:81]
	v_pk_fma_f32 v[20:21], v[54:55], v[20:21], v[82:83]
	v_pk_fma_f32 v[22:23], v[56:57], v[22:23], v[84:85]
	v_pk_fma_f32 v[24:25], v[58:59], v[24:25], v[86:87]
	v_pk_fma_f32 v[26:27], v[60:61], v[26:27], v[88:89]
	v_pk_fma_f32 v[28:29], v[62:63], v[28:29], v[90:91]
	v_pk_fma_f32 v[30:31], v[64:65], v[30:31], v[92:93]
	v_cvt_pk_bf16_f32 v16, v16, v17
	v_cvt_pk_bf16_f32 v17, v18, v19
	v_cvt_pk_bf16_f32 v20, v20, v21
	v_cvt_pk_bf16_f32 v21, v22, v23
	v_cvt_pk_bf16_f32 v24, v24, v25
	v_cvt_pk_bf16_f32 v25, v26, v27
	v_cvt_pk_bf16_f32 v28, v28, v29
	v_cvt_pk_bf16_f32 v29, v30, v31
	global_store_dwordx2 v67, v[16:17], s[6:7] offset:0
	global_store_dwordx2 v67, v[20:21], s[6:7] offset:512
	global_store_dwordx2 v67, v[24:25], s[6:7] offset:1024
	global_store_dwordx2 v67, v[28:29], s[6:7] offset:1536
	s_add_u32 s6, s6, 0x800
	s_addc_u32 s7, s7, 0
	global_load_dwordx4 v[16:19], v66, s[4:5] offset:0
	global_load_dwordx4 v[20:23], v66, s[4:5] offset:1024
	global_load_dwordx4 v[24:27], v66, s[4:5] offset:2048
	global_load_dwordx4 v[28:31], v66, s[4:5] offset:3072
	s_add_u32 s4, s4, 0x1000
	s_addc_u32 s5, s5, 0
	s_waitcnt vmcnt(16)
	v_pk_mul_f32 v[70:71], v[32:33], v[32:33]
	v_pk_mul_f32 v[72:73], v[34:35], v[34:35]
	v_pk_fma_f32 v[70:71], v[36:37], v[36:37], v[70:71]
	v_pk_fma_f32 v[72:73], v[38:39], v[38:39], v[72:73]
	v_pk_fma_f32 v[70:71], v[40:41], v[40:41], v[70:71]
	v_pk_fma_f32 v[72:73], v[42:43], v[42:43], v[72:73]
	v_pk_fma_f32 v[70:71], v[44:45], v[44:45], v[70:71]
	v_pk_fma_f32 v[72:73], v[46:47], v[46:47], v[72:73]
	s_nop 0
	v_pk_add_f32 v[70:71], v[70:71], v[72:73]
	s_nop 0
	v_add_f32_e32 v68, v70, v71
	s_nop 1
	v_add_f32_dpp v68, v68, v68 quad_perm:[1,0,3,2] row_mask:0xf bank_mask:0xf bound_ctrl:1
	s_nop 1
	v_add_f32_dpp v68, v68, v68 quad_perm:[2,3,0,1] row_mask:0xf bank_mask:0xf bound_ctrl:1
	s_nop 1
	v_add_f32_dpp v68, v68, v68 row_half_mirror row_mask:0xf bank_mask:0xf bound_ctrl:1
	s_nop 1
	v_add_f32_dpp v68, v68, v68 row_mirror row_mask:0xf bank_mask:0xf bound_ctrl:1
	s_nop 1
	v_add_f32_dpp v68, v68, v68 row_bcast:15 row_mask:0xa bank_mask:0xf
	s_nop 1
	v_add_f32_dpp v68, v68, v68 row_bcast:31 row_mask:0xc bank_mask:0xf
	s_nop 1
	v_readlane_b32 s3, v68, 63
	s_nop 3
	v_mov_b32_e32 v68, s3
	v_fmamk_f32 v68, v68, 0x3a800000, v74
	v_rsq_f32_e32 v68, v68
	s_nop 0
	v_pk_mul_f32 v[32:33], v[32:33], v[68:69] op_sel_hi:[1,0]
	v_pk_mul_f32 v[34:35], v[34:35], v[68:69] op_sel_hi:[1,0]
	v_pk_mul_f32 v[36:37], v[36:37], v[68:69] op_sel_hi:[1,0]
	v_pk_mul_f32 v[38:39], v[38:39], v[68:69] op_sel_hi:[1,0]
	v_pk_mul_f32 v[40:41], v[40:41], v[68:69] op_sel_hi:[1,0]
	v_pk_mul_f32 v[42:43], v[42:43], v[68:69] op_sel_hi:[1,0]
	v_pk_mul_f32 v[44:45], v[44:45], v[68:69] op_sel_hi:[1,0]
	v_pk_mul_f32 v[46:47], v[46:47], v[68:69] op_sel_hi:[1,0]
	v_pk_fma_f32 v[32:33], v[50:51], v[32:33], v[78:79]
	v_pk_fma_f32 v[34:35], v[52:53], v[34:35], v[80:81]
	v_pk_fma_f32 v[36:37], v[54:55], v[36:37], v[82:83]
	v_pk_fma_f32 v[38:39], v[56:57], v[38:39], v[84:85]
	v_pk_fma_f32 v[40:41], v[58:59], v[40:41], v[86:87]
	v_pk_fma_f32 v[42:43], v[60:61], v[42:43], v[88:89]
	v_pk_fma_f32 v[44:45], v[62:63], v[44:45], v[90:91]
	v_pk_fma_f32 v[46:47], v[64:65], v[46:47], v[92:93]
	v_cvt_pk_bf16_f32 v32, v32, v33
	v_cvt_pk_bf16_f32 v33, v34, v35
	v_cvt_pk_bf16_f32 v36, v36, v37
	v_cvt_pk_bf16_f32 v37, v38, v39
	v_cvt_pk_bf16_f32 v40, v40, v41
	v_cvt_pk_bf16_f32 v41, v42, v43
	v_cvt_pk_bf16_f32 v44, v44, v45
	v_cvt_pk_bf16_f32 v45, v46, v47
	global_store_dwordx2 v67, v[32:33], s[6:7] offset:0
	global_store_dwordx2 v67, v[36:37], s[6:7] offset:512
	global_store_dwordx2 v67, v[40:41], s[6:7] offset:1024
	global_store_dwordx2 v67, v[44:45], s[6:7] offset:1536
	s_add_u32 s6, s6, 0x800
	s_addc_u32 s7, s7, 0
	global_load_dwordx4 v[32:35], v66, s[4:5] offset:0
	global_load_dwordx4 v[36:39], v66, s[4:5] offset:1024
	global_load_dwordx4 v[40:43], v66, s[4:5] offset:2048
	global_load_dwordx4 v[44:47], v66, s[4:5] offset:3072
	s_add_u32 s4, s4, 0x1000
	s_addc_u32 s5, s5, 0
	s_waitcnt vmcnt(16)
	v_pk_mul_f32 v[70:71], v[0:1], v[0:1]
	v_pk_mul_f32 v[72:73], v[2:3], v[2:3]
	v_pk_fma_f32 v[70:71], v[4:5], v[4:5], v[70:71]
	v_pk_fma_f32 v[72:73], v[6:7], v[6:7], v[72:73]
	v_pk_fma_f32 v[70:71], v[8:9], v[8:9], v[70:71]
	v_pk_fma_f32 v[72:73], v[10:11], v[10:11], v[72:73]
	v_pk_fma_f32 v[70:71], v[12:13], v[12:13], v[70:71]
	v_pk_fma_f32 v[72:73], v[14:15], v[14:15], v[72:73]
	s_nop 0
	v_pk_add_f32 v[70:71], v[70:71], v[72:73]
	s_nop 0
	v_add_f32_e32 v68, v70, v71
	s_nop 1
	v_add_f32_dpp v68, v68, v68 quad_perm:[1,0,3,2] row_mask:0xf bank_mask:0xf bound_ctrl:1
	s_nop 1
	v_add_f32_dpp v68, v68, v68 quad_perm:[2,3,0,1] row_mask:0xf bank_mask:0xf bound_ctrl:1
	s_nop 1
	v_add_f32_dpp v68, v68, v68 row_half_mirror row_mask:0xf bank_mask:0xf bound_ctrl:1
	s_nop 1
	v_add_f32_dpp v68, v68, v68 row_mirror row_mask:0xf bank_mask:0xf bound_ctrl:1
	s_nop 1
	v_add_f32_dpp v68, v68, v68 row_bcast:15 row_mask:0xa bank_mask:0xf
	s_nop 1
	v_add_f32_dpp v68, v68, v68 row_bcast:31 row_mask:0xc bank_mask:0xf
	s_nop 1
	v_readlane_b32 s3, v68, 63
	s_nop 3
	v_mov_b32_e32 v68, s3
	v_fmamk_f32 v68, v68, 0x3a800000, v74
	v_rsq_f32_e32 v68, v68
	s_nop 0
	v_pk_mul_f32 v[0:1], v[0:1], v[68:69] op_sel_hi:[1,0]
	v_pk_mul_f32 v[2:3], v[2:3], v[68:69] op_sel_hi:[1,0]
	v_pk_mul_f32 v[4:5], v[4:5], v[68:69] op_sel_hi:[1,0]
	v_pk_mul_f32 v[6:7], v[6:7], v[68:69] op_sel_hi:[1,0]
	v_pk_mul_f32 v[8:9], v[8:9], v[68:69] op_sel_hi:[1,0]
	v_pk_mul_f32 v[10:11], v[10:11], v[68:69] op_sel_hi:[1,0]
	v_pk_mul_f32 v[12:13], v[12:13], v[68:69] op_sel_hi:[1,0]
	v_pk_mul_f32 v[14:15], v[14:15], v[68:69] op_sel_hi:[1,0]
	v_pk_fma_f32 v[0:1], v[50:51], v[0:1], v[78:79]
	v_pk_fma_f32 v[2:3], v[52:53], v[2:3], v[80:81]
	v_pk_fma_f32 v[4:5], v[54:55], v[4:5], v[82:83]
	v_pk_fma_f32 v[6:7], v[56:57], v[6:7], v[84:85]
	v_pk_fma_f32 v[8:9], v[58:59], v[8:9], v[86:87]
	v_pk_fma_f32 v[10:11], v[60:61], v[10:11], v[88:89]
	v_pk_fma_f32 v[12:13], v[62:63], v[12:13], v[90:91]
	v_pk_fma_f32 v[14:15], v[64:65], v[14:15], v[92:93]
	v_cvt_pk_bf16_f32 v0, v0, v1
	v_cvt_pk_bf16_f32 v1, v2, v3
	v_cvt_pk_bf16_f32 v4, v4, v5
	v_cvt_pk_bf16_f32 v5, v6, v7
	v_cvt_pk_bf16_f32 v8, v8, v9
	v_cvt_pk_bf16_f32 v9, v10, v11
	v_cvt_pk_bf16_f32 v12, v12, v13
	v_cvt_pk_bf16_f32 v13, v14, v15
	global_store_dwordx2 v67, v[0:1], s[6:7] offset:0
	global_store_dwordx2 v67, v[4:5], s[6:7] offset:512
	global_store_dwordx2 v67, v[8:9], s[6:7] offset:1024
	global_store_dwordx2 v67, v[12:13], s[6:7] offset:1536
	s_add_u32 s6, s6, 0x800
	s_addc_u32 s7, s7, 0
	global_load_dwordx4 v[0:3], v66, s[4:5] offset:0
	global_load_dwordx4 v[4:7], v66, s[4:5] offset:1024
	global_load_dwordx4 v[8:11], v66, s[4:5] offset:2048
	global_load_dwordx4 v[12:15], v66, s[4:5] offset:3072
	s_add_u32 s4, s4, 0x1000
	s_addc_u32 s5, s5, 0
	s_waitcnt vmcnt(16)
	v_pk_mul_f32 v[70:71], v[16:17], v[16:17]
	v_pk_mul_f32 v[72:73], v[18:19], v[18:19]
	v_pk_fma_f32 v[70:71], v[20:21], v[20:21], v[70:71]
	v_pk_fma_f32 v[72:73], v[22:23], v[22:23], v[72:73]
	v_pk_fma_f32 v[70:71], v[24:25], v[24:25], v[70:71]
	v_pk_fma_f32 v[72:73], v[26:27], v[26:27], v[72:73]
	v_pk_fma_f32 v[70:71], v[28:29], v[28:29], v[70:71]
	v_pk_fma_f32 v[72:73], v[30:31], v[30:31], v[72:73]
	s_nop 0
	v_pk_add_f32 v[70:71], v[70:71], v[72:73]
	s_nop 0
	v_add_f32_e32 v68, v70, v71
	s_nop 1
	v_add_f32_dpp v68, v68, v68 quad_perm:[1,0,3,2] row_mask:0xf bank_mask:0xf bound_ctrl:1
	s_nop 1
	v_add_f32_dpp v68, v68, v68 quad_perm:[2,3,0,1] row_mask:0xf bank_mask:0xf bound_ctrl:1
	s_nop 1
	v_add_f32_dpp v68, v68, v68 row_half_mirror row_mask:0xf bank_mask:0xf bound_ctrl:1
	s_nop 1
	v_add_f32_dpp v68, v68, v68 row_mirror row_mask:0xf bank_mask:0xf bound_ctrl:1
	s_nop 1
	v_add_f32_dpp v68, v68, v68 row_bcast:15 row_mask:0xa bank_mask:0xf
	s_nop 1
	v_add_f32_dpp v68, v68, v68 row_bcast:31 row_mask:0xc bank_mask:0xf
	s_nop 1
	v_readlane_b32 s3, v68, 63
	s_nop 3
	v_mov_b32_e32 v68, s3
	v_fmamk_f32 v68, v68, 0x3a800000, v74
	v_rsq_f32_e32 v68, v68
	s_nop 0
	v_pk_mul_f32 v[16:17], v[16:17], v[68:69] op_sel_hi:[1,0]
	v_pk_mul_f32 v[18:19], v[18:19], v[68:69] op_sel_hi:[1,0]
	v_pk_mul_f32 v[20:21], v[20:21], v[68:69] op_sel_hi:[1,0]
	v_pk_mul_f32 v[22:23], v[22:23], v[68:69] op_sel_hi:[1,0]
	v_pk_mul_f32 v[24:25], v[24:25], v[68:69] op_sel_hi:[1,0]
	v_pk_mul_f32 v[26:27], v[26:27], v[68:69] op_sel_hi:[1,0]
	v_pk_mul_f32 v[28:29], v[28:29], v[68:69] op_sel_hi:[1,0]
	v_pk_mul_f32 v[30:31], v[30:31], v[68:69] op_sel_hi:[1,0]
	v_pk_fma_f32 v[16:17], v[50:51], v[16:17], v[78:79]
	v_pk_fma_f32 v[18:19], v[52:53], v[18:19], v[80:81]
	v_pk_fma_f32 v[20:21], v[54:55], v[20:21], v[82:83]
	v_pk_fma_f32 v[22:23], v[56:57], v[22:23], v[84:85]
	v_pk_fma_f32 v[24:25], v[58:59], v[24:25], v[86:87]
	v_pk_fma_f32 v[26:27], v[60:61], v[26:27], v[88:89]
	v_pk_fma_f32 v[28:29], v[62:63], v[28:29], v[90:91]
	v_pk_fma_f32 v[30:31], v[64:65], v[30:31], v[92:93]
	v_cvt_pk_bf16_f32 v16, v16, v17
	v_cvt_pk_bf16_f32 v17, v18, v19
	v_cvt_pk_bf16_f32 v20, v20, v21
	v_cvt_pk_bf16_f32 v21, v22, v23
	v_cvt_pk_bf16_f32 v24, v24, v25
	v_cvt_pk_bf16_f32 v25, v26, v27
	v_cvt_pk_bf16_f32 v28, v28, v29
	v_cvt_pk_bf16_f32 v29, v30, v31
	global_store_dwordx2 v67, v[16:17], s[6:7] offset:0
	global_store_dwordx2 v67, v[20:21], s[6:7] offset:512
	global_store_dwordx2 v67, v[24:25], s[6:7] offset:1024
	global_store_dwordx2 v67, v[28:29], s[6:7] offset:1536
	s_add_u32 s6, s6, 0x800
	s_addc_u32 s7, s7, 0
	s_waitcnt vmcnt(12)
	v_pk_mul_f32 v[70:71], v[32:33], v[32:33]
	v_pk_mul_f32 v[72:73], v[34:35], v[34:35]
	v_pk_fma_f32 v[70:71], v[36:37], v[36:37], v[70:71]
	v_pk_fma_f32 v[72:73], v[38:39], v[38:39], v[72:73]
	v_pk_fma_f32 v[70:71], v[40:41], v[40:41], v[70:71]
	v_pk_fma_f32 v[72:73], v[42:43], v[42:43], v[72:73]
	v_pk_fma_f32 v[70:71], v[44:45], v[44:45], v[70:71]
	v_pk_fma_f32 v[72:73], v[46:47], v[46:47], v[72:73]
	s_nop 0
	v_pk_add_f32 v[70:71], v[70:71], v[72:73]
	s_nop 0
	v_add_f32_e32 v68, v70, v71
	s_nop 1
	v_add_f32_dpp v68, v68, v68 quad_perm:[1,0,3,2] row_mask:0xf bank_mask:0xf bound_ctrl:1
	s_nop 1
	v_add_f32_dpp v68, v68, v68 quad_perm:[2,3,0,1] row_mask:0xf bank_mask:0xf bound_ctrl:1
	s_nop 1
	v_add_f32_dpp v68, v68, v68 row_half_mirror row_mask:0xf bank_mask:0xf bound_ctrl:1
	s_nop 1
	v_add_f32_dpp v68, v68, v68 row_mirror row_mask:0xf bank_mask:0xf bound_ctrl:1
	s_nop 1
	v_add_f32_dpp v68, v68, v68 row_bcast:15 row_mask:0xa bank_mask:0xf
	s_nop 1
	v_add_f32_dpp v68, v68, v68 row_bcast:31 row_mask:0xc bank_mask:0xf
	s_nop 1
	v_readlane_b32 s3, v68, 63
	s_nop 3
	v_mov_b32_e32 v68, s3
	v_fmamk_f32 v68, v68, 0x3a800000, v74
	v_rsq_f32_e32 v68, v68
	s_nop 0
	v_pk_mul_f32 v[32:33], v[32:33], v[68:69] op_sel_hi:[1,0]
	v_pk_mul_f32 v[34:35], v[34:35], v[68:69] op_sel_hi:[1,0]
	v_pk_mul_f32 v[36:37], v[36:37], v[68:69] op_sel_hi:[1,0]
	v_pk_mul_f32 v[38:39], v[38:39], v[68:69] op_sel_hi:[1,0]
	v_pk_mul_f32 v[40:41], v[40:41], v[68:69] op_sel_hi:[1,0]
	v_pk_mul_f32 v[42:43], v[42:43], v[68:69] op_sel_hi:[1,0]
	v_pk_mul_f32 v[44:45], v[44:45], v[68:69] op_sel_hi:[1,0]
	v_pk_mul_f32 v[46:47], v[46:47], v[68:69] op_sel_hi:[1,0]
	v_pk_fma_f32 v[32:33], v[50:51], v[32:33], v[78:79]
	v_pk_fma_f32 v[34:35], v[52:53], v[34:35], v[80:81]
	v_pk_fma_f32 v[36:37], v[54:55], v[36:37], v[82:83]
	v_pk_fma_f32 v[38:39], v[56:57], v[38:39], v[84:85]
	v_pk_fma_f32 v[40:41], v[58:59], v[40:41], v[86:87]
	v_pk_fma_f32 v[42:43], v[60:61], v[42:43], v[88:89]
	v_pk_fma_f32 v[44:45], v[62:63], v[44:45], v[90:91]
	v_pk_fma_f32 v[46:47], v[64:65], v[46:47], v[92:93]
	v_cvt_pk_bf16_f32 v32, v32, v33
	v_cvt_pk_bf16_f32 v33, v34, v35
	v_cvt_pk_bf16_f32 v36, v36, v37
	v_cvt_pk_bf16_f32 v37, v38, v39
	v_cvt_pk_bf16_f32 v40, v40, v41
	v_cvt_pk_bf16_f32 v41, v42, v43
	v_cvt_pk_bf16_f32 v44, v44, v45
	v_cvt_pk_bf16_f32 v45, v46, v47
	global_store_dwordx2 v67, v[32:33], s[6:7] offset:0
	global_store_dwordx2 v67, v[36:37], s[6:7] offset:512
	global_store_dwordx2 v67, v[40:41], s[6:7] offset:1024
	global_store_dwordx2 v67, v[44:45], s[6:7] offset:1536
	s_add_u32 s6, s6, 0x800
	s_addc_u32 s7, s7, 0
	s_waitcnt vmcnt(8)
	v_pk_mul_f32 v[70:71], v[0:1], v[0:1]
	v_pk_mul_f32 v[72:73], v[2:3], v[2:3]
	v_pk_fma_f32 v[70:71], v[4:5], v[4:5], v[70:71]
	v_pk_fma_f32 v[72:73], v[6:7], v[6:7], v[72:73]
	v_pk_fma_f32 v[70:71], v[8:9], v[8:9], v[70:71]
	v_pk_fma_f32 v[72:73], v[10:11], v[10:11], v[72:73]
	v_pk_fma_f32 v[70:71], v[12:13], v[12:13], v[70:71]
	v_pk_fma_f32 v[72:73], v[14:15], v[14:15], v[72:73]
	s_nop 0
	v_pk_add_f32 v[70:71], v[70:71], v[72:73]
	s_nop 0
	v_add_f32_e32 v68, v70, v71
	s_nop 1
	v_add_f32_dpp v68, v68, v68 quad_perm:[1,0,3,2] row_mask:0xf bank_mask:0xf bound_ctrl:1
	s_nop 1
	v_add_f32_dpp v68, v68, v68 quad_perm:[2,3,0,1] row_mask:0xf bank_mask:0xf bound_ctrl:1
	s_nop 1
	v_add_f32_dpp v68, v68, v68 row_half_mirror row_mask:0xf bank_mask:0xf bound_ctrl:1
	s_nop 1
	v_add_f32_dpp v68, v68, v68 row_mirror row_mask:0xf bank_mask:0xf bound_ctrl:1
	s_nop 1
	v_add_f32_dpp v68, v68, v68 row_bcast:15 row_mask:0xa bank_mask:0xf
	s_nop 1
	v_add_f32_dpp v68, v68, v68 row_bcast:31 row_mask:0xc bank_mask:0xf
	s_nop 1
	v_readlane_b32 s3, v68, 63
	s_nop 3
	v_mov_b32_e32 v68, s3
	v_fmamk_f32 v68, v68, 0x3a800000, v74
	v_rsq_f32_e32 v68, v68
	s_nop 0
	v_pk_mul_f32 v[0:1], v[0:1], v[68:69] op_sel_hi:[1,0]
	v_pk_mul_f32 v[2:3], v[2:3], v[68:69] op_sel_hi:[1,0]
	v_pk_mul_f32 v[4:5], v[4:5], v[68:69] op_sel_hi:[1,0]
	v_pk_mul_f32 v[6:7], v[6:7], v[68:69] op_sel_hi:[1,0]
	v_pk_mul_f32 v[8:9], v[8:9], v[68:69] op_sel_hi:[1,0]
	v_pk_mul_f32 v[10:11], v[10:11], v[68:69] op_sel_hi:[1,0]
	v_pk_mul_f32 v[12:13], v[12:13], v[68:69] op_sel_hi:[1,0]
	v_pk_mul_f32 v[14:15], v[14:15], v[68:69] op_sel_hi:[1,0]
	v_pk_fma_f32 v[0:1], v[50:51], v[0:1], v[78:79]
	v_pk_fma_f32 v[2:3], v[52:53], v[2:3], v[80:81]
	v_pk_fma_f32 v[4:5], v[54:55], v[4:5], v[82:83]
	v_pk_fma_f32 v[6:7], v[56:57], v[6:7], v[84:85]
	v_pk_fma_f32 v[8:9], v[58:59], v[8:9], v[86:87]
	v_pk_fma_f32 v[10:11], v[60:61], v[10:11], v[88:89]
	v_pk_fma_f32 v[12:13], v[62:63], v[12:13], v[90:91]
	v_pk_fma_f32 v[14:15], v[64:65], v[14:15], v[92:93]
	v_cvt_pk_bf16_f32 v0, v0, v1
	v_cvt_pk_bf16_f32 v1, v2, v3
	v_cvt_pk_bf16_f32 v4, v4, v5
	v_cvt_pk_bf16_f32 v5, v6, v7
	v_cvt_pk_bf16_f32 v8, v8, v9
	v_cvt_pk_bf16_f32 v9, v10, v11
	v_cvt_pk_bf16_f32 v12, v12, v13
	v_cvt_pk_bf16_f32 v13, v14, v15
	global_store_dwordx2 v67, v[0:1], s[6:7] offset:0
	global_store_dwordx2 v67, v[4:5], s[6:7] offset:512
	global_store_dwordx2 v67, v[8:9], s[6:7] offset:1024
	global_store_dwordx2 v67, v[12:13], s[6:7] offset:1536
	s_add_u32 s6, s6, 0x800
	s_addc_u32 s7, s7, 0
	s_branch .LBB0_137
.Lnorm_orig_0:
	s_load_dwordx2 s[4:5], s[2:3], 0x0
	v_ashrrev_i32_e32 v49, 31, v48
	v_lshlrev_b32_e32 v2, 4, v16
	v_lshlrev_b64 v[18:19], 12, v[48:49]
	v_and_b32_e32 v60, 0x3f0, v2
	s_waitcnt lgkmcnt(0)
	v_lshl_add_u64 v[0:1], s[4:5], 0, v[18:19]
	v_mov_b32_e32 v61, 0
	v_lshl_add_u64 v[20:21], v[0:1], 0, v[60:61]
	s_load_dwordx2 s[6:7], s[2:3], 0x20
	s_load_dwordx2 s[8:9], s[2:3], 0xe0
	global_load_dwordx4 v[12:15], v[20:21], off
	global_load_dwordx4 v[8:11], v[20:21], off offset:1024
	global_load_dwordx4 v[4:7], v[20:21], off offset:2048
	global_load_dwordx4 v[0:3], v[20:21], off offset:3072
	v_mbcnt_lo_u32_b32 v17, -1, 0
	v_mbcnt_hi_u32_b32 v17, -1, v17
	v_and_b32_e32 v20, 64, v17
	v_add_u32_e32 v20, 64, v20
	v_xor_b32_e32 v21, 32, v17
	v_cmp_lt_i32_e32 vcc, v21, v20
	s_mov_b64 s[2:3], 0x781000
	v_and_b32_e32 v22, 63, v16
	v_cndmask_b32_e32 v21, v17, v21, vcc
	v_lshlrev_b32_e32 v77, 2, v21
	v_xor_b32_e32 v21, 16, v17
	v_cmp_lt_i32_e32 vcc, v21, v20
	v_lshl_or_b32 v18, v22, 4, v18
	v_mov_b32_e32 v83, -1
	v_cndmask_b32_e32 v21, v17, v21, vcc
	v_lshlrev_b32_e32 v78, 2, v21
	v_xor_b32_e32 v21, 8, v17
	v_cmp_lt_i32_e32 vcc, v21, v20
	s_waitcnt lgkmcnt(0)
	v_lshl_add_u64 v[50:51], s[6:7], 0, v[60:61]
	s_mov_b32 s12, 0x800000
	v_cndmask_b32_e32 v21, v17, v21, vcc
	v_lshlrev_b32_e32 v79, 2, v21
	v_xor_b32_e32 v21, 4, v17
	v_cmp_lt_i32_e32 vcc, v21, v20
	s_mov_b64 s[6:7], 0x800
	v_mov_b32_e32 v62, v61
	v_cndmask_b32_e32 v21, v17, v21, vcc
	v_lshlrev_b32_e32 v80, 2, v21
	v_xor_b32_e32 v21, 2, v17
	v_cmp_lt_i32_e32 vcc, v21, v20
	v_mov_b32_e32 v63, v61
	v_mov_b32_e32 v64, v61
	v_cndmask_b32_e32 v21, v17, v21, vcc
	v_lshlrev_b32_e32 v81, 2, v21
	v_xor_b32_e32 v21, 1, v17
	v_cmp_lt_i32_e32 vcc, v21, v20
	v_mov_b32_e32 v65, v61
	v_mov_b32_e32 v66, v61
	v_cndmask_b32_e32 v17, v17, v21, vcc
	v_lshl_add_u64 v[20:21], s[8:9], 0, v[60:61]
	v_lshl_add_u64 v[52:53], v[20:21], 0, s[2:3]
	s_mov_b64 s[2:3], 0x780000
	v_lshl_add_u64 v[54:55], v[20:21], 0, s[2:3]
	v_lshlrev_b64 v[20:21], 11, v[48:49]
	v_lshl_or_b32 v20, v22, 3, v20
	v_lshlrev_b32_e32 v82, 2, v17
	v_lshl_add_u64 v[16:17], s[8:9], 0, v[20:21]
	s_mov_b64 s[2:3], 0x2d00000
	v_lshl_add_u64 v[56:57], v[16:17], 0, s[2:3]
	v_lshl_add_u64 v[16:17], s[4:5], 0, v[18:19]
	s_mov_b64 s[2:3], 0x1c00
	v_lshl_add_u64 v[58:59], v[16:17], 0, s[2:3]
	s_mov_b64 s[4:5], 0
	v_mov_b32_e32 v49, 0x358637bd
	s_mov_b64 s[8:9], 0x1000
	v_mov_b32_e32 v60, v61
	v_mov_b32_e32 v67, v61
	v_mov_b32_e32 v68, v61
	v_mov_b32_e32 v69, v61
	v_mov_b32_e32 v70, v61
	v_mov_b32_e32 v71, v61
	v_mov_b32_e32 v72, v61
	v_mov_b32_e32 v73, v61
	v_mov_b32_e32 v74, v61
	v_mov_b32_e32 v75, v61
	s_branch .LBB0_133

.LBB0_702:
	s_andn2_b64 vcc, exec, s[0:1]
	s_cbranch_vccnz .LBB0_764
	v_readlane_b32 s2, v254, 0
	v_readlane_b32 s3, v254, 1
	v_readlane_b32 s0, v254, 2
	s_waitcnt vmcnt(0)
	v_mbcnt_lo_u32_b32 v8, -1, 0
	v_mbcnt_hi_u32_b32 v8, -1, v8
	s_nop 0
	v_lshl_add_u32 v0, s0, 6, v8
	v_ashrrev_i32_e32 v0, 6, v0
	v_readlane_b32 s0, v254, 9
	s_nop 1
	v_add_u32_e32 v0, s0, v0
	v_readlane_b32 s0, v255, 12
	s_nop 1
	v_mul_lo_u32 v48, v0, s0
	v_add_u32_e32 v0, s0, v48
	v_min_i32_e32 v76, 0x4000, v0
	v_cmp_lt_i32_e32 vcc, v48, v76
	s_and_saveexec_b64 s[0:1], vcc
	s_cbranch_execz .LBB0_710
	s_cmp_lg_u32 s80, 0x100
	s_cbranch_scc1 .Lnorm_orig_1
	v_readlane_b32 s2, v254, 0
	v_readlane_b32 s3, v254, 1
	v_readfirstlane_b32 s100, v48
	s_nop 3
	s_load_dwordx2 s[4:5], s[2:3], 0x0
	s_load_dwordx2 s[98:99], s[2:3], 0x20
	s_load_dwordx2 s[6:7], s[2:3], 0xe0
	v_mbcnt_lo_u32_b32 v66, -1, 0
	v_mbcnt_hi_u32_b32 v66, -1, v66
	v_lshlrev_b32_e32 v67, 3, v66
	v_lshlrev_b32_e32 v66, 4, v66
	v_mov_b32_e32 v74, 0x358637bd
	s_waitcnt lgkmcnt(0)
	s_mov_b32 s2, s100
	s_add_u32 s3, s2, 0
	s_lshl_b32 s3, s3, 12
	s_add_u32 s4, s4, s3
	s_addc_u32 s5, s5, 0
	global_load_dwordx4 v[50:53], v66, s[98:99] offset:0
	global_load_dwordx4 v[54:57], v66, s[98:99] offset:1024
	global_load_dwordx4 v[58:61], v66, s[98:99] offset:2048
	global_load_dwordx4 v[62:65], v66, s[98:99] offset:3072
	s_add_u32 s3, s2, 0
	s_lshr_b32 s3, s3, 12
	s_mul_i32 s3, s3, 0x6000
	s_add_u32 s100, s6, s3
	s_addc_u32 s101, s7, 0
	s_add_u32 s100, s100, 0x780000
	s_addc_u32 s101, s101, 0
	s_add_u32 s98, s100, 4096
	s_addc_u32 s99, s101, 0
	global_load_dwordx4 v[32:35], v66, s[98:99] offset:0
	global_load_dwordx4 v[36:39], v66, s[98:99] offset:1024
	global_load_dwordx4 v[40:43], v66, s[98:99] offset:2048
	global_load_dwordx4 v[44:47], v66, s[98:99] offset:3072
	s_add_u32 s100, s100, 0
	s_addc_u32 s101, s101, 0
	global_load_dwordx4 v[78:81], v66, s[100:101] offset:0
	global_load_dwordx4 v[82:85], v66, s[100:101] offset:1024
	global_load_dwordx4 v[86:89], v66, s[100:101] offset:2048
	global_load_dwordx4 v[90:93], v66, s[100:101] offset:3072
	s_add_u32 s6, s6, 0x1c00000
	s_addc_u32 s7, s7, 0
	s_lshl_b32 s3, s2, 11
	s_add_u32 s6, s6, s3
	s_addc_u32 s7, s7, 0
	global_load_dwordx4 v[0:3], v66, s[4:5] offset:0
	global_load_dwordx4 v[4:7], v66, s[4:5] offset:1024
	global_load_dwordx4 v[8:11], v66, s[4:5] offset:2048
	global_load_dwordx4 v[12:15], v66, s[4:5] offset:3072
	s_add_u32 s4, s4, 0x1000
	s_addc_u32 s5, s5, 0
	global_load_dwordx4 v[16:19], v66, s[4:5] offset:0
	global_load_dwordx4 v[20:23], v66, s[4:5] offset:1024
	global_load_dwordx4 v[24:27], v66, s[4:5] offset:2048
	global_load_dwordx4 v[28:31], v66, s[4:5] offset:3072
	s_add_u32 s4, s4, 0x1000
	s_addc_u32 s5, s5, 0
	s_waitcnt vmcnt(8)
	v_pk_add_f32 v[32:33], v[32:33], 1.0 op_sel_hi:[1,0]
	v_pk_add_f32 v[34:35], v[34:35], 1.0 op_sel_hi:[1,0]
	v_pk_add_f32 v[36:37], v[36:37], 1.0 op_sel_hi:[1,0]
	v_pk_add_f32 v[38:39], v[38:39], 1.0 op_sel_hi:[1,0]
	v_pk_add_f32 v[40:41], v[40:41], 1.0 op_sel_hi:[1,0]
	v_pk_add_f32 v[42:43], v[42:43], 1.0 op_sel_hi:[1,0]
	v_pk_add_f32 v[44:45], v[44:45], 1.0 op_sel_hi:[1,0]
	v_pk_add_f32 v[46:47], v[46:47], 1.0 op_sel_hi:[1,0]
	v_pk_mul_f32 v[50:51], v[50:51], v[32:33]
	v_pk_mul_f32 v[52:53], v[52:53], v[34:35]
	v_pk_mul_f32 v[54:55], v[54:55], v[36:37]
	v_pk_mul_f32 v[56:57], v[56:57], v[38:39]
	v_pk_mul_f32 v[58:59], v[58:59], v[40:41]
	v_pk_mul_f32 v[60:61], v[60:61], v[42:43]
	v_pk_mul_f32 v[62:63], v[62:63], v[44:45]
	v_pk_mul_f32 v[64:65], v[64:65], v[46:47]
	global_load_dwordx4 v[32:35], v66, s[4:5] offset:0
	global_load_dwordx4 v[36:39], v66, s[4:5] offset:1024
	global_load_dwordx4 v[40:43], v66, s[4:5] offset:2048
	global_load_dwordx4 v[44:47], v66, s[4:5] offset:3072
	s_add_u32 s4, s4, 0x1000
	s_addc_u32 s5, s5, 0
	s_waitcnt vmcnt(8)
	v_pk_mul_f32 v[70:71], v[0:1], v[0:1]
	v_pk_mul_f32 v[72:73], v[2:3], v[2:3]
	v_pk_fma_f32 v[70:71], v[4:5], v[4:5], v[70:71]
	v_pk_fma_f32 v[72:73], v[6:7], v[6:7], v[72:73]
	v_pk_fma_f32 v[70:71], v[8:9], v[8:9], v[70:71]
	v_pk_fma_f32 v[72:73], v[10:11], v[10:11], v[72:73]
	v_pk_fma_f32 v[70:71], v[12:13], v[12:13], v[70:71]
	v_pk_fma_f32 v[72:73], v[14:15], v[14:15], v[72:73]
	s_nop 0
	v_pk_add_f32 v[70:71], v[70:71], v[72:73]
	s_nop 0
	v_add_f32_e32 v68, v70, v71
	s_nop 1
	v_add_f32_dpp v68, v68, v68 quad_perm:[1,0,3,2] row_mask:0xf bank_mask:0xf bound_ctrl:1
	s_nop 1
	v_add_f32_dpp v68, v68, v68 quad_perm:[2,3,0,1] row_mask:0xf bank_mask:0xf bound_ctrl:1
	s_nop 1
	v_add_f32_dpp v68, v68, v68 row_half_mirror row_mask:0xf bank_mask:0xf bound_ctrl:1
	s_nop 1
	v_add_f32_dpp v68, v68, v68 row_mirror row_mask:0xf bank_mask:0xf bound_ctrl:1
	s_nop 1
	v_add_f32_dpp v68, v68, v68 row_bcast:15 row_mask:0xa bank_mask:0xf
	s_nop 1
	v_add_f32_dpp v68, v68, v68 row_bcast:31 row_mask:0xc bank_mask:0xf
	s_nop 1
	v_readlane_b32 s3, v68, 63
	s_nop 3
	v_mov_b32_e32 v68, s3
	v_fmamk_f32 v68, v68, 0x3a800000, v74
	v_rsq_f32_e32 v68, v68
	s_nop 0
	v_pk_mul_f32 v[0:1], v[0:1], v[68:69] op_sel_hi:[1,0]
	v_pk_mul_f32 v[2:3], v[2:3], v[68:69] op_sel_hi:[1,0]
	v_pk_mul_f32 v[4:5], v[4:5], v[68:69] op_sel_hi:[1,0]
	v_pk_mul_f32 v[6:7], v[6:7], v[68:69] op_sel_hi:[1,0]
	v_pk_mul_f32 v[8:9], v[8:9], v[68:69] op_sel_hi:[1,0]
	v_pk_mul_f32 v[10:11], v[10:11], v[68:69] op_sel_hi:[1,0]
	v_pk_mul_f32 v[12:13], v[12:13], v[68:69] op_sel_hi:[1,0]
	v_pk_mul_f32 v[14:15], v[14:15], v[68:69] op_sel_hi:[1,0]
	v_pk_fma_f32 v[0:1], v[50:51], v[0:1], v[78:79]
	v_pk_fma_f32 v[2:3], v[52:53], v[2:3], v[80:81]
	v_pk_fma_f32 v[4:5], v[54:55], v[4:5], v[82:83]
	v_pk_fma_f32 v[6:7], v[56:57], v[6:7], v[84:85]
	v_pk_fma_f32 v[8:9], v[58:59], v[8:9], v[86:87]
	v_pk_fma_f32 v[10:11], v[60:61], v[10:11], v[88:89]
	v_pk_fma_f32 v[12:13], v[62:63], v[12:13], v[90:91]
	v_pk_fma_f32 v[14:15], v[64:65], v[14:15], v[92:93]
	v_cvt_pk_bf16_f32 v0, v0, v1
	v_cvt_pk_bf16_f32 v1, v2, v3
	v_cvt_pk_bf16_f32 v4, v4, v5
	v_cvt_pk_bf16_f32 v5, v6, v7
	v_cvt_pk_bf16_f32 v8, v8, v9
	v_cvt_pk_bf16_f32 v9, v10, v11
	v_cvt_pk_bf16_f32 v12, v12, v13
	v_cvt_pk_bf16_f32 v13, v14, v15
	global_store_dwordx2 v67, v[0:1], s[6:7] offset:0
	global_store_dwordx2 v67, v[4:5], s[6:7] offset:512
	global_store_dwordx2 v67, v[8:9], s[6:7] offset:1024
	global_store_dwordx2 v67, v[12:13], s[6:7] offset:1536
	s_add_u32 s6, s6, 0x800
	s_addc_u32 s7, s7, 0
	global_load_dwordx4 v[0:3], v66, s[4:5] offset:0
	global_load_dwordx4 v[4:7], v66, s[4:5] offset:1024
	global_load_dwordx4 v[8:11], v66, s[4:5] offset:2048
	global_load_dwordx4 v[12:15], v66, s[4:5] offset:3072
	s_add_u32 s4, s4, 0x1000
	s_addc_u32 s5, s5, 0
	s_waitcnt vmcnt(12)
	v_pk_mul_f32 v[70:71], v[16:17], v[16:17]
	v_pk_mul_f32 v[72:73], v[18:19], v[18:19]
	v_pk_fma_f32 v[70:71], v[20:21], v[20:21], v[70:71]
	v_pk_fma_f32 v[72:73], v[22:23], v[22:23], v[72:73]
	v_pk_fma_f32 v[70:71], v[24:25], v[24:25], v[70:71]
	v_pk_fma_f32 v[72:73], v[26:27], v[26:27], v[72:73]
	v_pk_fma_f32 v[70:71], v[28:29], v[28:29], v[70:71]
	v_pk_fma_f32 v[72:73], v[30:31], v[30:31], v[72:73]
	s_nop 0
	v_pk_add_f32 v[70:71], v[70:71], v[72:73]
	s_nop 0
	v_add_f32_e32 v68, v70, v71
	s_nop 1
	v_add_f32_dpp v68, v68, v68 quad_perm:[1,0,3,2] row_mask:0xf bank_mask:0xf bound_ctrl:1
	s_nop 1
	v_add_f32_dpp v68, v68, v68 quad_perm:[2,3,0,1] row_mask:0xf bank_mask:0xf bound_ctrl:1
	s_nop 1
	v_add_f32_dpp v68, v68, v68 row_half_mirror row_mask:0xf bank_mask:0xf bound_ctrl:1
	s_nop 1
	v_add_f32_dpp v68, v68, v68 row_mirror row_mask:0xf bank_mask:0xf bound_ctrl:1
	s_nop 1
	v_add_f32_dpp v68, v68, v68 row_bcast:15 row_mask:0xa bank_mask:0xf
	s_nop 1
	v_add_f32_dpp v68, v68, v68 row_bcast:31 row_mask:0xc bank_mask:0xf
	s_nop 1
	v_readlane_b32 s3, v68, 63
	s_nop 3
	v_mov_b32_e32 v68, s3
	v_fmamk_f32 v68, v68, 0x3a800000, v74
	v_rsq_f32_e32 v68, v68
	s_nop 0
	v_pk_mul_f32 v[16:17], v[16:17], v[68:69] op_sel_hi:[1,0]
	v_pk_mul_f32 v[18:19], v[18:19], v[68:69] op_sel_hi:[1,0]
	v_pk_mul_f32 v[20:21], v[20:21], v[68:69] op_sel_hi:[1,0]
	v_pk_mul_f32 v[22:23], v[22:23], v[68:69] op_sel_hi:[1,0]
	v_pk_mul_f32 v[24:25], v[24:25], v[68:69] op_sel_hi:[1,0]
	v_pk_mul_f32 v[26:27], v[26:27], v[68:69] op_sel_hi:[1,0]
	v_pk_mul_f32 v[28:29], v[28:29], v[68:69] op_sel_hi:[1,0]
	v_pk_mul_f32 v[30:31], v[30:31], v[68:69] op_sel_hi:[1,0]
	v_pk_fma_f32 v[16:17], v[50:51], v[16:17], v[78:79]
	v_pk_fma_f32 v[18:19], v[52:53], v[18:19], v[80:81]
	v_pk_fma_f32 v[20:21], v[54:55], v[20:21], v[82:83]
	v_pk_fma_f32 v[22:23], v[56:57], v[22:23], v[84:85]
	v_pk_fma_f32 v[24:25], v[58:59], v[24:25], v[86:87]
	v_pk_fma_f32 v[26:27], v[60:61], v[26:27], v[88:89]
	v_pk_fma_f32 v[28:29], v[62:63], v[28:29], v[90:91]
	v_pk_fma_f32 v[30:31], v[64:65], v[30:31], v[92:93]
	v_cvt_pk_bf16_f32 v16, v16, v17
	v_cvt_pk_bf16_f32 v17, v18, v19
	v_cvt_pk_bf16_f32 v20, v20, v21
	v_cvt_pk_bf16_f32 v21, v22, v23
	v_cvt_pk_bf16_f32 v24, v24, v25
	v_cvt_pk_bf16_f32 v25, v26, v27
	v_cvt_pk_bf16_f32 v28, v28, v29
	v_cvt_pk_bf16_f32 v29, v30, v31
	global_store_dwordx2 v67, v[16:17], s[6:7] offset:0
	global_store_dwordx2 v67, v[20:21], s[6:7] offset:512
	global_store_dwordx2 v67, v[24:25], s[6:7] offset:1024
	global_store_dwordx2 v67, v[28:29], s[6:7] offset:1536
	s_add_u32 s6, s6, 0x800
	s_addc_u32 s7, s7, 0
	global_load_dwordx4 v[16:19], v66, s[4:5] offset:0
	global_load_dwordx4 v[20:23], v66, s[4:5] offset:1024
	global_load_dwordx4 v[24:27], v66, s[4:5] offset:2048
	global_load_dwordx4 v[28:31], v66, s[4:5] offset:3072
	s_add_u32 s4, s4, 0x1000
	s_addc_u32 s5, s5, 0
	s_waitcnt vmcnt(16)
	v_pk_mul_f32 v[70:71], v[32:33], v[32:33]
	v_pk_mul_f32 v[72:73], v[34:35], v[34:35]
	v_pk_fma_f32 v[70:71], v[36:37], v[36:37], v[70:71]
	v_pk_fma_f32 v[72:73], v[38:39], v[38:39], v[72:73]
	v_pk_fma_f32 v[70:71], v[40:41], v[40:41], v[70:71]
	v_pk_fma_f32 v[72:73], v[42:43], v[42:43], v[72:73]
	v_pk_fma_f32 v[70:71], v[44:45], v[44:45], v[70:71]
	v_pk_fma_f32 v[72:73], v[46:47], v[46:47], v[72:73]
	s_nop 0
	v_pk_add_f32 v[70:71], v[70:71], v[72:73]
	s_nop 0
	v_add_f32_e32 v68, v70, v71
	s_nop 1
	v_add_f32_dpp v68, v68, v68 quad_perm:[1,0,3,2] row_mask:0xf bank_mask:0xf bound_ctrl:1
	s_nop 1
	v_add_f32_dpp v68, v68, v68 quad_perm:[2,3,0,1] row_mask:0xf bank_mask:0xf bound_ctrl:1
	s_nop 1
	v_add_f32_dpp v68, v68, v68 row_half_mirror row_mask:0xf bank_mask:0xf bound_ctrl:1
	s_nop 1
	v_add_f32_dpp v68, v68, v68 row_mirror row_mask:0xf bank_mask:0xf bound_ctrl:1
	s_nop 1
	v_add_f32_dpp v68, v68, v68 row_bcast:15 row_mask:0xa bank_mask:0xf
	s_nop 1
	v_add_f32_dpp v68, v68, v68 row_bcast:31 row_mask:0xc bank_mask:0xf
	s_nop 1
	v_readlane_b32 s3, v68, 63
	s_nop 3
	v_mov_b32_e32 v68, s3
	v_fmamk_f32 v68, v68, 0x3a800000, v74
	v_rsq_f32_e32 v68, v68
	s_nop 0
	v_pk_mul_f32 v[32:33], v[32:33], v[68:69] op_sel_hi:[1,0]
	v_pk_mul_f32 v[34:35], v[34:35], v[68:69] op_sel_hi:[1,0]
	v_pk_mul_f32 v[36:37], v[36:37], v[68:69] op_sel_hi:[1,0]
	v_pk_mul_f32 v[38:39], v[38:39], v[68:69] op_sel_hi:[1,0]
	v_pk_mul_f32 v[40:41], v[40:41], v[68:69] op_sel_hi:[1,0]
	v_pk_mul_f32 v[42:43], v[42:43], v[68:69] op_sel_hi:[1,0]
	v_pk_mul_f32 v[44:45], v[44:45], v[68:69] op_sel_hi:[1,0]
	v_pk_mul_f32 v[46:47], v[46:47], v[68:69] op_sel_hi:[1,0]
	v_pk_fma_f32 v[32:33], v[50:51], v[32:33], v[78:79]
	v_pk_fma_f32 v[34:35], v[52:53], v[34:35], v[80:81]
	v_pk_fma_f32 v[36:37], v[54:55], v[36:37], v[82:83]
	v_pk_fma_f32 v[38:39], v[56:57], v[38:39], v[84:85]
	v_pk_fma_f32 v[40:41], v[58:59], v[40:41], v[86:87]
	v_pk_fma_f32 v[42:43], v[60:61], v[42:43], v[88:89]
	v_pk_fma_f32 v[44:45], v[62:63], v[44:45], v[90:91]
	v_pk_fma_f32 v[46:47], v[64:65], v[46:47], v[92:93]
	v_cvt_pk_bf16_f32 v32, v32, v33
	v_cvt_pk_bf16_f32 v33, v34, v35
	v_cvt_pk_bf16_f32 v36, v36, v37
	v_cvt_pk_bf16_f32 v37, v38, v39
	v_cvt_pk_bf16_f32 v40, v40, v41
	v_cvt_pk_bf16_f32 v41, v42, v43
	v_cvt_pk_bf16_f32 v44, v44, v45
	v_cvt_pk_bf16_f32 v45, v46, v47
	global_store_dwordx2 v67, v[32:33], s[6:7] offset:0
	global_store_dwordx2 v67, v[36:37], s[6:7] offset:512
	global_store_dwordx2 v67, v[40:41], s[6:7] offset:1024
	global_store_dwordx2 v67, v[44:45], s[6:7] offset:1536
	s_add_u32 s6, s6, 0x800
	s_addc_u32 s7, s7, 0
	global_load_dwordx4 v[32:35], v66, s[4:5] offset:0
	global_load_dwordx4 v[36:39], v66, s[4:5] offset:1024
	global_load_dwordx4 v[40:43], v66, s[4:5] offset:2048
	global_load_dwordx4 v[44:47], v66, s[4:5] offset:3072
	s_add_u32 s4, s4, 0x1000
	s_addc_u32 s5, s5, 0
	s_waitcnt vmcnt(16)
	v_pk_mul_f32 v[70:71], v[0:1], v[0:1]
	v_pk_mul_f32 v[72:73], v[2:3], v[2:3]
	v_pk_fma_f32 v[70:71], v[4:5], v[4:5], v[70:71]
	v_pk_fma_f32 v[72:73], v[6:7], v[6:7], v[72:73]
	v_pk_fma_f32 v[70:71], v[8:9], v[8:9], v[70:71]
	v_pk_fma_f32 v[72:73], v[10:11], v[10:11], v[72:73]
	v_pk_fma_f32 v[70:71], v[12:13], v[12:13], v[70:71]
	v_pk_fma_f32 v[72:73], v[14:15], v[14:15], v[72:73]
	s_nop 0
	v_pk_add_f32 v[70:71], v[70:71], v[72:73]
	s_nop 0
	v_add_f32_e32 v68, v70, v71
	s_nop 1
	v_add_f32_dpp v68, v68, v68 quad_perm:[1,0,3,2] row_mask:0xf bank_mask:0xf bound_ctrl:1
	s_nop 1
	v_add_f32_dpp v68, v68, v68 quad_perm:[2,3,0,1] row_mask:0xf bank_mask:0xf bound_ctrl:1
	s_nop 1
	v_add_f32_dpp v68, v68, v68 row_half_mirror row_mask:0xf bank_mask:0xf bound_ctrl:1
	s_nop 1
	v_add_f32_dpp v68, v68, v68 row_mirror row_mask:0xf bank_mask:0xf bound_ctrl:1
	s_nop 1
	v_add_f32_dpp v68, v68, v68 row_bcast:15 row_mask:0xa bank_mask:0xf
	s_nop 1
	v_add_f32_dpp v68, v68, v68 row_bcast:31 row_mask:0xc bank_mask:0xf
	s_nop 1
	v_readlane_b32 s3, v68, 63
	s_nop 3
	v_mov_b32_e32 v68, s3
	v_fmamk_f32 v68, v68, 0x3a800000, v74
	v_rsq_f32_e32 v68, v68
	s_nop 0
	v_pk_mul_f32 v[0:1], v[0:1], v[68:69] op_sel_hi:[1,0]
	v_pk_mul_f32 v[2:3], v[2:3], v[68:69] op_sel_hi:[1,0]
	v_pk_mul_f32 v[4:5], v[4:5], v[68:69] op_sel_hi:[1,0]
	v_pk_mul_f32 v[6:7], v[6:7], v[68:69] op_sel_hi:[1,0]
	v_pk_mul_f32 v[8:9], v[8:9], v[68:69] op_sel_hi:[1,0]
	v_pk_mul_f32 v[10:11], v[10:11], v[68:69] op_sel_hi:[1,0]
	v_pk_mul_f32 v[12:13], v[12:13], v[68:69] op_sel_hi:[1,0]
	v_pk_mul_f32 v[14:15], v[14:15], v[68:69] op_sel_hi:[1,0]
	v_pk_fma_f32 v[0:1], v[50:51], v[0:1], v[78:79]
	v_pk_fma_f32 v[2:3], v[52:53], v[2:3], v[80:81]
	v_pk_fma_f32 v[4:5], v[54:55], v[4:5], v[82:83]
	v_pk_fma_f32 v[6:7], v[56:57], v[6:7], v[84:85]
	v_pk_fma_f32 v[8:9], v[58:59], v[8:9], v[86:87]
	v_pk_fma_f32 v[10:11], v[60:61], v[10:11], v[88:89]
	v_pk_fma_f32 v[12:13], v[62:63], v[12:13], v[90:91]
	v_pk_fma_f32 v[14:15], v[64:65], v[14:15], v[92:93]
	v_cvt_pk_bf16_f32 v0, v0, v1
	v_cvt_pk_bf16_f32 v1, v2, v3
	v_cvt_pk_bf16_f32 v4, v4, v5
	v_cvt_pk_bf16_f32 v5, v6, v7
	v_cvt_pk_bf16_f32 v8, v8, v9
	v_cvt_pk_bf16_f32 v9, v10, v11
	v_cvt_pk_bf16_f32 v12, v12, v13
	v_cvt_pk_bf16_f32 v13, v14, v15
	global_store_dwordx2 v67, v[0:1], s[6:7] offset:0
	global_store_dwordx2 v67, v[4:5], s[6:7] offset:512
	global_store_dwordx2 v67, v[8:9], s[6:7] offset:1024
	global_store_dwordx2 v67, v[12:13], s[6:7] offset:1536
	s_add_u32 s6, s6, 0x800
	s_addc_u32 s7, s7, 0
	global_load_dwordx4 v[0:3], v66, s[4:5] offset:0
	global_load_dwordx4 v[4:7], v66, s[4:5] offset:1024
	global_load_dwordx4 v[8:11], v66, s[4:5] offset:2048
	global_load_dwordx4 v[12:15], v66, s[4:5] offset:3072
	s_add_u32 s4, s4, 0x1000
	s_addc_u32 s5, s5, 0
	s_waitcnt vmcnt(16)
	v_pk_mul_f32 v[70:71], v[16:17], v[16:17]
	v_pk_mul_f32 v[72:73], v[18:19], v[18:19]
	v_pk_fma_f32 v[70:71], v[20:21], v[20:21], v[70:71]
	v_pk_fma_f32 v[72:73], v[22:23], v[22:23], v[72:73]
	v_pk_fma_f32 v[70:71], v[24:25], v[24:25], v[70:71]
	v_pk_fma_f32 v[72:73], v[26:27], v[26:27], v[72:73]
	v_pk_fma_f32 v[70:71], v[28:29], v[28:29], v[70:71]
	v_pk_fma_f32 v[72:73], v[30:31], v[30:31], v[72:73]
	s_nop 0
	v_pk_add_f32 v[70:71], v[70:71], v[72:73]
	s_nop 0
	v_add_f32_e32 v68, v70, v71
	s_nop 1
	v_add_f32_dpp v68, v68, v68 quad_perm:[1,0,3,2] row_mask:0xf bank_mask:0xf bound_ctrl:1
	s_nop 1
	v_add_f32_dpp v68, v68, v68 quad_perm:[2,3,0,1] row_mask:0xf bank_mask:0xf bound_ctrl:1
	s_nop 1
	v_add_f32_dpp v68, v68, v68 row_half_mirror row_mask:0xf bank_mask:0xf bound_ctrl:1
	s_nop 1
	v_add_f32_dpp v68, v68, v68 row_mirror row_mask:0xf bank_mask:0xf bound_ctrl:1
	s_nop 1
	v_add_f32_dpp v68, v68, v68 row_bcast:15 row_mask:0xa bank_mask:0xf
	s_nop 1
	v_add_f32_dpp v68, v68, v68 row_bcast:31 row_mask:0xc bank_mask:0xf
	s_nop 1
	v_readlane_b32 s3, v68, 63
	s_nop 3
	v_mov_b32_e32 v68, s3
	v_fmamk_f32 v68, v68, 0x3a800000, v74
	v_rsq_f32_e32 v68, v68
	s_nop 0
	v_pk_mul_f32 v[16:17], v[16:17], v[68:69] op_sel_hi:[1,0]
	v_pk_mul_f32 v[18:19], v[18:19], v[68:69] op_sel_hi:[1,0]
	v_pk_mul_f32 v[20:21], v[20:21], v[68:69] op_sel_hi:[1,0]
	v_pk_mul_f32 v[22:23], v[22:23], v[68:69] op_sel_hi:[1,0]
	v_pk_mul_f32 v[24:25], v[24:25], v[68:69] op_sel_hi:[1,0]
	v_pk_mul_f32 v[26:27], v[26:27], v[68:69] op_sel_hi:[1,0]
	v_pk_mul_f32 v[28:29], v[28:29], v[68:69] op_sel_hi:[1,0]
	v_pk_mul_f32 v[30:31], v[30:31], v[68:69] op_sel_hi:[1,0]
	v_pk_fma_f32 v[16:17], v[50:51], v[16:17], v[78:79]
	v_pk_fma_f32 v[18:19], v[52:53], v[18:19], v[80:81]
	v_pk_fma_f32 v[20:21], v[54:55], v[20:21], v[82:83]
	v_pk_fma_f32 v[22:23], v[56:57], v[22:23], v[84:85]
	v_pk_fma_f32 v[24:25], v[58:59], v[24:25], v[86:87]
	v_pk_fma_f32 v[26:27], v[60:61], v[26:27], v[88:89]
	v_pk_fma_f32 v[28:29], v[62:63], v[28:29], v[90:91]
	v_pk_fma_f32 v[30:31], v[64:65], v[30:31], v[92:93]
	v_cvt_pk_bf16_f32 v16, v16, v17
	v_cvt_pk_bf16_f32 v17, v18, v19
	v_cvt_pk_bf16_f32 v20, v20, v21
	v_cvt_pk_bf16_f32 v21, v22, v23
	v_cvt_pk_bf16_f32 v24, v24, v25
	v_cvt_pk_bf16_f32 v25, v26, v27
	v_cvt_pk_bf16_f32 v28, v28, v29
	v_cvt_pk_bf16_f32 v29, v30, v31
	global_store_dwordx2 v67, v[16:17], s[6:7] offset:0
	global_store_dwordx2 v67, v[20:21], s[6:7] offset:512
	global_store_dwordx2 v67, v[24:25], s[6:7] offset:1024
	global_store_dwordx2 v67, v[28:29], s[6:7] offset:1536
	s_add_u32 s6, s6, 0x800
	s_addc_u32 s7, s7, 0
	global_load_dwordx4 v[16:19], v66, s[4:5] offset:0
	global_load_dwordx4 v[20:23], v66, s[4:5] offset:1024
	global_load_dwordx4 v[24:27], v66, s[4:5] offset:2048
	global_load_dwordx4 v[28:31], v66, s[4:5] offset:3072
	s_add_u32 s4, s4, 0x1000
	s_addc_u32 s5, s5, 0
	s_waitcnt vmcnt(16)
	v_pk_mul_f32 v[70:71], v[32:33], v[32:33]
	v_pk_mul_f32 v[72:73], v[34:35], v[34:35]
	v_pk_fma_f32 v[70:71], v[36:37], v[36:37], v[70:71]
	v_pk_fma_f32 v[72:73], v[38:39], v[38:39], v[72:73]
	v_pk_fma_f32 v[70:71], v[40:41], v[40:41], v[70:71]
	v_pk_fma_f32 v[72:73], v[42:43], v[42:43], v[72:73]
	v_pk_fma_f32 v[70:71], v[44:45], v[44:45], v[70:71]
	v_pk_fma_f32 v[72:73], v[46:47], v[46:47], v[72:73]
	s_nop 0
	v_pk_add_f32 v[70:71], v[70:71], v[72:73]
	s_nop 0
	v_add_f32_e32 v68, v70, v71
	s_nop 1
	v_add_f32_dpp v68, v68, v68 quad_perm:[1,0,3,2] row_mask:0xf bank_mask:0xf bound_ctrl:1
	s_nop 1
	v_add_f32_dpp v68, v68, v68 quad_perm:[2,3,0,1] row_mask:0xf bank_mask:0xf bound_ctrl:1
	s_nop 1
	v_add_f32_dpp v68, v68, v68 row_half_mirror row_mask:0xf bank_mask:0xf bound_ctrl:1
	s_nop 1
	v_add_f32_dpp v68, v68, v68 row_mirror row_mask:0xf bank_mask:0xf bound_ctrl:1
	s_nop 1
	v_add_f32_dpp v68, v68, v68 row_bcast:15 row_mask:0xa bank_mask:0xf
	s_nop 1
	v_add_f32_dpp v68, v68, v68 row_bcast:31 row_mask:0xc bank_mask:0xf
	s_nop 1
	v_readlane_b32 s3, v68, 63
	s_nop 3
	v_mov_b32_e32 v68, s3
	v_fmamk_f32 v68, v68, 0x3a800000, v74
	v_rsq_f32_e32 v68, v68
	s_nop 0
	v_pk_mul_f32 v[32:33], v[32:33], v[68:69] op_sel_hi:[1,0]
	v_pk_mul_f32 v[34:35], v[34:35], v[68:69] op_sel_hi:[1,0]
	v_pk_mul_f32 v[36:37], v[36:37], v[68:69] op_sel_hi:[1,0]
	v_pk_mul_f32 v[38:39], v[38:39], v[68:69] op_sel_hi:[1,0]
	v_pk_mul_f32 v[40:41], v[40:41], v[68:69] op_sel_hi:[1,0]
	v_pk_mul_f32 v[42:43], v[42:43], v[68:69] op_sel_hi:[1,0]
	v_pk_mul_f32 v[44:45], v[44:45], v[68:69] op_sel_hi:[1,0]
	v_pk_mul_f32 v[46:47], v[46:47], v[68:69] op_sel_hi:[1,0]
	v_pk_fma_f32 v[32:33], v[50:51], v[32:33], v[78:79]
	v_pk_fma_f32 v[34:35], v[52:53], v[34:35], v[80:81]
	v_pk_fma_f32 v[36:37], v[54:55], v[36:37], v[82:83]
	v_pk_fma_f32 v[38:39], v[56:57], v[38:39], v[84:85]
	v_pk_fma_f32 v[40:41], v[58:59], v[40:41], v[86:87]
	v_pk_fma_f32 v[42:43], v[60:61], v[42:43], v[88:89]
	v_pk_fma_f32 v[44:45], v[62:63], v[44:45], v[90:91]
	v_pk_fma_f32 v[46:47], v[64:65], v[46:47], v[92:93]
	v_cvt_pk_bf16_f32 v32, v32, v33
	v_cvt_pk_bf16_f32 v33, v34, v35
	v_cvt_pk_bf16_f32 v36, v36, v37
	v_cvt_pk_bf16_f32 v37, v38, v39
	v_cvt_pk_bf16_f32 v40, v40, v41
	v_cvt_pk_bf16_f32 v41, v42, v43
	v_cvt_pk_bf16_f32 v44, v44, v45
	v_cvt_pk_bf16_f32 v45, v46, v47
	global_store_dwordx2 v67, v[32:33], s[6:7] offset:0
	global_store_dwordx2 v67, v[36:37], s[6:7] offset:512
	global_store_dwordx2 v67, v[40:41], s[6:7] offset:1024
	global_store_dwordx2 v67, v[44:45], s[6:7] offset:1536
	s_add_u32 s6, s6, 0x800
	s_addc_u32 s7, s7, 0
	s_waitcnt vmcnt(12)
	v_pk_mul_f32 v[70:71], v[0:1], v[0:1]
	v_pk_mul_f32 v[72:73], v[2:3], v[2:3]
	v_pk_fma_f32 v[70:71], v[4:5], v[4:5], v[70:71]
	v_pk_fma_f32 v[72:73], v[6:7], v[6:7], v[72:73]
	v_pk_fma_f32 v[70:71], v[8:9], v[8:9], v[70:71]
	v_pk_fma_f32 v[72:73], v[10:11], v[10:11], v[72:73]
	v_pk_fma_f32 v[70:71], v[12:13], v[12:13], v[70:71]
	v_pk_fma_f32 v[72:73], v[14:15], v[14:15], v[72:73]
	s_nop 0
	v_pk_add_f32 v[70:71], v[70:71], v[72:73]
	s_nop 0
	v_add_f32_e32 v68, v70, v71
	s_nop 1
	v_add_f32_dpp v68, v68, v68 quad_perm:[1,0,3,2] row_mask:0xf bank_mask:0xf bound_ctrl:1
	s_nop 1
	v_add_f32_dpp v68, v68, v68 quad_perm:[2,3,0,1] row_mask:0xf bank_mask:0xf bound_ctrl:1
	s_nop 1
	v_add_f32_dpp v68, v68, v68 row_half_mirror row_mask:0xf bank_mask:0xf bound_ctrl:1
	s_nop 1
	v_add_f32_dpp v68, v68, v68 row_mirror row_mask:0xf bank_mask:0xf bound_ctrl:1
	s_nop 1
	v_add_f32_dpp v68, v68, v68 row_bcast:15 row_mask:0xa bank_mask:0xf
	s_nop 1
	v_add_f32_dpp v68, v68, v68 row_bcast:31 row_mask:0xc bank_mask:0xf
	s_nop 1
	v_readlane_b32 s3, v68, 63
	s_nop 3
	v_mov_b32_e32 v68, s3
	v_fmamk_f32 v68, v68, 0x3a800000, v74
	v_rsq_f32_e32 v68, v68
	s_nop 0
	v_pk_mul_f32 v[0:1], v[0:1], v[68:69] op_sel_hi:[1,0]
	v_pk_mul_f32 v[2:3], v[2:3], v[68:69] op_sel_hi:[1,0]
	v_pk_mul_f32 v[4:5], v[4:5], v[68:69] op_sel_hi:[1,0]
	v_pk_mul_f32 v[6:7], v[6:7], v[68:69] op_sel_hi:[1,0]
	v_pk_mul_f32 v[8:9], v[8:9], v[68:69] op_sel_hi:[1,0]
	v_pk_mul_f32 v[10:11], v[10:11], v[68:69] op_sel_hi:[1,0]
	v_pk_mul_f32 v[12:13], v[12:13], v[68:69] op_sel_hi:[1,0]
	v_pk_mul_f32 v[14:15], v[14:15], v[68:69] op_sel_hi:[1,0]
	v_pk_fma_f32 v[0:1], v[50:51], v[0:1], v[78:79]
	v_pk_fma_f32 v[2:3], v[52:53], v[2:3], v[80:81]
	v_pk_fma_f32 v[4:5], v[54:55], v[4:5], v[82:83]
	v_pk_fma_f32 v[6:7], v[56:57], v[6:7], v[84:85]
	v_pk_fma_f32 v[8:9], v[58:59], v[8:9], v[86:87]
	v_pk_fma_f32 v[10:11], v[60:61], v[10:11], v[88:89]
	v_pk_fma_f32 v[12:13], v[62:63], v[12:13], v[90:91]
	v_pk_fma_f32 v[14:15], v[64:65], v[14:15], v[92:93]
	v_cvt_pk_bf16_f32 v0, v0, v1
	v_cvt_pk_bf16_f32 v1, v2, v3
	v_cvt_pk_bf16_f32 v4, v4, v5
	v_cvt_pk_bf16_f32 v5, v6, v7
	v_cvt_pk_bf16_f32 v8, v8, v9
	v_cvt_pk_bf16_f32 v9, v10, v11
	v_cvt_pk_bf16_f32 v12, v12, v13
	v_cvt_pk_bf16_f32 v13, v14, v15
	global_store_dwordx2 v67, v[0:1], s[6:7] offset:0
	global_store_dwordx2 v67, v[4:5], s[6:7] offset:512
	global_store_dwordx2 v67, v[8:9], s[6:7] offset:1024
	global_store_dwordx2 v67, v[12:13], s[6:7] offset:1536
	s_add_u32 s6, s6, 0x800
	s_addc_u32 s7, s7, 0
	s_waitcnt vmcnt(8)
	v_pk_mul_f32 v[70:71], v[16:17], v[16:17]
	v_pk_mul_f32 v[72:73], v[18:19], v[18:19]
	v_pk_fma_f32 v[70:71], v[20:21], v[20:21], v[70:71]
	v_pk_fma_f32 v[72:73], v[22:23], v[22:23], v[72:73]
	v_pk_fma_f32 v[70:71], v[24:25], v[24:25], v[70:71]
	v_pk_fma_f32 v[72:73], v[26:27], v[26:27], v[72:73]
	v_pk_fma_f32 v[70:71], v[28:29], v[28:29], v[70:71]
	v_pk_fma_f32 v[72:73], v[30:31], v[30:31], v[72:73]
	s_nop 0
	v_pk_add_f32 v[70:71], v[70:71], v[72:73]
	s_nop 0
	v_add_f32_e32 v68, v70, v71
	s_nop 1
	v_add_f32_dpp v68, v68, v68 quad_perm:[1,0,3,2] row_mask:0xf bank_mask:0xf bound_ctrl:1
	s_nop 1
	v_add_f32_dpp v68, v68, v68 quad_perm:[2,3,0,1] row_mask:0xf bank_mask:0xf bound_ctrl:1
	s_nop 1
	v_add_f32_dpp v68, v68, v68 row_half_mirror row_mask:0xf bank_mask:0xf bound_ctrl:1
	s_nop 1
	v_add_f32_dpp v68, v68, v68 row_mirror row_mask:0xf bank_mask:0xf bound_ctrl:1
	s_nop 1
	v_add_f32_dpp v68, v68, v68 row_bcast:15 row_mask:0xa bank_mask:0xf
	s_nop 1
	v_add_f32_dpp v68, v68, v68 row_bcast:31 row_mask:0xc bank_mask:0xf
	s_nop 1
	v_readlane_b32 s3, v68, 63
	s_nop 3
	v_mov_b32_e32 v68, s3
	v_fmamk_f32 v68, v68, 0x3a800000, v74
	v_rsq_f32_e32 v68, v68
	s_nop 0
	v_pk_mul_f32 v[16:17], v[16:17], v[68:69] op_sel_hi:[1,0]
	v_pk_mul_f32 v[18:19], v[18:19], v[68:69] op_sel_hi:[1,0]
	v_pk_mul_f32 v[20:21], v[20:21], v[68:69] op_sel_hi:[1,0]
	v_pk_mul_f32 v[22:23], v[22:23], v[68:69] op_sel_hi:[1,0]
	v_pk_mul_f32 v[24:25], v[24:25], v[68:69] op_sel_hi:[1,0]
	v_pk_mul_f32 v[26:27], v[26:27], v[68:69] op_sel_hi:[1,0]
	v_pk_mul_f32 v[28:29], v[28:29], v[68:69] op_sel_hi:[1,0]
	v_pk_mul_f32 v[30:31], v[30:31], v[68:69] op_sel_hi:[1,0]
	v_pk_fma_f32 v[16:17], v[50:51], v[16:17], v[78:79]
	v_pk_fma_f32 v[18:19], v[52:53], v[18:19], v[80:81]
	v_pk_fma_f32 v[20:21], v[54:55], v[20:21], v[82:83]
	v_pk_fma_f32 v[22:23], v[56:57], v[22:23], v[84:85]
	v_pk_fma_f32 v[24:25], v[58:59], v[24:25], v[86:87]
	v_pk_fma_f32 v[26:27], v[60:61], v[26:27], v[88:89]
	v_pk_fma_f32 v[28:29], v[62:63], v[28:29], v[90:91]
	v_pk_fma_f32 v[30:31], v[64:65], v[30:31], v[92:93]
	v_cvt_pk_bf16_f32 v16, v16, v17
	v_cvt_pk_bf16_f32 v17, v18, v19
	v_cvt_pk_bf16_f32 v20, v20, v21
	v_cvt_pk_bf16_f32 v21, v22, v23
	v_cvt_pk_bf16_f32 v24, v24, v25
	v_cvt_pk_bf16_f32 v25, v26, v27
	v_cvt_pk_bf16_f32 v28, v28, v29
	v_cvt_pk_bf16_f32 v29, v30, v31
	global_store_dwordx2 v67, v[16:17], s[6:7] offset:0
	global_store_dwordx2 v67, v[20:21], s[6:7] offset:512
	global_store_dwordx2 v67, v[24:25], s[6:7] offset:1024
	global_store_dwordx2 v67, v[28:29], s[6:7] offset:1536
	s_add_u32 s6, s6, 0x800
	s_addc_u32 s7, s7, 0
	s_branch .LBB0_710
.Lnorm_orig_1:
	s_load_dwordx2 s[4:5], s[2:3], 0x0
	v_ashrrev_i32_e32 v49, 31, v48
	v_lshlrev_b32_e32 v2, 4, v8
	v_lshlrev_b64 v[10:11], 12, v[48:49]
	v_and_b32_e32 v128, 0x3f0, v2
	s_waitcnt lgkmcnt(0)
	v_lshl_add_u64 v[0:1], s[4:5], 0, v[10:11]
	v_lshl_add_u64 v[0:1], v[0:1], 0, v[128:129]
	s_load_dwordx2 s[6:7], s[2:3], 0x20
	s_nop 0
	s_load_dwordx2 s[2:3], s[2:3], 0xe0
	global_load_dwordx4 v[20:23], v[0:1], off
	global_load_dwordx4 v[12:15], v[0:1], off offset:1024
	global_load_dwordx4 v[4:7], v[0:1], off offset:2048
	s_nop 0
	global_load_dwordx4 v[0:3], v[0:1], off offset:3072
	v_cmp_lt_i32_e32 vcc, v171, v165
	v_and_b32_e32 v18, 63, v8
	s_waitcnt lgkmcnt(0)
	v_lshl_add_u64 v[50:51], s[6:7], 0, v[128:129]
	v_cndmask_b32_e32 v9, v164, v171, vcc
	v_cmp_lt_i32_e32 vcc, v170, v165
	v_lshlrev_b32_e32 v77, 2, v9
	v_lshl_add_u64 v[16:17], s[2:3], 0, v[128:129]
	v_cndmask_b32_e32 v9, v164, v170, vcc
	v_cmp_lt_i32_e32 vcc, v169, v165
	v_lshlrev_b32_e32 v78, 2, v9
	s_mov_b64 s[6:7], 0x781000
	v_cndmask_b32_e32 v9, v164, v169, vcc
	v_cmp_lt_i32_e32 vcc, v168, v165
	v_lshlrev_b32_e32 v79, 2, v9
	v_lshl_add_u64 v[52:53], v[16:17], 0, s[6:7]
	v_cndmask_b32_e32 v9, v164, v168, vcc
	v_cmp_lt_i32_e32 vcc, v167, v165
	s_mov_b64 s[6:7], 0x780000
	v_lshlrev_b32_e32 v80, 2, v9
	v_cndmask_b32_e32 v9, v164, v167, vcc
	v_cmp_lt_i32_e32 vcc, v166, v165
	v_lshl_add_u64 v[54:55], v[16:17], 0, s[6:7]
	v_lshlrev_b64 v[16:17], 11, v[48:49]
	v_lshlrev_b32_e32 v81, 2, v9
	v_cndmask_b32_e32 v9, v164, v166, vcc
	v_lshl_or_b32 v16, v18, 3, v16
	v_lshlrev_b32_e32 v82, 2, v9
	v_lshl_add_u64 v[8:9], s[2:3], 0, v[16:17]
	s_mov_b64 s[2:3], 0x1c00000
	v_lshl_or_b32 v10, v18, 4, v10
	v_lshl_add_u64 v[56:57], v[8:9], 0, s[2:3]
	v_lshl_add_u64 v[8:9], s[4:5], 0, v[10:11]
	s_mov_b64 s[2:3], 0x1c00
	v_mov_b32_e32 v60, 0
	v_mov_b32_e32 v83, -1
	v_lshl_add_u64 v[58:59], v[8:9], 0, s[2:3]
	s_mov_b64 s[4:5], 0
	v_mov_b32_e32 v61, v60
	v_mov_b32_e32 v62, v60
	v_mov_b32_e32 v63, v60
	v_mov_b32_e32 v64, v60
	v_mov_b32_e32 v65, v60
	v_mov_b32_e32 v66, v60
	v_mov_b32_e32 v67, v60
	v_mov_b32_e32 v68, v60
	v_mov_b32_e32 v69, v60
	v_mov_b32_e32 v70, v60
	v_mov_b32_e32 v71, v60
	v_mov_b32_e32 v72, v60
	v_mov_b32_e32 v73, v60
	v_mov_b32_e32 v74, v60
	v_mov_b32_e32 v75, v60
	s_branch .LBB0_706

.LBB0_1014:
	s_or_b64 exec, exec, s[4:5]
	v_readlane_b32 s4, v255, 23
	v_readlane_b32 s5, v255, 24
	s_andn2_b64 vcc, exec, s[4:5]
	s_cbranch_vccnz .LBB0_1023
	v_readlane_b32 s4, v254, 2
	v_mbcnt_lo_u32_b32 v8, -1, 0
	v_mbcnt_hi_u32_b32 v8, -1, v8
	s_nop 1
	v_lshl_add_u32 v0, s4, 6, v8
	v_ashrrev_i32_e32 v0, 6, v0
	v_readlane_b32 s4, v254, 9
	s_nop 1
	v_add_u32_e32 v0, s4, v0
	v_readlane_b32 s4, v255, 12
	s_nop 1
	v_mul_lo_u32 v48, v0, s4
	v_add_u32_e32 v0, s4, v48
	v_min_i32_e32 v76, 0x4000, v0
	v_cmp_lt_i32_e32 vcc, v48, v76
	s_and_saveexec_b64 s[4:5], vcc
	s_cbranch_execz .LBB0_1022
	s_cmp_lg_u32 s80, 0x100
	s_cbranch_scc1 .Lnorm_orig_2
	v_readlane_b32 s0, v254, 0
	v_readlane_b32 s1, v254, 1
	v_readfirstlane_b32 s100, v48
	s_nop 3
	s_load_dwordx2 s[2:3], s[0:1], 0x0
	s_load_dwordx2 s[98:99], s[0:1], 0x20
	s_load_dwordx2 s[6:7], s[0:1], 0xe0
	v_mbcnt_lo_u32_b32 v66, -1, 0
	v_mbcnt_hi_u32_b32 v66, -1, v66
	v_lshlrev_b32_e32 v67, 3, v66
	v_lshlrev_b32_e32 v66, 4, v66
	v_mov_b32_e32 v74, 0x358637bd
	s_waitcnt lgkmcnt(0)
	s_mov_b32 s0, s100
	s_add_u32 s1, s0, 16384
	s_lshl_b32 s1, s1, 12
	s_add_u32 s2, s2, s1
	s_addc_u32 s3, s3, 0
	global_load_dwordx4 v[50:53], v66, s[98:99] offset:0
	global_load_dwordx4 v[54:57], v66, s[98:99] offset:1024
	global_load_dwordx4 v[58:61], v66, s[98:99] offset:2048
	global_load_dwordx4 v[62:65], v66, s[98:99] offset:3072
	s_add_u32 s1, s0, 16384
	s_lshr_b32 s1, s1, 12
	s_mul_i32 s1, s1, 0x6000
	s_add_u32 s100, s6, s1
	s_addc_u32 s101, s7, 0
	s_add_u32 s100, s100, 0x780000
	s_addc_u32 s101, s101, 0
	s_add_u32 s98, s100, 4096
	s_addc_u32 s99, s101, 0
	global_load_dwordx4 v[32:35], v66, s[98:99] offset:0
	global_load_dwordx4 v[36:39], v66, s[98:99] offset:1024
	global_load_dwordx4 v[40:43], v66, s[98:99] offset:2048
	global_load_dwordx4 v[44:47], v66, s[98:99] offset:3072
	s_add_u32 s100, s100, 0
	s_addc_u32 s101, s101, 0
	global_load_dwordx4 v[78:81], v66, s[100:101] offset:0
	global_load_dwordx4 v[82:85], v66, s[100:101] offset:1024
	global_load_dwordx4 v[86:89], v66, s[100:101] offset:2048
	global_load_dwordx4 v[90:93], v66, s[100:101] offset:3072
	s_add_u32 s6, s6, 0x1c00000
	s_addc_u32 s7, s7, 0
	s_lshl_b32 s1, s0, 11
	s_add_u32 s6, s6, s1
	s_addc_u32 s7, s7, 0
	global_load_dwordx4 v[0:3], v66, s[2:3] offset:0
	global_load_dwordx4 v[4:7], v66, s[2:3] offset:1024
	global_load_dwordx4 v[8:11], v66, s[2:3] offset:2048
	global_load_dwordx4 v[12:15], v66, s[2:3] offset:3072
	s_add_u32 s2, s2, 0x1000
	s_addc_u32 s3, s3, 0
	global_load_dwordx4 v[16:19], v66, s[2:3] offset:0
	global_load_dwordx4 v[20:23], v66, s[2:3] offset:1024
	global_load_dwordx4 v[24:27], v66, s[2:3] offset:2048
	global_load_dwordx4 v[28:31], v66, s[2:3] offset:3072
	s_add_u32 s2, s2, 0x1000
	s_addc_u32 s3, s3, 0
	s_waitcnt vmcnt(8)
	v_pk_add_f32 v[32:33], v[32:33], 1.0 op_sel_hi:[1,0]
	v_pk_add_f32 v[34:35], v[34:35], 1.0 op_sel_hi:[1,0]
	v_pk_add_f32 v[36:37], v[36:37], 1.0 op_sel_hi:[1,0]
	v_pk_add_f32 v[38:39], v[38:39], 1.0 op_sel_hi:[1,0]
	v_pk_add_f32 v[40:41], v[40:41], 1.0 op_sel_hi:[1,0]
	v_pk_add_f32 v[42:43], v[42:43], 1.0 op_sel_hi:[1,0]
	v_pk_add_f32 v[44:45], v[44:45], 1.0 op_sel_hi:[1,0]
	v_pk_add_f32 v[46:47], v[46:47], 1.0 op_sel_hi:[1,0]
	v_pk_mul_f32 v[50:51], v[50:51], v[32:33]
	v_pk_mul_f32 v[52:53], v[52:53], v[34:35]
	v_pk_mul_f32 v[54:55], v[54:55], v[36:37]
	v_pk_mul_f32 v[56:57], v[56:57], v[38:39]
	v_pk_mul_f32 v[58:59], v[58:59], v[40:41]
	v_pk_mul_f32 v[60:61], v[60:61], v[42:43]
	v_pk_mul_f32 v[62:63], v[62:63], v[44:45]
	v_pk_mul_f32 v[64:65], v[64:65], v[46:47]
	global_load_dwordx4 v[32:35], v66, s[2:3] offset:0
	global_load_dwordx4 v[36:39], v66, s[2:3] offset:1024
	global_load_dwordx4 v[40:43], v66, s[2:3] offset:2048
	global_load_dwordx4 v[44:47], v66, s[2:3] offset:3072
	s_add_u32 s2, s2, 0x1000
	s_addc_u32 s3, s3, 0
	s_waitcnt vmcnt(8)
	v_pk_mul_f32 v[70:71], v[0:1], v[0:1]
	v_pk_mul_f32 v[72:73], v[2:3], v[2:3]
	v_pk_fma_f32 v[70:71], v[4:5], v[4:5], v[70:71]
	v_pk_fma_f32 v[72:73], v[6:7], v[6:7], v[72:73]
	v_pk_fma_f32 v[70:71], v[8:9], v[8:9], v[70:71]
	v_pk_fma_f32 v[72:73], v[10:11], v[10:11], v[72:73]
	v_pk_fma_f32 v[70:71], v[12:13], v[12:13], v[70:71]
	v_pk_fma_f32 v[72:73], v[14:15], v[14:15], v[72:73]
	s_nop 0
	v_pk_add_f32 v[70:71], v[70:71], v[72:73]
	s_nop 0
	v_add_f32_e32 v68, v70, v71
	s_nop 1
	v_add_f32_dpp v68, v68, v68 quad_perm:[1,0,3,2] row_mask:0xf bank_mask:0xf bound_ctrl:1
	s_nop 1
	v_add_f32_dpp v68, v68, v68 quad_perm:[2,3,0,1] row_mask:0xf bank_mask:0xf bound_ctrl:1
	s_nop 1
	v_add_f32_dpp v68, v68, v68 row_half_mirror row_mask:0xf bank_mask:0xf bound_ctrl:1
	s_nop 1
	v_add_f32_dpp v68, v68, v68 row_mirror row_mask:0xf bank_mask:0xf bound_ctrl:1
	s_nop 1
	v_add_f32_dpp v68, v68, v68 row_bcast:15 row_mask:0xa bank_mask:0xf
	s_nop 1
	v_add_f32_dpp v68, v68, v68 row_bcast:31 row_mask:0xc bank_mask:0xf
	s_nop 1
	v_readlane_b32 s1, v68, 63
	s_nop 3
	v_mov_b32_e32 v68, s1
	v_fmamk_f32 v68, v68, 0x3a800000, v74
	v_rsq_f32_e32 v68, v68
	s_nop 0
	v_pk_mul_f32 v[0:1], v[0:1], v[68:69] op_sel_hi:[1,0]
	v_pk_mul_f32 v[2:3], v[2:3], v[68:69] op_sel_hi:[1,0]
	v_pk_mul_f32 v[4:5], v[4:5], v[68:69] op_sel_hi:[1,0]
	v_pk_mul_f32 v[6:7], v[6:7], v[68:69] op_sel_hi:[1,0]
	v_pk_mul_f32 v[8:9], v[8:9], v[68:69] op_sel_hi:[1,0]
	v_pk_mul_f32 v[10:11], v[10:11], v[68:69] op_sel_hi:[1,0]
	v_pk_mul_f32 v[12:13], v[12:13], v[68:69] op_sel_hi:[1,0]
	v_pk_mul_f32 v[14:15], v[14:15], v[68:69] op_sel_hi:[1,0]
	v_pk_fma_f32 v[0:1], v[50:51], v[0:1], v[78:79]
	v_pk_fma_f32 v[2:3], v[52:53], v[2:3], v[80:81]
	v_pk_fma_f32 v[4:5], v[54:55], v[4:5], v[82:83]
	v_pk_fma_f32 v[6:7], v[56:57], v[6:7], v[84:85]
	v_pk_fma_f32 v[8:9], v[58:59], v[8:9], v[86:87]
	v_pk_fma_f32 v[10:11], v[60:61], v[10:11], v[88:89]
	v_pk_fma_f32 v[12:13], v[62:63], v[12:13], v[90:91]
	v_pk_fma_f32 v[14:15], v[64:65], v[14:15], v[92:93]
	v_cvt_pk_bf16_f32 v0, v0, v1
	v_cvt_pk_bf16_f32 v1, v2, v3
	v_cvt_pk_bf16_f32 v4, v4, v5
	v_cvt_pk_bf16_f32 v5, v6, v7
	v_cvt_pk_bf16_f32 v8, v8, v9
	v_cvt_pk_bf16_f32 v9, v10, v11
	v_cvt_pk_bf16_f32 v12, v12, v13
	v_cvt_pk_bf16_f32 v13, v14, v15
	global_store_dwordx2 v67, v[0:1], s[6:7] offset:0
	global_store_dwordx2 v67, v[4:5], s[6:7] offset:512
	global_store_dwordx2 v67, v[8:9], s[6:7] offset:1024
	global_store_dwordx2 v67, v[12:13], s[6:7] offset:1536
	s_add_u32 s6, s6, 0x800
	s_addc_u32 s7, s7, 0
	global_load_dwordx4 v[0:3], v66, s[2:3] offset:0
	global_load_dwordx4 v[4:7], v66, s[2:3] offset:1024
	global_load_dwordx4 v[8:11], v66, s[2:3] offset:2048
	global_load_dwordx4 v[12:15], v66, s[2:3] offset:3072
	s_add_u32 s2, s2, 0x1000
	s_addc_u32 s3, s3, 0
	s_waitcnt vmcnt(12)
	v_pk_mul_f32 v[70:71], v[16:17], v[16:17]
	v_pk_mul_f32 v[72:73], v[18:19], v[18:19]
	v_pk_fma_f32 v[70:71], v[20:21], v[20:21], v[70:71]
	v_pk_fma_f32 v[72:73], v[22:23], v[22:23], v[72:73]
	v_pk_fma_f32 v[70:71], v[24:25], v[24:25], v[70:71]
	v_pk_fma_f32 v[72:73], v[26:27], v[26:27], v[72:73]
	v_pk_fma_f32 v[70:71], v[28:29], v[28:29], v[70:71]
	v_pk_fma_f32 v[72:73], v[30:31], v[30:31], v[72:73]
	s_nop 0
	v_pk_add_f32 v[70:71], v[70:71], v[72:73]
	s_nop 0
	v_add_f32_e32 v68, v70, v71
	s_nop 1
	v_add_f32_dpp v68, v68, v68 quad_perm:[1,0,3,2] row_mask:0xf bank_mask:0xf bound_ctrl:1
	s_nop 1
	v_add_f32_dpp v68, v68, v68 quad_perm:[2,3,0,1] row_mask:0xf bank_mask:0xf bound_ctrl:1
	s_nop 1
	v_add_f32_dpp v68, v68, v68 row_half_mirror row_mask:0xf bank_mask:0xf bound_ctrl:1
	s_nop 1
	v_add_f32_dpp v68, v68, v68 row_mirror row_mask:0xf bank_mask:0xf bound_ctrl:1
	s_nop 1
	v_add_f32_dpp v68, v68, v68 row_bcast:15 row_mask:0xa bank_mask:0xf
	s_nop 1
	v_add_f32_dpp v68, v68, v68 row_bcast:31 row_mask:0xc bank_mask:0xf
	s_nop 1
	v_readlane_b32 s1, v68, 63
	s_nop 3
	v_mov_b32_e32 v68, s1
	v_fmamk_f32 v68, v68, 0x3a800000, v74
	v_rsq_f32_e32 v68, v68
	s_nop 0
	v_pk_mul_f32 v[16:17], v[16:17], v[68:69] op_sel_hi:[1,0]
	v_pk_mul_f32 v[18:19], v[18:19], v[68:69] op_sel_hi:[1,0]
	v_pk_mul_f32 v[20:21], v[20:21], v[68:69] op_sel_hi:[1,0]
	v_pk_mul_f32 v[22:23], v[22:23], v[68:69] op_sel_hi:[1,0]
	v_pk_mul_f32 v[24:25], v[24:25], v[68:69] op_sel_hi:[1,0]
	v_pk_mul_f32 v[26:27], v[26:27], v[68:69] op_sel_hi:[1,0]
	v_pk_mul_f32 v[28:29], v[28:29], v[68:69] op_sel_hi:[1,0]
	v_pk_mul_f32 v[30:31], v[30:31], v[68:69] op_sel_hi:[1,0]
	v_pk_fma_f32 v[16:17], v[50:51], v[16:17], v[78:79]
	v_pk_fma_f32 v[18:19], v[52:53], v[18:19], v[80:81]
	v_pk_fma_f32 v[20:21], v[54:55], v[20:21], v[82:83]
	v_pk_fma_f32 v[22:23], v[56:57], v[22:23], v[84:85]
	v_pk_fma_f32 v[24:25], v[58:59], v[24:25], v[86:87]
	v_pk_fma_f32 v[26:27], v[60:61], v[26:27], v[88:89]
	v_pk_fma_f32 v[28:29], v[62:63], v[28:29], v[90:91]
	v_pk_fma_f32 v[30:31], v[64:65], v[30:31], v[92:93]
	v_cvt_pk_bf16_f32 v16, v16, v17
	v_cvt_pk_bf16_f32 v17, v18, v19
	v_cvt_pk_bf16_f32 v20, v20, v21
	v_cvt_pk_bf16_f32 v21, v22, v23
	v_cvt_pk_bf16_f32 v24, v24, v25
	v_cvt_pk_bf16_f32 v25, v26, v27
	v_cvt_pk_bf16_f32 v28, v28, v29
	v_cvt_pk_bf16_f32 v29, v30, v31
	global_store_dwordx2 v67, v[16:17], s[6:7] offset:0
	global_store_dwordx2 v67, v[20:21], s[6:7] offset:512
	global_store_dwordx2 v67, v[24:25], s[6:7] offset:1024
	global_store_dwordx2 v67, v[28:29], s[6:7] offset:1536
	s_add_u32 s6, s6, 0x800
	s_addc_u32 s7, s7, 0
	global_load_dwordx4 v[16:19], v66, s[2:3] offset:0
	global_load_dwordx4 v[20:23], v66, s[2:3] offset:1024
	global_load_dwordx4 v[24:27], v66, s[2:3] offset:2048
	global_load_dwordx4 v[28:31], v66, s[2:3] offset:3072
	s_add_u32 s2, s2, 0x1000
	s_addc_u32 s3, s3, 0
	s_waitcnt vmcnt(16)
	v_pk_mul_f32 v[70:71], v[32:33], v[32:33]
	v_pk_mul_f32 v[72:73], v[34:35], v[34:35]
	v_pk_fma_f32 v[70:71], v[36:37], v[36:37], v[70:71]
	v_pk_fma_f32 v[72:73], v[38:39], v[38:39], v[72:73]
	v_pk_fma_f32 v[70:71], v[40:41], v[40:41], v[70:71]
	v_pk_fma_f32 v[72:73], v[42:43], v[42:43], v[72:73]
	v_pk_fma_f32 v[70:71], v[44:45], v[44:45], v[70:71]
	v_pk_fma_f32 v[72:73], v[46:47], v[46:47], v[72:73]
	s_nop 0
	v_pk_add_f32 v[70:71], v[70:71], v[72:73]
	s_nop 0
	v_add_f32_e32 v68, v70, v71
	s_nop 1
	v_add_f32_dpp v68, v68, v68 quad_perm:[1,0,3,2] row_mask:0xf bank_mask:0xf bound_ctrl:1
	s_nop 1
	v_add_f32_dpp v68, v68, v68 quad_perm:[2,3,0,1] row_mask:0xf bank_mask:0xf bound_ctrl:1
	s_nop 1
	v_add_f32_dpp v68, v68, v68 row_half_mirror row_mask:0xf bank_mask:0xf bound_ctrl:1
	s_nop 1
	v_add_f32_dpp v68, v68, v68 row_mirror row_mask:0xf bank_mask:0xf bound_ctrl:1
	s_nop 1
	v_add_f32_dpp v68, v68, v68 row_bcast:15 row_mask:0xa bank_mask:0xf
	s_nop 1
	v_add_f32_dpp v68, v68, v68 row_bcast:31 row_mask:0xc bank_mask:0xf
	s_nop 1
	v_readlane_b32 s1, v68, 63
	s_nop 3
	v_mov_b32_e32 v68, s1
	v_fmamk_f32 v68, v68, 0x3a800000, v74
	v_rsq_f32_e32 v68, v68
	s_nop 0
	v_pk_mul_f32 v[32:33], v[32:33], v[68:69] op_sel_hi:[1,0]
	v_pk_mul_f32 v[34:35], v[34:35], v[68:69] op_sel_hi:[1,0]
	v_pk_mul_f32 v[36:37], v[36:37], v[68:69] op_sel_hi:[1,0]
	v_pk_mul_f32 v[38:39], v[38:39], v[68:69] op_sel_hi:[1,0]
	v_pk_mul_f32 v[40:41], v[40:41], v[68:69] op_sel_hi:[1,0]
	v_pk_mul_f32 v[42:43], v[42:43], v[68:69] op_sel_hi:[1,0]
	v_pk_mul_f32 v[44:45], v[44:45], v[68:69] op_sel_hi:[1,0]
	v_pk_mul_f32 v[46:47], v[46:47], v[68:69] op_sel_hi:[1,0]
	v_pk_fma_f32 v[32:33], v[50:51], v[32:33], v[78:79]
	v_pk_fma_f32 v[34:35], v[52:53], v[34:35], v[80:81]
	v_pk_fma_f32 v[36:37], v[54:55], v[36:37], v[82:83]
	v_pk_fma_f32 v[38:39], v[56:57], v[38:39], v[84:85]
	v_pk_fma_f32 v[40:41], v[58:59], v[40:41], v[86:87]
	v_pk_fma_f32 v[42:43], v[60:61], v[42:43], v[88:89]
	v_pk_fma_f32 v[44:45], v[62:63], v[44:45], v[90:91]
	v_pk_fma_f32 v[46:47], v[64:65], v[46:47], v[92:93]
	v_cvt_pk_bf16_f32 v32, v32, v33
	v_cvt_pk_bf16_f32 v33, v34, v35
	v_cvt_pk_bf16_f32 v36, v36, v37
	v_cvt_pk_bf16_f32 v37, v38, v39
	v_cvt_pk_bf16_f32 v40, v40, v41
	v_cvt_pk_bf16_f32 v41, v42, v43
	v_cvt_pk_bf16_f32 v44, v44, v45
	v_cvt_pk_bf16_f32 v45, v46, v47
	global_store_dwordx2 v67, v[32:33], s[6:7] offset:0
	global_store_dwordx2 v67, v[36:37], s[6:7] offset:512
	global_store_dwordx2 v67, v[40:41], s[6:7] offset:1024
	global_store_dwordx2 v67, v[44:45], s[6:7] offset:1536
	s_add_u32 s6, s6, 0x800
	s_addc_u32 s7, s7, 0
	global_load_dwordx4 v[32:35], v66, s[2:3] offset:0
	global_load_dwordx4 v[36:39], v66, s[2:3] offset:1024
	global_load_dwordx4 v[40:43], v66, s[2:3] offset:2048
	global_load_dwordx4 v[44:47], v66, s[2:3] offset:3072
	s_add_u32 s2, s2, 0x1000
	s_addc_u32 s3, s3, 0
	s_waitcnt vmcnt(16)
	v_pk_mul_f32 v[70:71], v[0:1], v[0:1]
	v_pk_mul_f32 v[72:73], v[2:3], v[2:3]
	v_pk_fma_f32 v[70:71], v[4:5], v[4:5], v[70:71]
	v_pk_fma_f32 v[72:73], v[6:7], v[6:7], v[72:73]
	v_pk_fma_f32 v[70:71], v[8:9], v[8:9], v[70:71]
	v_pk_fma_f32 v[72:73], v[10:11], v[10:11], v[72:73]
	v_pk_fma_f32 v[70:71], v[12:13], v[12:13], v[70:71]
	v_pk_fma_f32 v[72:73], v[14:15], v[14:15], v[72:73]
	s_nop 0
	v_pk_add_f32 v[70:71], v[70:71], v[72:73]
	s_nop 0
	v_add_f32_e32 v68, v70, v71
	s_nop 1
	v_add_f32_dpp v68, v68, v68 quad_perm:[1,0,3,2] row_mask:0xf bank_mask:0xf bound_ctrl:1
	s_nop 1
	v_add_f32_dpp v68, v68, v68 quad_perm:[2,3,0,1] row_mask:0xf bank_mask:0xf bound_ctrl:1
	s_nop 1
	v_add_f32_dpp v68, v68, v68 row_half_mirror row_mask:0xf bank_mask:0xf bound_ctrl:1
	s_nop 1
	v_add_f32_dpp v68, v68, v68 row_mirror row_mask:0xf bank_mask:0xf bound_ctrl:1
	s_nop 1
	v_add_f32_dpp v68, v68, v68 row_bcast:15 row_mask:0xa bank_mask:0xf
	s_nop 1
	v_add_f32_dpp v68, v68, v68 row_bcast:31 row_mask:0xc bank_mask:0xf
	s_nop 1
	v_readlane_b32 s1, v68, 63
	s_nop 3
	v_mov_b32_e32 v68, s1
	v_fmamk_f32 v68, v68, 0x3a800000, v74
	v_rsq_f32_e32 v68, v68
	s_nop 0
	v_pk_mul_f32 v[0:1], v[0:1], v[68:69] op_sel_hi:[1,0]
	v_pk_mul_f32 v[2:3], v[2:3], v[68:69] op_sel_hi:[1,0]
	v_pk_mul_f32 v[4:5], v[4:5], v[68:69] op_sel_hi:[1,0]
	v_pk_mul_f32 v[6:7], v[6:7], v[68:69] op_sel_hi:[1,0]
	v_pk_mul_f32 v[8:9], v[8:9], v[68:69] op_sel_hi:[1,0]
	v_pk_mul_f32 v[10:11], v[10:11], v[68:69] op_sel_hi:[1,0]
	v_pk_mul_f32 v[12:13], v[12:13], v[68:69] op_sel_hi:[1,0]
	v_pk_mul_f32 v[14:15], v[14:15], v[68:69] op_sel_hi:[1,0]
	v_pk_fma_f32 v[0:1], v[50:51], v[0:1], v[78:79]
	v_pk_fma_f32 v[2:3], v[52:53], v[2:3], v[80:81]
	v_pk_fma_f32 v[4:5], v[54:55], v[4:5], v[82:83]
	v_pk_fma_f32 v[6:7], v[56:57], v[6:7], v[84:85]
	v_pk_fma_f32 v[8:9], v[58:59], v[8:9], v[86:87]
	v_pk_fma_f32 v[10:11], v[60:61], v[10:11], v[88:89]
	v_pk_fma_f32 v[12:13], v[62:63], v[12:13], v[90:91]
	v_pk_fma_f32 v[14:15], v[64:65], v[14:15], v[92:93]
	v_cvt_pk_bf16_f32 v0, v0, v1
	v_cvt_pk_bf16_f32 v1, v2, v3
	v_cvt_pk_bf16_f32 v4, v4, v5
	v_cvt_pk_bf16_f32 v5, v6, v7
	v_cvt_pk_bf16_f32 v8, v8, v9
	v_cvt_pk_bf16_f32 v9, v10, v11
	v_cvt_pk_bf16_f32 v12, v12, v13
	v_cvt_pk_bf16_f32 v13, v14, v15
	global_store_dwordx2 v67, v[0:1], s[6:7] offset:0
	global_store_dwordx2 v67, v[4:5], s[6:7] offset:512
	global_store_dwordx2 v67, v[8:9], s[6:7] offset:1024
	global_store_dwordx2 v67, v[12:13], s[6:7] offset:1536
	s_add_u32 s6, s6, 0x800
	s_addc_u32 s7, s7, 0
	global_load_dwordx4 v[0:3], v66, s[2:3] offset:0
	global_load_dwordx4 v[4:7], v66, s[2:3] offset:1024
	global_load_dwordx4 v[8:11], v66, s[2:3] offset:2048
	global_load_dwordx4 v[12:15], v66, s[2:3] offset:3072
	s_add_u32 s2, s2, 0x1000
	s_addc_u32 s3, s3, 0
	s_waitcnt vmcnt(16)
	v_pk_mul_f32 v[70:71], v[16:17], v[16:17]
	v_pk_mul_f32 v[72:73], v[18:19], v[18:19]
	v_pk_fma_f32 v[70:71], v[20:21], v[20:21], v[70:71]
	v_pk_fma_f32 v[72:73], v[22:23], v[22:23], v[72:73]
	v_pk_fma_f32 v[70:71], v[24:25], v[24:25], v[70:71]
	v_pk_fma_f32 v[72:73], v[26:27], v[26:27], v[72:73]
	v_pk_fma_f32 v[70:71], v[28:29], v[28:29], v[70:71]
	v_pk_fma_f32 v[72:73], v[30:31], v[30:31], v[72:73]
	s_nop 0
	v_pk_add_f32 v[70:71], v[70:71], v[72:73]
	s_nop 0
	v_add_f32_e32 v68, v70, v71
	s_nop 1
	v_add_f32_dpp v68, v68, v68 quad_perm:[1,0,3,2] row_mask:0xf bank_mask:0xf bound_ctrl:1
	s_nop 1
	v_add_f32_dpp v68, v68, v68 quad_perm:[2,3,0,1] row_mask:0xf bank_mask:0xf bound_ctrl:1
	s_nop 1
	v_add_f32_dpp v68, v68, v68 row_half_mirror row_mask:0xf bank_mask:0xf bound_ctrl:1
	s_nop 1
	v_add_f32_dpp v68, v68, v68 row_mirror row_mask:0xf bank_mask:0xf bound_ctrl:1
	s_nop 1
	v_add_f32_dpp v68, v68, v68 row_bcast:15 row_mask:0xa bank_mask:0xf
	s_nop 1
	v_add_f32_dpp v68, v68, v68 row_bcast:31 row_mask:0xc bank_mask:0xf
	s_nop 1
	v_readlane_b32 s1, v68, 63
	s_nop 3
	v_mov_b32_e32 v68, s1
	v_fmamk_f32 v68, v68, 0x3a800000, v74
	v_rsq_f32_e32 v68, v68
	s_nop 0
	v_pk_mul_f32 v[16:17], v[16:17], v[68:69] op_sel_hi:[1,0]
	v_pk_mul_f32 v[18:19], v[18:19], v[68:69] op_sel_hi:[1,0]
	v_pk_mul_f32 v[20:21], v[20:21], v[68:69] op_sel_hi:[1,0]
	v_pk_mul_f32 v[22:23], v[22:23], v[68:69] op_sel_hi:[1,0]
	v_pk_mul_f32 v[24:25], v[24:25], v[68:69] op_sel_hi:[1,0]
	v_pk_mul_f32 v[26:27], v[26:27], v[68:69] op_sel_hi:[1,0]
	v_pk_mul_f32 v[28:29], v[28:29], v[68:69] op_sel_hi:[1,0]
	v_pk_mul_f32 v[30:31], v[30:31], v[68:69] op_sel_hi:[1,0]
	v_pk_fma_f32 v[16:17], v[50:51], v[16:17], v[78:79]
	v_pk_fma_f32 v[18:19], v[52:53], v[18:19], v[80:81]
	v_pk_fma_f32 v[20:21], v[54:55], v[20:21], v[82:83]
	v_pk_fma_f32 v[22:23], v[56:57], v[22:23], v[84:85]
	v_pk_fma_f32 v[24:25], v[58:59], v[24:25], v[86:87]
	v_pk_fma_f32 v[26:27], v[60:61], v[26:27], v[88:89]
	v_pk_fma_f32 v[28:29], v[62:63], v[28:29], v[90:91]
	v_pk_fma_f32 v[30:31], v[64:65], v[30:31], v[92:93]
	v_cvt_pk_bf16_f32 v16, v16, v17
	v_cvt_pk_bf16_f32 v17, v18, v19
	v_cvt_pk_bf16_f32 v20, v20, v21
	v_cvt_pk_bf16_f32 v21, v22, v23
	v_cvt_pk_bf16_f32 v24, v24, v25
	v_cvt_pk_bf16_f32 v25, v26, v27
	v_cvt_pk_bf16_f32 v28, v28, v29
	v_cvt_pk_bf16_f32 v29, v30, v31
	global_store_dwordx2 v67, v[16:17], s[6:7] offset:0
	global_store_dwordx2 v67, v[20:21], s[6:7] offset:512
	global_store_dwordx2 v67, v[24:25], s[6:7] offset:1024
	global_store_dwordx2 v67, v[28:29], s[6:7] offset:1536
	s_add_u32 s6, s6, 0x800
	s_addc_u32 s7, s7, 0
	global_load_dwordx4 v[16:19], v66, s[2:3] offset:0
	global_load_dwordx4 v[20:23], v66, s[2:3] offset:1024
	global_load_dwordx4 v[24:27], v66, s[2:3] offset:2048
	global_load_dwordx4 v[28:31], v66, s[2:3] offset:3072
	s_add_u32 s2, s2, 0x1000
	s_addc_u32 s3, s3, 0
	s_waitcnt vmcnt(16)
	v_pk_mul_f32 v[70:71], v[32:33], v[32:33]
	v_pk_mul_f32 v[72:73], v[34:35], v[34:35]
	v_pk_fma_f32 v[70:71], v[36:37], v[36:37], v[70:71]
	v_pk_fma_f32 v[72:73], v[38:39], v[38:39], v[72:73]
	v_pk_fma_f32 v[70:71], v[40:41], v[40:41], v[70:71]
	v_pk_fma_f32 v[72:73], v[42:43], v[42:43], v[72:73]
	v_pk_fma_f32 v[70:71], v[44:45], v[44:45], v[70:71]
	v_pk_fma_f32 v[72:73], v[46:47], v[46:47], v[72:73]
	s_nop 0
	v_pk_add_f32 v[70:71], v[70:71], v[72:73]
	s_nop 0
	v_add_f32_e32 v68, v70, v71
	s_nop 1
	v_add_f32_dpp v68, v68, v68 quad_perm:[1,0,3,2] row_mask:0xf bank_mask:0xf bound_ctrl:1
	s_nop 1
	v_add_f32_dpp v68, v68, v68 quad_perm:[2,3,0,1] row_mask:0xf bank_mask:0xf bound_ctrl:1
	s_nop 1
	v_add_f32_dpp v68, v68, v68 row_half_mirror row_mask:0xf bank_mask:0xf bound_ctrl:1
	s_nop 1
	v_add_f32_dpp v68, v68, v68 row_mirror row_mask:0xf bank_mask:0xf bound_ctrl:1
	s_nop 1
	v_add_f32_dpp v68, v68, v68 row_bcast:15 row_mask:0xa bank_mask:0xf
	s_nop 1
	v_add_f32_dpp v68, v68, v68 row_bcast:31 row_mask:0xc bank_mask:0xf
	s_nop 1
	v_readlane_b32 s1, v68, 63
	s_nop 3
	v_mov_b32_e32 v68, s1
	v_fmamk_f32 v68, v68, 0x3a800000, v74
	v_rsq_f32_e32 v68, v68
	s_nop 0
	v_pk_mul_f32 v[32:33], v[32:33], v[68:69] op_sel_hi:[1,0]
	v_pk_mul_f32 v[34:35], v[34:35], v[68:69] op_sel_hi:[1,0]
	v_pk_mul_f32 v[36:37], v[36:37], v[68:69] op_sel_hi:[1,0]
	v_pk_mul_f32 v[38:39], v[38:39], v[68:69] op_sel_hi:[1,0]
	v_pk_mul_f32 v[40:41], v[40:41], v[68:69] op_sel_hi:[1,0]
	v_pk_mul_f32 v[42:43], v[42:43], v[68:69] op_sel_hi:[1,0]
	v_pk_mul_f32 v[44:45], v[44:45], v[68:69] op_sel_hi:[1,0]
	v_pk_mul_f32 v[46:47], v[46:47], v[68:69] op_sel_hi:[1,0]
	v_pk_fma_f32 v[32:33], v[50:51], v[32:33], v[78:79]
	v_pk_fma_f32 v[34:35], v[52:53], v[34:35], v[80:81]
	v_pk_fma_f32 v[36:37], v[54:55], v[36:37], v[82:83]
	v_pk_fma_f32 v[38:39], v[56:57], v[38:39], v[84:85]
	v_pk_fma_f32 v[40:41], v[58:59], v[40:41], v[86:87]
	v_pk_fma_f32 v[42:43], v[60:61], v[42:43], v[88:89]
	v_pk_fma_f32 v[44:45], v[62:63], v[44:45], v[90:91]
	v_pk_fma_f32 v[46:47], v[64:65], v[46:47], v[92:93]
	v_cvt_pk_bf16_f32 v32, v32, v33
	v_cvt_pk_bf16_f32 v33, v34, v35
	v_cvt_pk_bf16_f32 v36, v36, v37
	v_cvt_pk_bf16_f32 v37, v38, v39
	v_cvt_pk_bf16_f32 v40, v40, v41
	v_cvt_pk_bf16_f32 v41, v42, v43
	v_cvt_pk_bf16_f32 v44, v44, v45
	v_cvt_pk_bf16_f32 v45, v46, v47
	global_store_dwordx2 v67, v[32:33], s[6:7] offset:0
	global_store_dwordx2 v67, v[36:37], s[6:7] offset:512
	global_store_dwordx2 v67, v[40:41], s[6:7] offset:1024
	global_store_dwordx2 v67, v[44:45], s[6:7] offset:1536
	s_add_u32 s6, s6, 0x800
	s_addc_u32 s7, s7, 0
	s_waitcnt vmcnt(12)
	v_pk_mul_f32 v[70:71], v[0:1], v[0:1]
	v_pk_mul_f32 v[72:73], v[2:3], v[2:3]
	v_pk_fma_f32 v[70:71], v[4:5], v[4:5], v[70:71]
	v_pk_fma_f32 v[72:73], v[6:7], v[6:7], v[72:73]
	v_pk_fma_f32 v[70:71], v[8:9], v[8:9], v[70:71]
	v_pk_fma_f32 v[72:73], v[10:11], v[10:11], v[72:73]
	v_pk_fma_f32 v[70:71], v[12:13], v[12:13], v[70:71]
	v_pk_fma_f32 v[72:73], v[14:15], v[14:15], v[72:73]
	s_nop 0
	v_pk_add_f32 v[70:71], v[70:71], v[72:73]
	s_nop 0
	v_add_f32_e32 v68, v70, v71
	s_nop 1
	v_add_f32_dpp v68, v68, v68 quad_perm:[1,0,3,2] row_mask:0xf bank_mask:0xf bound_ctrl:1
	s_nop 1
	v_add_f32_dpp v68, v68, v68 quad_perm:[2,3,0,1] row_mask:0xf bank_mask:0xf bound_ctrl:1
	s_nop 1
	v_add_f32_dpp v68, v68, v68 row_half_mirror row_mask:0xf bank_mask:0xf bound_ctrl:1
	s_nop 1
	v_add_f32_dpp v68, v68, v68 row_mirror row_mask:0xf bank_mask:0xf bound_ctrl:1
	s_nop 1
	v_add_f32_dpp v68, v68, v68 row_bcast:15 row_mask:0xa bank_mask:0xf
	s_nop 1
	v_add_f32_dpp v68, v68, v68 row_bcast:31 row_mask:0xc bank_mask:0xf
	s_nop 1
	v_readlane_b32 s1, v68, 63
	s_nop 3
	v_mov_b32_e32 v68, s1
	v_fmamk_f32 v68, v68, 0x3a800000, v74
	v_rsq_f32_e32 v68, v68
	s_nop 0
	v_pk_mul_f32 v[0:1], v[0:1], v[68:69] op_sel_hi:[1,0]
	v_pk_mul_f32 v[2:3], v[2:3], v[68:69] op_sel_hi:[1,0]
	v_pk_mul_f32 v[4:5], v[4:5], v[68:69] op_sel_hi:[1,0]
	v_pk_mul_f32 v[6:7], v[6:7], v[68:69] op_sel_hi:[1,0]
	v_pk_mul_f32 v[8:9], v[8:9], v[68:69] op_sel_hi:[1,0]
	v_pk_mul_f32 v[10:11], v[10:11], v[68:69] op_sel_hi:[1,0]
	v_pk_mul_f32 v[12:13], v[12:13], v[68:69] op_sel_hi:[1,0]
	v_pk_mul_f32 v[14:15], v[14:15], v[68:69] op_sel_hi:[1,0]
	v_pk_fma_f32 v[0:1], v[50:51], v[0:1], v[78:79]
	v_pk_fma_f32 v[2:3], v[52:53], v[2:3], v[80:81]
	v_pk_fma_f32 v[4:5], v[54:55], v[4:5], v[82:83]
	v_pk_fma_f32 v[6:7], v[56:57], v[6:7], v[84:85]
	v_pk_fma_f32 v[8:9], v[58:59], v[8:9], v[86:87]
	v_pk_fma_f32 v[10:11], v[60:61], v[10:11], v[88:89]
	v_pk_fma_f32 v[12:13], v[62:63], v[12:13], v[90:91]
	v_pk_fma_f32 v[14:15], v[64:65], v[14:15], v[92:93]
	v_cvt_pk_bf16_f32 v0, v0, v1
	v_cvt_pk_bf16_f32 v1, v2, v3
	v_cvt_pk_bf16_f32 v4, v4, v5
	v_cvt_pk_bf16_f32 v5, v6, v7
	v_cvt_pk_bf16_f32 v8, v8, v9
	v_cvt_pk_bf16_f32 v9, v10, v11
	v_cvt_pk_bf16_f32 v12, v12, v13
	v_cvt_pk_bf16_f32 v13, v14, v15
	global_store_dwordx2 v67, v[0:1], s[6:7] offset:0
	global_store_dwordx2 v67, v[4:5], s[6:7] offset:512
	global_store_dwordx2 v67, v[8:9], s[6:7] offset:1024
	global_store_dwordx2 v67, v[12:13], s[6:7] offset:1536
	s_add_u32 s6, s6, 0x800
	s_addc_u32 s7, s7, 0
	s_waitcnt vmcnt(8)
	v_pk_mul_f32 v[70:71], v[16:17], v[16:17]
	v_pk_mul_f32 v[72:73], v[18:19], v[18:19]
	v_pk_fma_f32 v[70:71], v[20:21], v[20:21], v[70:71]
	v_pk_fma_f32 v[72:73], v[22:23], v[22:23], v[72:73]
	v_pk_fma_f32 v[70:71], v[24:25], v[24:25], v[70:71]
	v_pk_fma_f32 v[72:73], v[26:27], v[26:27], v[72:73]
	v_pk_fma_f32 v[70:71], v[28:29], v[28:29], v[70:71]
	v_pk_fma_f32 v[72:73], v[30:31], v[30:31], v[72:73]
	s_nop 0
	v_pk_add_f32 v[70:71], v[70:71], v[72:73]
	s_nop 0
	v_add_f32_e32 v68, v70, v71
	s_nop 1
	v_add_f32_dpp v68, v68, v68 quad_perm:[1,0,3,2] row_mask:0xf bank_mask:0xf bound_ctrl:1
	s_nop 1
	v_add_f32_dpp v68, v68, v68 quad_perm:[2,3,0,1] row_mask:0xf bank_mask:0xf bound_ctrl:1
	s_nop 1
	v_add_f32_dpp v68, v68, v68 row_half_mirror row_mask:0xf bank_mask:0xf bound_ctrl:1
	s_nop 1
	v_add_f32_dpp v68, v68, v68 row_mirror row_mask:0xf bank_mask:0xf bound_ctrl:1
	s_nop 1
	v_add_f32_dpp v68, v68, v68 row_bcast:15 row_mask:0xa bank_mask:0xf
	s_nop 1
	v_add_f32_dpp v68, v68, v68 row_bcast:31 row_mask:0xc bank_mask:0xf
	s_nop 1
	v_readlane_b32 s1, v68, 63
	s_nop 3
	v_mov_b32_e32 v68, s1
	v_fmamk_f32 v68, v68, 0x3a800000, v74
	v_rsq_f32_e32 v68, v68
	s_nop 0
	v_pk_mul_f32 v[16:17], v[16:17], v[68:69] op_sel_hi:[1,0]
	v_pk_mul_f32 v[18:19], v[18:19], v[68:69] op_sel_hi:[1,0]
	v_pk_mul_f32 v[20:21], v[20:21], v[68:69] op_sel_hi:[1,0]
	v_pk_mul_f32 v[22:23], v[22:23], v[68:69] op_sel_hi:[1,0]
	v_pk_mul_f32 v[24:25], v[24:25], v[68:69] op_sel_hi:[1,0]
	v_pk_mul_f32 v[26:27], v[26:27], v[68:69] op_sel_hi:[1,0]
	v_pk_mul_f32 v[28:29], v[28:29], v[68:69] op_sel_hi:[1,0]
	v_pk_mul_f32 v[30:31], v[30:31], v[68:69] op_sel_hi:[1,0]
	v_pk_fma_f32 v[16:17], v[50:51], v[16:17], v[78:79]
	v_pk_fma_f32 v[18:19], v[52:53], v[18:19], v[80:81]
	v_pk_fma_f32 v[20:21], v[54:55], v[20:21], v[82:83]
	v_pk_fma_f32 v[22:23], v[56:57], v[22:23], v[84:85]
	v_pk_fma_f32 v[24:25], v[58:59], v[24:25], v[86:87]
	v_pk_fma_f32 v[26:27], v[60:61], v[26:27], v[88:89]
	v_pk_fma_f32 v[28:29], v[62:63], v[28:29], v[90:91]
	v_pk_fma_f32 v[30:31], v[64:65], v[30:31], v[92:93]
	v_cvt_pk_bf16_f32 v16, v16, v17
	v_cvt_pk_bf16_f32 v17, v18, v19
	v_cvt_pk_bf16_f32 v20, v20, v21
	v_cvt_pk_bf16_f32 v21, v22, v23
	v_cvt_pk_bf16_f32 v24, v24, v25
	v_cvt_pk_bf16_f32 v25, v26, v27
	v_cvt_pk_bf16_f32 v28, v28, v29
	v_cvt_pk_bf16_f32 v29, v30, v31
	global_store_dwordx2 v67, v[16:17], s[6:7] offset:0
	global_store_dwordx2 v67, v[20:21], s[6:7] offset:512
	global_store_dwordx2 v67, v[24:25], s[6:7] offset:1024
	global_store_dwordx2 v67, v[28:29], s[6:7] offset:1536
	s_add_u32 s6, s6, 0x800
	s_addc_u32 s7, s7, 0
	s_branch .LBB0_1022
.Lnorm_orig_2:
	s_load_dwordx2 s[6:7], s[2:3], 0x0
	s_nop 0
	s_load_dwordx2 s[2:3], s[2:3], 0x20
	v_ashrrev_i32_e32 v49, 31, v48
	v_lshlrev_b32_e32 v2, 4, v8
	v_lshlrev_b64 v[10:11], 12, v[48:49]
	s_waitcnt lgkmcnt(0)
	v_lshl_add_u64 v[0:1], s[6:7], 0, v[10:11]
	v_and_b32_e32 v128, 0x3f0, v2
	v_lshl_add_u64 v[0:1], v[0:1], 0, v[128:129]
	s_mov_b64 s[8:9], 0x4000000
	v_lshl_add_u64 v[2:3], v[0:1], 0, s[8:9]
	v_add_co_u32_e32 v0, vcc, 0x4000000, v0
	v_lshl_add_u64 v[50:51], s[2:3], 0, v[128:129]
	s_nop 0
	v_addc_co_u32_e32 v1, vcc, 0, v1, vcc
	global_load_dwordx4 v[12:15], v[2:3], off offset:1024
	global_load_dwordx4 v[4:7], v[2:3], off offset:2048
	global_load_dwordx4 v[20:23], v[0:1], off
	s_nop 0
	global_load_dwordx4 v[0:3], v[2:3], off offset:3072
	v_cmp_lt_i32_e32 vcc, v171, v165
	v_lshl_add_u64 v[16:17], s[0:1], 0, v[128:129]
	s_mov_b64 s[2:3], 0x781000
	v_cndmask_b32_e32 v9, v164, v171, vcc
	v_cmp_lt_i32_e32 vcc, v170, v165
	v_lshlrev_b32_e32 v77, 2, v9
	v_lshl_add_u64 v[52:53], v[16:17], 0, s[2:3]
	v_cndmask_b32_e32 v9, v164, v170, vcc
	v_cmp_lt_i32_e32 vcc, v169, v165
	v_lshlrev_b32_e32 v78, 2, v9
	s_mov_b64 s[2:3], 0x780000
	v_cndmask_b32_e32 v9, v164, v169, vcc
	v_cmp_lt_i32_e32 vcc, v168, v165
	v_lshlrev_b32_e32 v79, 2, v9
	v_lshl_add_u64 v[54:55], v[16:17], 0, s[2:3]
	v_cndmask_b32_e32 v9, v164, v168, vcc
	v_cmp_lt_i32_e32 vcc, v167, v165
	v_lshlrev_b32_e32 v80, 2, v9
	v_lshlrev_b64 v[16:17], 11, v[48:49]
	v_cndmask_b32_e32 v9, v164, v167, vcc
	v_cmp_lt_i32_e32 vcc, v166, v165
	v_and_b32_e32 v18, 63, v8
	v_lshlrev_b32_e32 v81, 2, v9
	v_cndmask_b32_e32 v9, v164, v166, vcc
	v_lshl_or_b32 v16, v18, 3, v16
	v_lshlrev_b32_e32 v82, 2, v9
	v_lshl_add_u64 v[8:9], s[0:1], 0, v[16:17]
	s_mov_b64 s[0:1], 0x1c00000
	v_lshl_or_b32 v10, v18, 4, v10
	v_lshl_add_u64 v[56:57], v[8:9], 0, s[0:1]
	v_lshl_add_u64 v[8:9], s[6:7], 0, v[10:11]
	s_mov_b64 s[0:1], 0x4001c00
	v_mov_b32_e32 v60, 0
	v_mov_b32_e32 v83, -1
	v_lshl_add_u64 v[58:59], v[8:9], 0, s[0:1]
	s_mov_b64 s[2:3], 0
	v_mov_b32_e32 v61, v60
	v_mov_b32_e32 v62, v60
	v_mov_b32_e32 v63, v60
	v_mov_b32_e32 v64, v60
	v_mov_b32_e32 v65, v60
	v_mov_b32_e32 v66, v60
	v_mov_b32_e32 v67, v60
	v_mov_b32_e32 v68, v60
	v_mov_b32_e32 v69, v60
	v_mov_b32_e32 v70, v60
	v_mov_b32_e32 v71, v60
	v_mov_b32_e32 v72, v60
	v_mov_b32_e32 v73, v60
	v_mov_b32_e32 v74, v60
	v_mov_b32_e32 v75, v60
	s_branch .LBB0_1018

.LBB0_1262:
	v_readlane_b32 s3, v254, 2
	v_readlane_b32 s6, v255, 9
	v_mbcnt_lo_u32_b32 v16, -1, 0
	v_mbcnt_hi_u32_b32 v16, -1, v16
	s_add_i32 s2, s6, 0x7fff
	v_lshl_add_u32 v0, s3, 6, v16
	v_ashrrev_i32_e32 v0, 6, v0
	v_readlane_b32 s3, v254, 9
	s_sub_i32 s6, 0xffff8001, s6
	v_readlane_b32 s7, v255, 8
	v_add_u32_e32 v0, s3, v0
	s_ashr_i32 s3, s2, 31
	s_max_i32 s2, s2, s6
	v_readlane_b32 s6, v255, 10
	s_mul_hi_u32 s6, s2, s6
	v_readlane_b32 s9, v255, 11
	s_xor_b32 s3, s3, s7
	s_mul_i32 s7, s6, s9
	s_sub_i32 s2, s2, s7
	s_add_i32 s7, s6, 1
	s_sub_i32 s8, s2, s9
	s_cmp_ge_u32 s2, s9
	s_cselect_b32 s6, s7, s6
	s_cselect_b32 s2, s8, s2
	s_add_i32 s7, s6, 1
	s_cmp_ge_u32 s2, s9
	s_cselect_b32 s2, s7, s6
	s_xor_b32 s2, s2, s3
	s_sub_i32 s2, s2, s3
	v_mul_lo_u32 v48, v0, s2
	v_add_u32_e32 v0, s2, v48
	v_min_i32_e32 v76, 0x8000, v0
	v_cmp_lt_i32_e32 vcc, v48, v76
	s_and_saveexec_b64 s[2:3], vcc
	s_cbranch_execz .LBB0_1269
	s_cmp_lg_u32 s80, 0x100
	s_cbranch_scc1 .Lnorm_orig_3
	v_readlane_b32 s0, v254, 0
	v_readlane_b32 s1, v254, 1
	v_readfirstlane_b32 s100, v48
	s_nop 3
	s_load_dwordx2 s[4:5], s[0:1], 0xd8
	s_load_dwordx2 s[98:99], s[0:1], 0xa8
	s_load_dwordx2 s[6:7], s[0:1], 0xe0
	v_mbcnt_lo_u32_b32 v66, -1, 0
	v_mbcnt_hi_u32_b32 v66, -1, v66
	v_lshlrev_b32_e32 v67, 3, v66
	v_lshlrev_b32_e32 v66, 4, v66
	v_mov_b32_e32 v74, 0x358637bd
	s_waitcnt lgkmcnt(0)
	s_mov_b32 s0, s100
	s_add_u32 s1, s0, 0
	s_lshl_b32 s1, s1, 12
	s_add_u32 s4, s4, s1
	s_addc_u32 s5, s5, 0
	global_load_dwordx4 v[50:53], v66, s[98:99] offset:0
	global_load_dwordx4 v[54:57], v66, s[98:99] offset:1024
	global_load_dwordx4 v[58:61], v66, s[98:99] offset:2048
	global_load_dwordx4 v[62:65], v66, s[98:99] offset:3072
	s_add_u32 s1, s0, 0
	s_lshr_b32 s1, s1, 12
	s_mul_i32 s1, s1, 0x6000
	s_add_u32 s100, s6, s1
	s_addc_u32 s101, s7, 0
	s_add_u32 s100, s100, 0x780000
	s_addc_u32 s101, s101, 0
	s_add_u32 s98, s100, 16384
	s_addc_u32 s99, s101, 0
	global_load_dwordx4 v[32:35], v66, s[98:99] offset:0
	global_load_dwordx4 v[36:39], v66, s[98:99] offset:1024
	global_load_dwordx4 v[40:43], v66, s[98:99] offset:2048
	global_load_dwordx4 v[44:47], v66, s[98:99] offset:3072
	s_add_u32 s100, s100, 12288
	s_addc_u32 s101, s101, 0
	global_load_dwordx4 v[78:81], v66, s[100:101] offset:0
	global_load_dwordx4 v[82:85], v66, s[100:101] offset:1024
	global_load_dwordx4 v[86:89], v66, s[100:101] offset:2048
	global_load_dwordx4 v[90:93], v66, s[100:101] offset:3072
	s_add_u32 s6, s6, 0x1c00000
	s_addc_u32 s7, s7, 0
	s_lshl_b32 s1, s0, 11
	s_add_u32 s6, s6, s1
	s_addc_u32 s7, s7, 0
	global_load_dwordx4 v[0:3], v66, s[4:5] offset:0
	global_load_dwordx4 v[4:7], v66, s[4:5] offset:1024
	global_load_dwordx4 v[8:11], v66, s[4:5] offset:2048
	global_load_dwordx4 v[12:15], v66, s[4:5] offset:3072
	s_add_u32 s4, s4, 0x1000
	s_addc_u32 s5, s5, 0
	global_load_dwordx4 v[16:19], v66, s[4:5] offset:0
	global_load_dwordx4 v[20:23], v66, s[4:5] offset:1024
	global_load_dwordx4 v[24:27], v66, s[4:5] offset:2048
	global_load_dwordx4 v[28:31], v66, s[4:5] offset:3072
	s_add_u32 s4, s4, 0x1000
	s_addc_u32 s5, s5, 0
	s_waitcnt vmcnt(8)
	v_pk_add_f32 v[32:33], v[32:33], 1.0 op_sel_hi:[1,0]
	v_pk_add_f32 v[34:35], v[34:35], 1.0 op_sel_hi:[1,0]
	v_pk_add_f32 v[36:37], v[36:37], 1.0 op_sel_hi:[1,0]
	v_pk_add_f32 v[38:39], v[38:39], 1.0 op_sel_hi:[1,0]
	v_pk_add_f32 v[40:41], v[40:41], 1.0 op_sel_hi:[1,0]
	v_pk_add_f32 v[42:43], v[42:43], 1.0 op_sel_hi:[1,0]
	v_pk_add_f32 v[44:45], v[44:45], 1.0 op_sel_hi:[1,0]
	v_pk_add_f32 v[46:47], v[46:47], 1.0 op_sel_hi:[1,0]
	v_pk_mul_f32 v[50:51], v[50:51], v[32:33]
	v_pk_mul_f32 v[52:53], v[52:53], v[34:35]
	v_pk_mul_f32 v[54:55], v[54:55], v[36:37]
	v_pk_mul_f32 v[56:57], v[56:57], v[38:39]
	v_pk_mul_f32 v[58:59], v[58:59], v[40:41]
	v_pk_mul_f32 v[60:61], v[60:61], v[42:43]
	v_pk_mul_f32 v[62:63], v[62:63], v[44:45]
	v_pk_mul_f32 v[64:65], v[64:65], v[46:47]
	global_load_dwordx4 v[32:35], v66, s[4:5] offset:0
	global_load_dwordx4 v[36:39], v66, s[4:5] offset:1024
	global_load_dwordx4 v[40:43], v66, s[4:5] offset:2048
	global_load_dwordx4 v[44:47], v66, s[4:5] offset:3072
	s_add_u32 s4, s4, 0x1000
	s_addc_u32 s5, s5, 0
	s_waitcnt vmcnt(8)
	v_pk_mul_f32 v[70:71], v[0:1], v[0:1]
	v_pk_mul_f32 v[72:73], v[2:3], v[2:3]
	v_pk_fma_f32 v[70:71], v[4:5], v[4:5], v[70:71]
	v_pk_fma_f32 v[72:73], v[6:7], v[6:7], v[72:73]
	v_pk_fma_f32 v[70:71], v[8:9], v[8:9], v[70:71]
	v_pk_fma_f32 v[72:73], v[10:11], v[10:11], v[72:73]
	v_pk_fma_f32 v[70:71], v[12:13], v[12:13], v[70:71]
	v_pk_fma_f32 v[72:73], v[14:15], v[14:15], v[72:73]
	s_nop 0
	v_pk_add_f32 v[70:71], v[70:71], v[72:73]
	s_nop 0
	v_add_f32_e32 v68, v70, v71
	s_nop 1
	v_add_f32_dpp v68, v68, v68 quad_perm:[1,0,3,2] row_mask:0xf bank_mask:0xf bound_ctrl:1
	s_nop 1
	v_add_f32_dpp v68, v68, v68 quad_perm:[2,3,0,1] row_mask:0xf bank_mask:0xf bound_ctrl:1
	s_nop 1
	v_add_f32_dpp v68, v68, v68 row_half_mirror row_mask:0xf bank_mask:0xf bound_ctrl:1
	s_nop 1
	v_add_f32_dpp v68, v68, v68 row_mirror row_mask:0xf bank_mask:0xf bound_ctrl:1
	s_nop 1
	v_add_f32_dpp v68, v68, v68 row_bcast:15 row_mask:0xa bank_mask:0xf
	s_nop 1
	v_add_f32_dpp v68, v68, v68 row_bcast:31 row_mask:0xc bank_mask:0xf
	s_nop 1
	v_readlane_b32 s1, v68, 63
	s_nop 3
	v_mov_b32_e32 v68, s1
	v_fmamk_f32 v68, v68, 0x3a800000, v74
	v_rsq_f32_e32 v68, v68
	s_nop 0
	v_pk_mul_f32 v[0:1], v[0:1], v[68:69] op_sel_hi:[1,0]
	v_pk_mul_f32 v[2:3], v[2:3], v[68:69] op_sel_hi:[1,0]
	v_pk_mul_f32 v[4:5], v[4:5], v[68:69] op_sel_hi:[1,0]
	v_pk_mul_f32 v[6:7], v[6:7], v[68:69] op_sel_hi:[1,0]
	v_pk_mul_f32 v[8:9], v[8:9], v[68:69] op_sel_hi:[1,0]
	v_pk_mul_f32 v[10:11], v[10:11], v[68:69] op_sel_hi:[1,0]
	v_pk_mul_f32 v[12:13], v[12:13], v[68:69] op_sel_hi:[1,0]
	v_pk_mul_f32 v[14:15], v[14:15], v[68:69] op_sel_hi:[1,0]
	v_pk_fma_f32 v[0:1], v[50:51], v[0:1], v[78:79]
	v_pk_fma_f32 v[2:3], v[52:53], v[2:3], v[80:81]
	v_pk_fma_f32 v[4:5], v[54:55], v[4:5], v[82:83]
	v_pk_fma_f32 v[6:7], v[56:57], v[6:7], v[84:85]
	v_pk_fma_f32 v[8:9], v[58:59], v[8:9], v[86:87]
	v_pk_fma_f32 v[10:11], v[60:61], v[10:11], v[88:89]
	v_pk_fma_f32 v[12:13], v[62:63], v[12:13], v[90:91]
	v_pk_fma_f32 v[14:15], v[64:65], v[14:15], v[92:93]
	v_cvt_pk_bf16_f32 v0, v0, v1
	v_cvt_pk_bf16_f32 v1, v2, v3
	v_cvt_pk_bf16_f32 v4, v4, v5
	v_cvt_pk_bf16_f32 v5, v6, v7
	v_cvt_pk_bf16_f32 v8, v8, v9
	v_cvt_pk_bf16_f32 v9, v10, v11
	v_cvt_pk_bf16_f32 v12, v12, v13
	v_cvt_pk_bf16_f32 v13, v14, v15
	global_store_dwordx2 v67, v[0:1], s[6:7] offset:0
	global_store_dwordx2 v67, v[4:5], s[6:7] offset:512
	global_store_dwordx2 v67, v[8:9], s[6:7] offset:1024
	global_store_dwordx2 v67, v[12:13], s[6:7] offset:1536
	s_add_u32 s6, s6, 0x800
	s_addc_u32 s7, s7, 0
	global_load_dwordx4 v[0:3], v66, s[4:5] offset:0
	global_load_dwordx4 v[4:7], v66, s[4:5] offset:1024
	global_load_dwordx4 v[8:11], v66, s[4:5] offset:2048
	global_load_dwordx4 v[12:15], v66, s[4:5] offset:3072
	s_add_u32 s4, s4, 0x1000
	s_addc_u32 s5, s5, 0
	s_waitcnt vmcnt(12)
	v_pk_mul_f32 v[70:71], v[16:17], v[16:17]
	v_pk_mul_f32 v[72:73], v[18:19], v[18:19]
	v_pk_fma_f32 v[70:71], v[20:21], v[20:21], v[70:71]
	v_pk_fma_f32 v[72:73], v[22:23], v[22:23], v[72:73]
	v_pk_fma_f32 v[70:71], v[24:25], v[24:25], v[70:71]
	v_pk_fma_f32 v[72:73], v[26:27], v[26:27], v[72:73]
	v_pk_fma_f32 v[70:71], v[28:29], v[28:29], v[70:71]
	v_pk_fma_f32 v[72:73], v[30:31], v[30:31], v[72:73]
	s_nop 0
	v_pk_add_f32 v[70:71], v[70:71], v[72:73]
	s_nop 0
	v_add_f32_e32 v68, v70, v71
	s_nop 1
	v_add_f32_dpp v68, v68, v68 quad_perm:[1,0,3,2] row_mask:0xf bank_mask:0xf bound_ctrl:1
	s_nop 1
	v_add_f32_dpp v68, v68, v68 quad_perm:[2,3,0,1] row_mask:0xf bank_mask:0xf bound_ctrl:1
	s_nop 1
	v_add_f32_dpp v68, v68, v68 row_half_mirror row_mask:0xf bank_mask:0xf bound_ctrl:1
	s_nop 1
	v_add_f32_dpp v68, v68, v68 row_mirror row_mask:0xf bank_mask:0xf bound_ctrl:1
	s_nop 1
	v_add_f32_dpp v68, v68, v68 row_bcast:15 row_mask:0xa bank_mask:0xf
	s_nop 1
	v_add_f32_dpp v68, v68, v68 row_bcast:31 row_mask:0xc bank_mask:0xf
	s_nop 1
	v_readlane_b32 s1, v68, 63
	s_nop 3
	v_mov_b32_e32 v68, s1
	v_fmamk_f32 v68, v68, 0x3a800000, v74
	v_rsq_f32_e32 v68, v68
	s_nop 0
	v_pk_mul_f32 v[16:17], v[16:17], v[68:69] op_sel_hi:[1,0]
	v_pk_mul_f32 v[18:19], v[18:19], v[68:69] op_sel_hi:[1,0]
	v_pk_mul_f32 v[20:21], v[20:21], v[68:69] op_sel_hi:[1,0]
	v_pk_mul_f32 v[22:23], v[22:23], v[68:69] op_sel_hi:[1,0]
	v_pk_mul_f32 v[24:25], v[24:25], v[68:69] op_sel_hi:[1,0]
	v_pk_mul_f32 v[26:27], v[26:27], v[68:69] op_sel_hi:[1,0]
	v_pk_mul_f32 v[28:29], v[28:29], v[68:69] op_sel_hi:[1,0]
	v_pk_mul_f32 v[30:31], v[30:31], v[68:69] op_sel_hi:[1,0]
	v_pk_fma_f32 v[16:17], v[50:51], v[16:17], v[78:79]
	v_pk_fma_f32 v[18:19], v[52:53], v[18:19], v[80:81]
	v_pk_fma_f32 v[20:21], v[54:55], v[20:21], v[82:83]
	v_pk_fma_f32 v[22:23], v[56:57], v[22:23], v[84:85]
	v_pk_fma_f32 v[24:25], v[58:59], v[24:25], v[86:87]
	v_pk_fma_f32 v[26:27], v[60:61], v[26:27], v[88:89]
	v_pk_fma_f32 v[28:29], v[62:63], v[28:29], v[90:91]
	v_pk_fma_f32 v[30:31], v[64:65], v[30:31], v[92:93]
	v_cvt_pk_bf16_f32 v16, v16, v17
	v_cvt_pk_bf16_f32 v17, v18, v19
	v_cvt_pk_bf16_f32 v20, v20, v21
	v_cvt_pk_bf16_f32 v21, v22, v23
	v_cvt_pk_bf16_f32 v24, v24, v25
	v_cvt_pk_bf16_f32 v25, v26, v27
	v_cvt_pk_bf16_f32 v28, v28, v29
	v_cvt_pk_bf16_f32 v29, v30, v31
	global_store_dwordx2 v67, v[16:17], s[6:7] offset:0
	global_store_dwordx2 v67, v[20:21], s[6:7] offset:512
	global_store_dwordx2 v67, v[24:25], s[6:7] offset:1024
	global_store_dwordx2 v67, v[28:29], s[6:7] offset:1536
	s_add_u32 s6, s6, 0x800
	s_addc_u32 s7, s7, 0
	global_load_dwordx4 v[16:19], v66, s[4:5] offset:0
	global_load_dwordx4 v[20:23], v66, s[4:5] offset:1024
	global_load_dwordx4 v[24:27], v66, s[4:5] offset:2048
	global_load_dwordx4 v[28:31], v66, s[4:5] offset:3072
	s_add_u32 s4, s4, 0x1000
	s_addc_u32 s5, s5, 0
	s_waitcnt vmcnt(16)
	v_pk_mul_f32 v[70:71], v[32:33], v[32:33]
	v_pk_mul_f32 v[72:73], v[34:35], v[34:35]
	v_pk_fma_f32 v[70:71], v[36:37], v[36:37], v[70:71]
	v_pk_fma_f32 v[72:73], v[38:39], v[38:39], v[72:73]
	v_pk_fma_f32 v[70:71], v[40:41], v[40:41], v[70:71]
	v_pk_fma_f32 v[72:73], v[42:43], v[42:43], v[72:73]
	v_pk_fma_f32 v[70:71], v[44:45], v[44:45], v[70:71]
	v_pk_fma_f32 v[72:73], v[46:47], v[46:47], v[72:73]
	s_nop 0
	v_pk_add_f32 v[70:71], v[70:71], v[72:73]
	s_nop 0
	v_add_f32_e32 v68, v70, v71
	s_nop 1
	v_add_f32_dpp v68, v68, v68 quad_perm:[1,0,3,2] row_mask:0xf bank_mask:0xf bound_ctrl:1
	s_nop 1
	v_add_f32_dpp v68, v68, v68 quad_perm:[2,3,0,1] row_mask:0xf bank_mask:0xf bound_ctrl:1
	s_nop 1
	v_add_f32_dpp v68, v68, v68 row_half_mirror row_mask:0xf bank_mask:0xf bound_ctrl:1
	s_nop 1
	v_add_f32_dpp v68, v68, v68 row_mirror row_mask:0xf bank_mask:0xf bound_ctrl:1
	s_nop 1
	v_add_f32_dpp v68, v68, v68 row_bcast:15 row_mask:0xa bank_mask:0xf
	s_nop 1
	v_add_f32_dpp v68, v68, v68 row_bcast:31 row_mask:0xc bank_mask:0xf
	s_nop 1
	v_readlane_b32 s1, v68, 63
	s_nop 3
	v_mov_b32_e32 v68, s1
	v_fmamk_f32 v68, v68, 0x3a800000, v74
	v_rsq_f32_e32 v68, v68
	s_nop 0
	v_pk_mul_f32 v[32:33], v[32:33], v[68:69] op_sel_hi:[1,0]
	v_pk_mul_f32 v[34:35], v[34:35], v[68:69] op_sel_hi:[1,0]
	v_pk_mul_f32 v[36:37], v[36:37], v[68:69] op_sel_hi:[1,0]
	v_pk_mul_f32 v[38:39], v[38:39], v[68:69] op_sel_hi:[1,0]
	v_pk_mul_f32 v[40:41], v[40:41], v[68:69] op_sel_hi:[1,0]
	v_pk_mul_f32 v[42:43], v[42:43], v[68:69] op_sel_hi:[1,0]
	v_pk_mul_f32 v[44:45], v[44:45], v[68:69] op_sel_hi:[1,0]
	v_pk_mul_f32 v[46:47], v[46:47], v[68:69] op_sel_hi:[1,0]
	v_pk_fma_f32 v[32:33], v[50:51], v[32:33], v[78:79]
	v_pk_fma_f32 v[34:35], v[52:53], v[34:35], v[80:81]
	v_pk_fma_f32 v[36:37], v[54:55], v[36:37], v[82:83]
	v_pk_fma_f32 v[38:39], v[56:57], v[38:39], v[84:85]
	v_pk_fma_f32 v[40:41], v[58:59], v[40:41], v[86:87]
	v_pk_fma_f32 v[42:43], v[60:61], v[42:43], v[88:89]
	v_pk_fma_f32 v[44:45], v[62:63], v[44:45], v[90:91]
	v_pk_fma_f32 v[46:47], v[64:65], v[46:47], v[92:93]
	v_cvt_pk_bf16_f32 v32, v32, v33
	v_cvt_pk_bf16_f32 v33, v34, v35
	v_cvt_pk_bf16_f32 v36, v36, v37
	v_cvt_pk_bf16_f32 v37, v38, v39
	v_cvt_pk_bf16_f32 v40, v40, v41
	v_cvt_pk_bf16_f32 v41, v42, v43
	v_cvt_pk_bf16_f32 v44, v44, v45
	v_cvt_pk_bf16_f32 v45, v46, v47
	global_store_dwordx2 v67, v[32:33], s[6:7] offset:0
	global_store_dwordx2 v67, v[36:37], s[6:7] offset:512
	global_store_dwordx2 v67, v[40:41], s[6:7] offset:1024
	global_store_dwordx2 v67, v[44:45], s[6:7] offset:1536
	s_add_u32 s6, s6, 0x800
	s_addc_u32 s7, s7, 0
	global_load_dwordx4 v[32:35], v66, s[4:5] offset:0
	global_load_dwordx4 v[36:39], v66, s[4:5] offset:1024
	global_load_dwordx4 v[40:43], v66, s[4:5] offset:2048
	global_load_dwordx4 v[44:47], v66, s[4:5] offset:3072
	s_add_u32 s4, s4, 0x1000
	s_addc_u32 s5, s5, 0
	s_waitcnt vmcnt(16)
	v_pk_mul_f32 v[70:71], v[0:1], v[0:1]
	v_pk_mul_f32 v[72:73], v[2:3], v[2:3]
	v_pk_fma_f32 v[70:71], v[4:5], v[4:5], v[70:71]
	v_pk_fma_f32 v[72:73], v[6:7], v[6:7], v[72:73]
	v_pk_fma_f32 v[70:71], v[8:9], v[8:9], v[70:71]
	v_pk_fma_f32 v[72:73], v[10:11], v[10:11], v[72:73]
	v_pk_fma_f32 v[70:71], v[12:13], v[12:13], v[70:71]
	v_pk_fma_f32 v[72:73], v[14:15], v[14:15], v[72:73]
	s_nop 0
	v_pk_add_f32 v[70:71], v[70:71], v[72:73]
	s_nop 0
	v_add_f32_e32 v68, v70, v71
	s_nop 1
	v_add_f32_dpp v68, v68, v68 quad_perm:[1,0,3,2] row_mask:0xf bank_mask:0xf bound_ctrl:1
	s_nop 1
	v_add_f32_dpp v68, v68, v68 quad_perm:[2,3,0,1] row_mask:0xf bank_mask:0xf bound_ctrl:1
	s_nop 1
	v_add_f32_dpp v68, v68, v68 row_half_mirror row_mask:0xf bank_mask:0xf bound_ctrl:1
	s_nop 1
	v_add_f32_dpp v68, v68, v68 row_mirror row_mask:0xf bank_mask:0xf bound_ctrl:1
	s_nop 1
	v_add_f32_dpp v68, v68, v68 row_bcast:15 row_mask:0xa bank_mask:0xf
	s_nop 1
	v_add_f32_dpp v68, v68, v68 row_bcast:31 row_mask:0xc bank_mask:0xf
	s_nop 1
	v_readlane_b32 s1, v68, 63
	s_nop 3
	v_mov_b32_e32 v68, s1
	v_fmamk_f32 v68, v68, 0x3a800000, v74
	v_rsq_f32_e32 v68, v68
	s_nop 0
	v_pk_mul_f32 v[0:1], v[0:1], v[68:69] op_sel_hi:[1,0]
	v_pk_mul_f32 v[2:3], v[2:3], v[68:69] op_sel_hi:[1,0]
	v_pk_mul_f32 v[4:5], v[4:5], v[68:69] op_sel_hi:[1,0]
	v_pk_mul_f32 v[6:7], v[6:7], v[68:69] op_sel_hi:[1,0]
	v_pk_mul_f32 v[8:9], v[8:9], v[68:69] op_sel_hi:[1,0]
	v_pk_mul_f32 v[10:11], v[10:11], v[68:69] op_sel_hi:[1,0]
	v_pk_mul_f32 v[12:13], v[12:13], v[68:69] op_sel_hi:[1,0]
	v_pk_mul_f32 v[14:15], v[14:15], v[68:69] op_sel_hi:[1,0]
	v_pk_fma_f32 v[0:1], v[50:51], v[0:1], v[78:79]
	v_pk_fma_f32 v[2:3], v[52:53], v[2:3], v[80:81]
	v_pk_fma_f32 v[4:5], v[54:55], v[4:5], v[82:83]
	v_pk_fma_f32 v[6:7], v[56:57], v[6:7], v[84:85]
	v_pk_fma_f32 v[8:9], v[58:59], v[8:9], v[86:87]
	v_pk_fma_f32 v[10:11], v[60:61], v[10:11], v[88:89]
	v_pk_fma_f32 v[12:13], v[62:63], v[12:13], v[90:91]
	v_pk_fma_f32 v[14:15], v[64:65], v[14:15], v[92:93]
	v_cvt_pk_bf16_f32 v0, v0, v1
	v_cvt_pk_bf16_f32 v1, v2, v3
	v_cvt_pk_bf16_f32 v4, v4, v5
	v_cvt_pk_bf16_f32 v5, v6, v7
	v_cvt_pk_bf16_f32 v8, v8, v9
	v_cvt_pk_bf16_f32 v9, v10, v11
	v_cvt_pk_bf16_f32 v12, v12, v13
	v_cvt_pk_bf16_f32 v13, v14, v15
	global_store_dwordx2 v67, v[0:1], s[6:7] offset:0
	global_store_dwordx2 v67, v[4:5], s[6:7] offset:512
	global_store_dwordx2 v67, v[8:9], s[6:7] offset:1024
	global_store_dwordx2 v67, v[12:13], s[6:7] offset:1536
	s_add_u32 s6, s6, 0x800
	s_addc_u32 s7, s7, 0
	global_load_dwordx4 v[0:3], v66, s[4:5] offset:0
	global_load_dwordx4 v[4:7], v66, s[4:5] offset:1024
	global_load_dwordx4 v[8:11], v66, s[4:5] offset:2048
	global_load_dwordx4 v[12:15], v66, s[4:5] offset:3072
	s_add_u32 s4, s4, 0x1000
	s_addc_u32 s5, s5, 0
	s_waitcnt vmcnt(16)
	v_pk_mul_f32 v[70:71], v[16:17], v[16:17]
	v_pk_mul_f32 v[72:73], v[18:19], v[18:19]
	v_pk_fma_f32 v[70:71], v[20:21], v[20:21], v[70:71]
	v_pk_fma_f32 v[72:73], v[22:23], v[22:23], v[72:73]
	v_pk_fma_f32 v[70:71], v[24:25], v[24:25], v[70:71]
	v_pk_fma_f32 v[72:73], v[26:27], v[26:27], v[72:73]
	v_pk_fma_f32 v[70:71], v[28:29], v[28:29], v[70:71]
	v_pk_fma_f32 v[72:73], v[30:31], v[30:31], v[72:73]
	s_nop 0
	v_pk_add_f32 v[70:71], v[70:71], v[72:73]
	s_nop 0
	v_add_f32_e32 v68, v70, v71
	s_nop 1
	v_add_f32_dpp v68, v68, v68 quad_perm:[1,0,3,2] row_mask:0xf bank_mask:0xf bound_ctrl:1
	s_nop 1
	v_add_f32_dpp v68, v68, v68 quad_perm:[2,3,0,1] row_mask:0xf bank_mask:0xf bound_ctrl:1
	s_nop 1
	v_add_f32_dpp v68, v68, v68 row_half_mirror row_mask:0xf bank_mask:0xf bound_ctrl:1
	s_nop 1
	v_add_f32_dpp v68, v68, v68 row_mirror row_mask:0xf bank_mask:0xf bound_ctrl:1
	s_nop 1
	v_add_f32_dpp v68, v68, v68 row_bcast:15 row_mask:0xa bank_mask:0xf
	s_nop 1
	v_add_f32_dpp v68, v68, v68 row_bcast:31 row_mask:0xc bank_mask:0xf
	s_nop 1
	v_readlane_b32 s1, v68, 63
	s_nop 3
	v_mov_b32_e32 v68, s1
	v_fmamk_f32 v68, v68, 0x3a800000, v74
	v_rsq_f32_e32 v68, v68
	s_nop 0
	v_pk_mul_f32 v[16:17], v[16:17], v[68:69] op_sel_hi:[1,0]
	v_pk_mul_f32 v[18:19], v[18:19], v[68:69] op_sel_hi:[1,0]
	v_pk_mul_f32 v[20:21], v[20:21], v[68:69] op_sel_hi:[1,0]
	v_pk_mul_f32 v[22:23], v[22:23], v[68:69] op_sel_hi:[1,0]
	v_pk_mul_f32 v[24:25], v[24:25], v[68:69] op_sel_hi:[1,0]
	v_pk_mul_f32 v[26:27], v[26:27], v[68:69] op_sel_hi:[1,0]
	v_pk_mul_f32 v[28:29], v[28:29], v[68:69] op_sel_hi:[1,0]
	v_pk_mul_f32 v[30:31], v[30:31], v[68:69] op_sel_hi:[1,0]
	v_pk_fma_f32 v[16:17], v[50:51], v[16:17], v[78:79]
	v_pk_fma_f32 v[18:19], v[52:53], v[18:19], v[80:81]
	v_pk_fma_f32 v[20:21], v[54:55], v[20:21], v[82:83]
	v_pk_fma_f32 v[22:23], v[56:57], v[22:23], v[84:85]
	v_pk_fma_f32 v[24:25], v[58:59], v[24:25], v[86:87]
	v_pk_fma_f32 v[26:27], v[60:61], v[26:27], v[88:89]
	v_pk_fma_f32 v[28:29], v[62:63], v[28:29], v[90:91]
	v_pk_fma_f32 v[30:31], v[64:65], v[30:31], v[92:93]
	v_cvt_pk_bf16_f32 v16, v16, v17
	v_cvt_pk_bf16_f32 v17, v18, v19
	v_cvt_pk_bf16_f32 v20, v20, v21
	v_cvt_pk_bf16_f32 v21, v22, v23
	v_cvt_pk_bf16_f32 v24, v24, v25
	v_cvt_pk_bf16_f32 v25, v26, v27
	v_cvt_pk_bf16_f32 v28, v28, v29
	v_cvt_pk_bf16_f32 v29, v30, v31
	global_store_dwordx2 v67, v[16:17], s[6:7] offset:0
	global_store_dwordx2 v67, v[20:21], s[6:7] offset:512
	global_store_dwordx2 v67, v[24:25], s[6:7] offset:1024
	global_store_dwordx2 v67, v[28:29], s[6:7] offset:1536
	s_add_u32 s6, s6, 0x800
	s_addc_u32 s7, s7, 0
	global_load_dwordx4 v[16:19], v66, s[4:5] offset:0
	global_load_dwordx4 v[20:23], v66, s[4:5] offset:1024
	global_load_dwordx4 v[24:27], v66, s[4:5] offset:2048
	global_load_dwordx4 v[28:31], v66, s[4:5] offset:3072
	s_add_u32 s4, s4, 0x1000
	s_addc_u32 s5, s5, 0
	s_waitcnt vmcnt(16)
	v_pk_mul_f32 v[70:71], v[32:33], v[32:33]
	v_pk_mul_f32 v[72:73], v[34:35], v[34:35]
	v_pk_fma_f32 v[70:71], v[36:37], v[36:37], v[70:71]
	v_pk_fma_f32 v[72:73], v[38:39], v[38:39], v[72:73]
	v_pk_fma_f32 v[70:71], v[40:41], v[40:41], v[70:71]
	v_pk_fma_f32 v[72:73], v[42:43], v[42:43], v[72:73]
	v_pk_fma_f32 v[70:71], v[44:45], v[44:45], v[70:71]
	v_pk_fma_f32 v[72:73], v[46:47], v[46:47], v[72:73]
	s_nop 0
	v_pk_add_f32 v[70:71], v[70:71], v[72:73]
	s_nop 0
	v_add_f32_e32 v68, v70, v71
	s_nop 1
	v_add_f32_dpp v68, v68, v68 quad_perm:[1,0,3,2] row_mask:0xf bank_mask:0xf bound_ctrl:1
	s_nop 1
	v_add_f32_dpp v68, v68, v68 quad_perm:[2,3,0,1] row_mask:0xf bank_mask:0xf bound_ctrl:1
	s_nop 1
	v_add_f32_dpp v68, v68, v68 row_half_mirror row_mask:0xf bank_mask:0xf bound_ctrl:1
	s_nop 1
	v_add_f32_dpp v68, v68, v68 row_mirror row_mask:0xf bank_mask:0xf bound_ctrl:1
	s_nop 1
	v_add_f32_dpp v68, v68, v68 row_bcast:15 row_mask:0xa bank_mask:0xf
	s_nop 1
	v_add_f32_dpp v68, v68, v68 row_bcast:31 row_mask:0xc bank_mask:0xf
	s_nop 1
	v_readlane_b32 s1, v68, 63
	s_nop 3
	v_mov_b32_e32 v68, s1
	v_fmamk_f32 v68, v68, 0x3a800000, v74
	v_rsq_f32_e32 v68, v68
	s_nop 0
	v_pk_mul_f32 v[32:33], v[32:33], v[68:69] op_sel_hi:[1,0]
	v_pk_mul_f32 v[34:35], v[34:35], v[68:69] op_sel_hi:[1,0]
	v_pk_mul_f32 v[36:37], v[36:37], v[68:69] op_sel_hi:[1,0]
	v_pk_mul_f32 v[38:39], v[38:39], v[68:69] op_sel_hi:[1,0]
	v_pk_mul_f32 v[40:41], v[40:41], v[68:69] op_sel_hi:[1,0]
	v_pk_mul_f32 v[42:43], v[42:43], v[68:69] op_sel_hi:[1,0]
	v_pk_mul_f32 v[44:45], v[44:45], v[68:69] op_sel_hi:[1,0]
	v_pk_mul_f32 v[46:47], v[46:47], v[68:69] op_sel_hi:[1,0]
	v_pk_fma_f32 v[32:33], v[50:51], v[32:33], v[78:79]
	v_pk_fma_f32 v[34:35], v[52:53], v[34:35], v[80:81]
	v_pk_fma_f32 v[36:37], v[54:55], v[36:37], v[82:83]
	v_pk_fma_f32 v[38:39], v[56:57], v[38:39], v[84:85]
	v_pk_fma_f32 v[40:41], v[58:59], v[40:41], v[86:87]
	v_pk_fma_f32 v[42:43], v[60:61], v[42:43], v[88:89]
	v_pk_fma_f32 v[44:45], v[62:63], v[44:45], v[90:91]
	v_pk_fma_f32 v[46:47], v[64:65], v[46:47], v[92:93]
	v_cvt_pk_bf16_f32 v32, v32, v33
	v_cvt_pk_bf16_f32 v33, v34, v35
	v_cvt_pk_bf16_f32 v36, v36, v37
	v_cvt_pk_bf16_f32 v37, v38, v39
	v_cvt_pk_bf16_f32 v40, v40, v41
	v_cvt_pk_bf16_f32 v41, v42, v43
	v_cvt_pk_bf16_f32 v44, v44, v45
	v_cvt_pk_bf16_f32 v45, v46, v47
	global_store_dwordx2 v67, v[32:33], s[6:7] offset:0
	global_store_dwordx2 v67, v[36:37], s[6:7] offset:512
	global_store_dwordx2 v67, v[40:41], s[6:7] offset:1024
	global_store_dwordx2 v67, v[44:45], s[6:7] offset:1536
	s_add_u32 s6, s6, 0x800
	s_addc_u32 s7, s7, 0
	global_load_dwordx4 v[32:35], v66, s[4:5] offset:0
	global_load_dwordx4 v[36:39], v66, s[4:5] offset:1024
	global_load_dwordx4 v[40:43], v66, s[4:5] offset:2048
	global_load_dwordx4 v[44:47], v66, s[4:5] offset:3072
	s_add_u32 s4, s4, 0x1000
	s_addc_u32 s5, s5, 0
	s_waitcnt vmcnt(16)
	v_pk_mul_f32 v[70:71], v[0:1], v[0:1]
	v_pk_mul_f32 v[72:73], v[2:3], v[2:3]
	v_pk_fma_f32 v[70:71], v[4:5], v[4:5], v[70:71]
	v_pk_fma_f32 v[72:73], v[6:7], v[6:7], v[72:73]
	v_pk_fma_f32 v[70:71], v[8:9], v[8:9], v[70:71]
	v_pk_fma_f32 v[72:73], v[10:11], v[10:11], v[72:73]
	v_pk_fma_f32 v[70:71], v[12:13], v[12:13], v[70:71]
	v_pk_fma_f32 v[72:73], v[14:15], v[14:15], v[72:73]
	s_nop 0
	v_pk_add_f32 v[70:71], v[70:71], v[72:73]
	s_nop 0
	v_add_f32_e32 v68, v70, v71
	s_nop 1
	v_add_f32_dpp v68, v68, v68 quad_perm:[1,0,3,2] row_mask:0xf bank_mask:0xf bound_ctrl:1
	s_nop 1
	v_add_f32_dpp v68, v68, v68 quad_perm:[2,3,0,1] row_mask:0xf bank_mask:0xf bound_ctrl:1
	s_nop 1
	v_add_f32_dpp v68, v68, v68 row_half_mirror row_mask:0xf bank_mask:0xf bound_ctrl:1
	s_nop 1
	v_add_f32_dpp v68, v68, v68 row_mirror row_mask:0xf bank_mask:0xf bound_ctrl:1
	s_nop 1
	v_add_f32_dpp v68, v68, v68 row_bcast:15 row_mask:0xa bank_mask:0xf
	s_nop 1
	v_add_f32_dpp v68, v68, v68 row_bcast:31 row_mask:0xc bank_mask:0xf
	s_nop 1
	v_readlane_b32 s1, v68, 63
	s_nop 3
	v_mov_b32_e32 v68, s1
	v_fmamk_f32 v68, v68, 0x3a800000, v74
	v_rsq_f32_e32 v68, v68
	s_nop 0
	v_pk_mul_f32 v[0:1], v[0:1], v[68:69] op_sel_hi:[1,0]
	v_pk_mul_f32 v[2:3], v[2:3], v[68:69] op_sel_hi:[1,0]
	v_pk_mul_f32 v[4:5], v[4:5], v[68:69] op_sel_hi:[1,0]
	v_pk_mul_f32 v[6:7], v[6:7], v[68:69] op_sel_hi:[1,0]
	v_pk_mul_f32 v[8:9], v[8:9], v[68:69] op_sel_hi:[1,0]
	v_pk_mul_f32 v[10:11], v[10:11], v[68:69] op_sel_hi:[1,0]
	v_pk_mul_f32 v[12:13], v[12:13], v[68:69] op_sel_hi:[1,0]
	v_pk_mul_f32 v[14:15], v[14:15], v[68:69] op_sel_hi:[1,0]
	v_pk_fma_f32 v[0:1], v[50:51], v[0:1], v[78:79]
	v_pk_fma_f32 v[2:3], v[52:53], v[2:3], v[80:81]
	v_pk_fma_f32 v[4:5], v[54:55], v[4:5], v[82:83]
	v_pk_fma_f32 v[6:7], v[56:57], v[6:7], v[84:85]
	v_pk_fma_f32 v[8:9], v[58:59], v[8:9], v[86:87]
	v_pk_fma_f32 v[10:11], v[60:61], v[10:11], v[88:89]
	v_pk_fma_f32 v[12:13], v[62:63], v[12:13], v[90:91]
	v_pk_fma_f32 v[14:15], v[64:65], v[14:15], v[92:93]
	v_cvt_pk_bf16_f32 v0, v0, v1
	v_cvt_pk_bf16_f32 v1, v2, v3
	v_cvt_pk_bf16_f32 v4, v4, v5
	v_cvt_pk_bf16_f32 v5, v6, v7
	v_cvt_pk_bf16_f32 v8, v8, v9
	v_cvt_pk_bf16_f32 v9, v10, v11
	v_cvt_pk_bf16_f32 v12, v12, v13
	v_cvt_pk_bf16_f32 v13, v14, v15
	global_store_dwordx2 v67, v[0:1], s[6:7] offset:0
	global_store_dwordx2 v67, v[4:5], s[6:7] offset:512
	global_store_dwordx2 v67, v[8:9], s[6:7] offset:1024
	global_store_dwordx2 v67, v[12:13], s[6:7] offset:1536
	s_add_u32 s6, s6, 0x800
	s_addc_u32 s7, s7, 0
	global_load_dwordx4 v[0:3], v66, s[4:5] offset:0
	global_load_dwordx4 v[4:7], v66, s[4:5] offset:1024
	global_load_dwordx4 v[8:11], v66, s[4:5] offset:2048
	global_load_dwordx4 v[12:15], v66, s[4:5] offset:3072
	s_add_u32 s4, s4, 0x1000
	s_addc_u32 s5, s5, 0
	s_waitcnt vmcnt(16)
	v_pk_mul_f32 v[70:71], v[16:17], v[16:17]
	v_pk_mul_f32 v[72:73], v[18:19], v[18:19]
	v_pk_fma_f32 v[70:71], v[20:21], v[20:21], v[70:71]
	v_pk_fma_f32 v[72:73], v[22:23], v[22:23], v[72:73]
	v_pk_fma_f32 v[70:71], v[24:25], v[24:25], v[70:71]
	v_pk_fma_f32 v[72:73], v[26:27], v[26:27], v[72:73]
	v_pk_fma_f32 v[70:71], v[28:29], v[28:29], v[70:71]
	v_pk_fma_f32 v[72:73], v[30:31], v[30:31], v[72:73]
	s_nop 0
	v_pk_add_f32 v[70:71], v[70:71], v[72:73]
	s_nop 0
	v_add_f32_e32 v68, v70, v71
	s_nop 1
	v_add_f32_dpp v68, v68, v68 quad_perm:[1,0,3,2] row_mask:0xf bank_mask:0xf bound_ctrl:1
	s_nop 1
	v_add_f32_dpp v68, v68, v68 quad_perm:[2,3,0,1] row_mask:0xf bank_mask:0xf bound_ctrl:1
	s_nop 1
	v_add_f32_dpp v68, v68, v68 row_half_mirror row_mask:0xf bank_mask:0xf bound_ctrl:1
	s_nop 1
	v_add_f32_dpp v68, v68, v68 row_mirror row_mask:0xf bank_mask:0xf bound_ctrl:1
	s_nop 1
	v_add_f32_dpp v68, v68, v68 row_bcast:15 row_mask:0xa bank_mask:0xf
	s_nop 1
	v_add_f32_dpp v68, v68, v68 row_bcast:31 row_mask:0xc bank_mask:0xf
	s_nop 1
	v_readlane_b32 s1, v68, 63
	s_nop 3
	v_mov_b32_e32 v68, s1
	v_fmamk_f32 v68, v68, 0x3a800000, v74
	v_rsq_f32_e32 v68, v68
	s_nop 0
	v_pk_mul_f32 v[16:17], v[16:17], v[68:69] op_sel_hi:[1,0]
	v_pk_mul_f32 v[18:19], v[18:19], v[68:69] op_sel_hi:[1,0]
	v_pk_mul_f32 v[20:21], v[20:21], v[68:69] op_sel_hi:[1,0]
	v_pk_mul_f32 v[22:23], v[22:23], v[68:69] op_sel_hi:[1,0]
	v_pk_mul_f32 v[24:25], v[24:25], v[68:69] op_sel_hi:[1,0]
	v_pk_mul_f32 v[26:27], v[26:27], v[68:69] op_sel_hi:[1,0]
	v_pk_mul_f32 v[28:29], v[28:29], v[68:69] op_sel_hi:[1,0]
	v_pk_mul_f32 v[30:31], v[30:31], v[68:69] op_sel_hi:[1,0]
	v_pk_fma_f32 v[16:17], v[50:51], v[16:17], v[78:79]
	v_pk_fma_f32 v[18:19], v[52:53], v[18:19], v[80:81]
	v_pk_fma_f32 v[20:21], v[54:55], v[20:21], v[82:83]
	v_pk_fma_f32 v[22:23], v[56:57], v[22:23], v[84:85]
	v_pk_fma_f32 v[24:25], v[58:59], v[24:25], v[86:87]
	v_pk_fma_f32 v[26:27], v[60:61], v[26:27], v[88:89]
	v_pk_fma_f32 v[28:29], v[62:63], v[28:29], v[90:91]
	v_pk_fma_f32 v[30:31], v[64:65], v[30:31], v[92:93]
	v_cvt_pk_bf16_f32 v16, v16, v17
	v_cvt_pk_bf16_f32 v17, v18, v19
	v_cvt_pk_bf16_f32 v20, v20, v21
	v_cvt_pk_bf16_f32 v21, v22, v23
	v_cvt_pk_bf16_f32 v24, v24, v25
	v_cvt_pk_bf16_f32 v25, v26, v27
	v_cvt_pk_bf16_f32 v28, v28, v29
	v_cvt_pk_bf16_f32 v29, v30, v31
	global_store_dwordx2 v67, v[16:17], s[6:7] offset:0
	global_store_dwordx2 v67, v[20:21], s[6:7] offset:512
	global_store_dwordx2 v67, v[24:25], s[6:7] offset:1024
	global_store_dwordx2 v67, v[28:29], s[6:7] offset:1536
	s_add_u32 s6, s6, 0x800
	s_addc_u32 s7, s7, 0
	global_load_dwordx4 v[16:19], v66, s[4:5] offset:0
	global_load_dwordx4 v[20:23], v66, s[4:5] offset:1024
	global_load_dwordx4 v[24:27], v66, s[4:5] offset:2048
	global_load_dwordx4 v[28:31], v66, s[4:5] offset:3072
	s_add_u32 s4, s4, 0x1000
	s_addc_u32 s5, s5, 0
	s_waitcnt vmcnt(16)
	v_pk_mul_f32 v[70:71], v[32:33], v[32:33]
	v_pk_mul_f32 v[72:73], v[34:35], v[34:35]
	v_pk_fma_f32 v[70:71], v[36:37], v[36:37], v[70:71]
	v_pk_fma_f32 v[72:73], v[38:39], v[38:39], v[72:73]
	v_pk_fma_f32 v[70:71], v[40:41], v[40:41], v[70:71]
	v_pk_fma_f32 v[72:73], v[42:43], v[42:43], v[72:73]
	v_pk_fma_f32 v[70:71], v[44:45], v[44:45], v[70:71]
	v_pk_fma_f32 v[72:73], v[46:47], v[46:47], v[72:73]
	s_nop 0
	v_pk_add_f32 v[70:71], v[70:71], v[72:73]
	s_nop 0
	v_add_f32_e32 v68, v70, v71
	s_nop 1
	v_add_f32_dpp v68, v68, v68 quad_perm:[1,0,3,2] row_mask:0xf bank_mask:0xf bound_ctrl:1
	s_nop 1
	v_add_f32_dpp v68, v68, v68 quad_perm:[2,3,0,1] row_mask:0xf bank_mask:0xf bound_ctrl:1
	s_nop 1
	v_add_f32_dpp v68, v68, v68 row_half_mirror row_mask:0xf bank_mask:0xf bound_ctrl:1
	s_nop 1
	v_add_f32_dpp v68, v68, v68 row_mirror row_mask:0xf bank_mask:0xf bound_ctrl:1
	s_nop 1
	v_add_f32_dpp v68, v68, v68 row_bcast:15 row_mask:0xa bank_mask:0xf
	s_nop 1
	v_add_f32_dpp v68, v68, v68 row_bcast:31 row_mask:0xc bank_mask:0xf
	s_nop 1
	v_readlane_b32 s1, v68, 63
	s_nop 3
	v_mov_b32_e32 v68, s1
	v_fmamk_f32 v68, v68, 0x3a800000, v74
	v_rsq_f32_e32 v68, v68
	s_nop 0
	v_pk_mul_f32 v[32:33], v[32:33], v[68:69] op_sel_hi:[1,0]
	v_pk_mul_f32 v[34:35], v[34:35], v[68:69] op_sel_hi:[1,0]
	v_pk_mul_f32 v[36:37], v[36:37], v[68:69] op_sel_hi:[1,0]
	v_pk_mul_f32 v[38:39], v[38:39], v[68:69] op_sel_hi:[1,0]
	v_pk_mul_f32 v[40:41], v[40:41], v[68:69] op_sel_hi:[1,0]
	v_pk_mul_f32 v[42:43], v[42:43], v[68:69] op_sel_hi:[1,0]
	v_pk_mul_f32 v[44:45], v[44:45], v[68:69] op_sel_hi:[1,0]
	v_pk_mul_f32 v[46:47], v[46:47], v[68:69] op_sel_hi:[1,0]
	v_pk_fma_f32 v[32:33], v[50:51], v[32:33], v[78:79]
	v_pk_fma_f32 v[34:35], v[52:53], v[34:35], v[80:81]
	v_pk_fma_f32 v[36:37], v[54:55], v[36:37], v[82:83]
	v_pk_fma_f32 v[38:39], v[56:57], v[38:39], v[84:85]
	v_pk_fma_f32 v[40:41], v[58:59], v[40:41], v[86:87]
	v_pk_fma_f32 v[42:43], v[60:61], v[42:43], v[88:89]
	v_pk_fma_f32 v[44:45], v[62:63], v[44:45], v[90:91]
	v_pk_fma_f32 v[46:47], v[64:65], v[46:47], v[92:93]
	v_cvt_pk_bf16_f32 v32, v32, v33
	v_cvt_pk_bf16_f32 v33, v34, v35
	v_cvt_pk_bf16_f32 v36, v36, v37
	v_cvt_pk_bf16_f32 v37, v38, v39
	v_cvt_pk_bf16_f32 v40, v40, v41
	v_cvt_pk_bf16_f32 v41, v42, v43
	v_cvt_pk_bf16_f32 v44, v44, v45
	v_cvt_pk_bf16_f32 v45, v46, v47
	global_store_dwordx2 v67, v[32:33], s[6:7] offset:0
	global_store_dwordx2 v67, v[36:37], s[6:7] offset:512
	global_store_dwordx2 v67, v[40:41], s[6:7] offset:1024
	global_store_dwordx2 v67, v[44:45], s[6:7] offset:1536
	s_add_u32 s6, s6, 0x800
	s_addc_u32 s7, s7, 0
	global_load_dwordx4 v[32:35], v66, s[4:5] offset:0
	global_load_dwordx4 v[36:39], v66, s[4:5] offset:1024
	global_load_dwordx4 v[40:43], v66, s[4:5] offset:2048
	global_load_dwordx4 v[44:47], v66, s[4:5] offset:3072
	s_add_u32 s4, s4, 0x1000
	s_addc_u32 s5, s5, 0
	s_waitcnt vmcnt(16)
	v_pk_mul_f32 v[70:71], v[0:1], v[0:1]
	v_pk_mul_f32 v[72:73], v[2:3], v[2:3]
	v_pk_fma_f32 v[70:71], v[4:5], v[4:5], v[70:71]
	v_pk_fma_f32 v[72:73], v[6:7], v[6:7], v[72:73]
	v_pk_fma_f32 v[70:71], v[8:9], v[8:9], v[70:71]
	v_pk_fma_f32 v[72:73], v[10:11], v[10:11], v[72:73]
	v_pk_fma_f32 v[70:71], v[12:13], v[12:13], v[70:71]
	v_pk_fma_f32 v[72:73], v[14:15], v[14:15], v[72:73]
	s_nop 0
	v_pk_add_f32 v[70:71], v[70:71], v[72:73]
	s_nop 0
	v_add_f32_e32 v68, v70, v71
	s_nop 1
	v_add_f32_dpp v68, v68, v68 quad_perm:[1,0,3,2] row_mask:0xf bank_mask:0xf bound_ctrl:1
	s_nop 1
	v_add_f32_dpp v68, v68, v68 quad_perm:[2,3,0,1] row_mask:0xf bank_mask:0xf bound_ctrl:1
	s_nop 1
	v_add_f32_dpp v68, v68, v68 row_half_mirror row_mask:0xf bank_mask:0xf bound_ctrl:1
	s_nop 1
	v_add_f32_dpp v68, v68, v68 row_mirror row_mask:0xf bank_mask:0xf bound_ctrl:1
	s_nop 1
	v_add_f32_dpp v68, v68, v68 row_bcast:15 row_mask:0xa bank_mask:0xf
	s_nop 1
	v_add_f32_dpp v68, v68, v68 row_bcast:31 row_mask:0xc bank_mask:0xf
	s_nop 1
	v_readlane_b32 s1, v68, 63
	s_nop 3
	v_mov_b32_e32 v68, s1
	v_fmamk_f32 v68, v68, 0x3a800000, v74
	v_rsq_f32_e32 v68, v68
	s_nop 0
	v_pk_mul_f32 v[0:1], v[0:1], v[68:69] op_sel_hi:[1,0]
	v_pk_mul_f32 v[2:3], v[2:3], v[68:69] op_sel_hi:[1,0]
	v_pk_mul_f32 v[4:5], v[4:5], v[68:69] op_sel_hi:[1,0]
	v_pk_mul_f32 v[6:7], v[6:7], v[68:69] op_sel_hi:[1,0]
	v_pk_mul_f32 v[8:9], v[8:9], v[68:69] op_sel_hi:[1,0]
	v_pk_mul_f32 v[10:11], v[10:11], v[68:69] op_sel_hi:[1,0]
	v_pk_mul_f32 v[12:13], v[12:13], v[68:69] op_sel_hi:[1,0]
	v_pk_mul_f32 v[14:15], v[14:15], v[68:69] op_sel_hi:[1,0]
	v_pk_fma_f32 v[0:1], v[50:51], v[0:1], v[78:79]
	v_pk_fma_f32 v[2:3], v[52:53], v[2:3], v[80:81]
	v_pk_fma_f32 v[4:5], v[54:55], v[4:5], v[82:83]
	v_pk_fma_f32 v[6:7], v[56:57], v[6:7], v[84:85]
	v_pk_fma_f32 v[8:9], v[58:59], v[8:9], v[86:87]
	v_pk_fma_f32 v[10:11], v[60:61], v[10:11], v[88:89]
	v_pk_fma_f32 v[12:13], v[62:63], v[12:13], v[90:91]
	v_pk_fma_f32 v[14:15], v[64:65], v[14:15], v[92:93]
	v_cvt_pk_bf16_f32 v0, v0, v1
	v_cvt_pk_bf16_f32 v1, v2, v3
	v_cvt_pk_bf16_f32 v4, v4, v5
	v_cvt_pk_bf16_f32 v5, v6, v7
	v_cvt_pk_bf16_f32 v8, v8, v9
	v_cvt_pk_bf16_f32 v9, v10, v11
	v_cvt_pk_bf16_f32 v12, v12, v13
	v_cvt_pk_bf16_f32 v13, v14, v15
	global_store_dwordx2 v67, v[0:1], s[6:7] offset:0
	global_store_dwordx2 v67, v[4:5], s[6:7] offset:512
	global_store_dwordx2 v67, v[8:9], s[6:7] offset:1024
	global_store_dwordx2 v67, v[12:13], s[6:7] offset:1536
	s_add_u32 s6, s6, 0x800
	s_addc_u32 s7, s7, 0
	global_load_dwordx4 v[0:3], v66, s[4:5] offset:0
	global_load_dwordx4 v[4:7], v66, s[4:5] offset:1024
	global_load_dwordx4 v[8:11], v66, s[4:5] offset:2048
	global_load_dwordx4 v[12:15], v66, s[4:5] offset:3072
	s_add_u32 s4, s4, 0x1000
	s_addc_u32 s5, s5, 0
	s_waitcnt vmcnt(16)
	v_pk_mul_f32 v[70:71], v[16:17], v[16:17]
	v_pk_mul_f32 v[72:73], v[18:19], v[18:19]
	v_pk_fma_f32 v[70:71], v[20:21], v[20:21], v[70:71]
	v_pk_fma_f32 v[72:73], v[22:23], v[22:23], v[72:73]
	v_pk_fma_f32 v[70:71], v[24:25], v[24:25], v[70:71]
	v_pk_fma_f32 v[72:73], v[26:27], v[26:27], v[72:73]
	v_pk_fma_f32 v[70:71], v[28:29], v[28:29], v[70:71]
	v_pk_fma_f32 v[72:73], v[30:31], v[30:31], v[72:73]
	s_nop 0
	v_pk_add_f32 v[70:71], v[70:71], v[72:73]
	s_nop 0
	v_add_f32_e32 v68, v70, v71
	s_nop 1
	v_add_f32_dpp v68, v68, v68 quad_perm:[1,0,3,2] row_mask:0xf bank_mask:0xf bound_ctrl:1
	s_nop 1
	v_add_f32_dpp v68, v68, v68 quad_perm:[2,3,0,1] row_mask:0xf bank_mask:0xf bound_ctrl:1
	s_nop 1
	v_add_f32_dpp v68, v68, v68 row_half_mirror row_mask:0xf bank_mask:0xf bound_ctrl:1
	s_nop 1
	v_add_f32_dpp v68, v68, v68 row_mirror row_mask:0xf bank_mask:0xf bound_ctrl:1
	s_nop 1
	v_add_f32_dpp v68, v68, v68 row_bcast:15 row_mask:0xa bank_mask:0xf
	s_nop 1
	v_add_f32_dpp v68, v68, v68 row_bcast:31 row_mask:0xc bank_mask:0xf
	s_nop 1
	v_readlane_b32 s1, v68, 63
	s_nop 3
	v_mov_b32_e32 v68, s1
	v_fmamk_f32 v68, v68, 0x3a800000, v74
	v_rsq_f32_e32 v68, v68
	s_nop 0
	v_pk_mul_f32 v[16:17], v[16:17], v[68:69] op_sel_hi:[1,0]
	v_pk_mul_f32 v[18:19], v[18:19], v[68:69] op_sel_hi:[1,0]
	v_pk_mul_f32 v[20:21], v[20:21], v[68:69] op_sel_hi:[1,0]
	v_pk_mul_f32 v[22:23], v[22:23], v[68:69] op_sel_hi:[1,0]
	v_pk_mul_f32 v[24:25], v[24:25], v[68:69] op_sel_hi:[1,0]
	v_pk_mul_f32 v[26:27], v[26:27], v[68:69] op_sel_hi:[1,0]
	v_pk_mul_f32 v[28:29], v[28:29], v[68:69] op_sel_hi:[1,0]
	v_pk_mul_f32 v[30:31], v[30:31], v[68:69] op_sel_hi:[1,0]
	v_pk_fma_f32 v[16:17], v[50:51], v[16:17], v[78:79]
	v_pk_fma_f32 v[18:19], v[52:53], v[18:19], v[80:81]
	v_pk_fma_f32 v[20:21], v[54:55], v[20:21], v[82:83]
	v_pk_fma_f32 v[22:23], v[56:57], v[22:23], v[84:85]
	v_pk_fma_f32 v[24:25], v[58:59], v[24:25], v[86:87]
	v_pk_fma_f32 v[26:27], v[60:61], v[26:27], v[88:89]
	v_pk_fma_f32 v[28:29], v[62:63], v[28:29], v[90:91]
	v_pk_fma_f32 v[30:31], v[64:65], v[30:31], v[92:93]
	v_cvt_pk_bf16_f32 v16, v16, v17
	v_cvt_pk_bf16_f32 v17, v18, v19
	v_cvt_pk_bf16_f32 v20, v20, v21
	v_cvt_pk_bf16_f32 v21, v22, v23
	v_cvt_pk_bf16_f32 v24, v24, v25
	v_cvt_pk_bf16_f32 v25, v26, v27
	v_cvt_pk_bf16_f32 v28, v28, v29
	v_cvt_pk_bf16_f32 v29, v30, v31
	global_store_dwordx2 v67, v[16:17], s[6:7] offset:0
	global_store_dwordx2 v67, v[20:21], s[6:7] offset:512
	global_store_dwordx2 v67, v[24:25], s[6:7] offset:1024
	global_store_dwordx2 v67, v[28:29], s[6:7] offset:1536
	s_add_u32 s6, s6, 0x800
	s_addc_u32 s7, s7, 0
	global_load_dwordx4 v[16:19], v66, s[4:5] offset:0
	global_load_dwordx4 v[20:23], v66, s[4:5] offset:1024
	global_load_dwordx4 v[24:27], v66, s[4:5] offset:2048
	global_load_dwordx4 v[28:31], v66, s[4:5] offset:3072
	s_add_u32 s4, s4, 0x1000
	s_addc_u32 s5, s5, 0
	s_waitcnt vmcnt(16)
	v_pk_mul_f32 v[70:71], v[32:33], v[32:33]
	v_pk_mul_f32 v[72:73], v[34:35], v[34:35]
	v_pk_fma_f32 v[70:71], v[36:37], v[36:37], v[70:71]
	v_pk_fma_f32 v[72:73], v[38:39], v[38:39], v[72:73]
	v_pk_fma_f32 v[70:71], v[40:41], v[40:41], v[70:71]
	v_pk_fma_f32 v[72:73], v[42:43], v[42:43], v[72:73]
	v_pk_fma_f32 v[70:71], v[44:45], v[44:45], v[70:71]
	v_pk_fma_f32 v[72:73], v[46:47], v[46:47], v[72:73]
	s_nop 0
	v_pk_add_f32 v[70:71], v[70:71], v[72:73]
	s_nop 0
	v_add_f32_e32 v68, v70, v71
	s_nop 1
	v_add_f32_dpp v68, v68, v68 quad_perm:[1,0,3,2] row_mask:0xf bank_mask:0xf bound_ctrl:1
	s_nop 1
	v_add_f32_dpp v68, v68, v68 quad_perm:[2,3,0,1] row_mask:0xf bank_mask:0xf bound_ctrl:1
	s_nop 1
	v_add_f32_dpp v68, v68, v68 row_half_mirror row_mask:0xf bank_mask:0xf bound_ctrl:1
	s_nop 1
	v_add_f32_dpp v68, v68, v68 row_mirror row_mask:0xf bank_mask:0xf bound_ctrl:1
	s_nop 1
	v_add_f32_dpp v68, v68, v68 row_bcast:15 row_mask:0xa bank_mask:0xf
	s_nop 1
	v_add_f32_dpp v68, v68, v68 row_bcast:31 row_mask:0xc bank_mask:0xf
	s_nop 1
	v_readlane_b32 s1, v68, 63
	s_nop 3
	v_mov_b32_e32 v68, s1
	v_fmamk_f32 v68, v68, 0x3a800000, v74
	v_rsq_f32_e32 v68, v68
	s_nop 0
	v_pk_mul_f32 v[32:33], v[32:33], v[68:69] op_sel_hi:[1,0]
	v_pk_mul_f32 v[34:35], v[34:35], v[68:69] op_sel_hi:[1,0]
	v_pk_mul_f32 v[36:37], v[36:37], v[68:69] op_sel_hi:[1,0]
	v_pk_mul_f32 v[38:39], v[38:39], v[68:69] op_sel_hi:[1,0]
	v_pk_mul_f32 v[40:41], v[40:41], v[68:69] op_sel_hi:[1,0]
	v_pk_mul_f32 v[42:43], v[42:43], v[68:69] op_sel_hi:[1,0]
	v_pk_mul_f32 v[44:45], v[44:45], v[68:69] op_sel_hi:[1,0]
	v_pk_mul_f32 v[46:47], v[46:47], v[68:69] op_sel_hi:[1,0]
	v_pk_fma_f32 v[32:33], v[50:51], v[32:33], v[78:79]
	v_pk_fma_f32 v[34:35], v[52:53], v[34:35], v[80:81]
	v_pk_fma_f32 v[36:37], v[54:55], v[36:37], v[82:83]
	v_pk_fma_f32 v[38:39], v[56:57], v[38:39], v[84:85]
	v_pk_fma_f32 v[40:41], v[58:59], v[40:41], v[86:87]
	v_pk_fma_f32 v[42:43], v[60:61], v[42:43], v[88:89]
	v_pk_fma_f32 v[44:45], v[62:63], v[44:45], v[90:91]
	v_pk_fma_f32 v[46:47], v[64:65], v[46:47], v[92:93]
	v_cvt_pk_bf16_f32 v32, v32, v33
	v_cvt_pk_bf16_f32 v33, v34, v35
	v_cvt_pk_bf16_f32 v36, v36, v37
	v_cvt_pk_bf16_f32 v37, v38, v39
	v_cvt_pk_bf16_f32 v40, v40, v41
	v_cvt_pk_bf16_f32 v41, v42, v43
	v_cvt_pk_bf16_f32 v44, v44, v45
	v_cvt_pk_bf16_f32 v45, v46, v47
	global_store_dwordx2 v67, v[32:33], s[6:7] offset:0
	global_store_dwordx2 v67, v[36:37], s[6:7] offset:512
	global_store_dwordx2 v67, v[40:41], s[6:7] offset:1024
	global_store_dwordx2 v67, v[44:45], s[6:7] offset:1536
	s_add_u32 s6, s6, 0x800
	s_addc_u32 s7, s7, 0
	global_load_dwordx4 v[32:35], v66, s[4:5] offset:0
	global_load_dwordx4 v[36:39], v66, s[4:5] offset:1024
	global_load_dwordx4 v[40:43], v66, s[4:5] offset:2048
	global_load_dwordx4 v[44:47], v66, s[4:5] offset:3072
	s_add_u32 s4, s4, 0x1000
	s_addc_u32 s5, s5, 0
	s_waitcnt vmcnt(16)
	v_pk_mul_f32 v[70:71], v[0:1], v[0:1]
	v_pk_mul_f32 v[72:73], v[2:3], v[2:3]
	v_pk_fma_f32 v[70:71], v[4:5], v[4:5], v[70:71]
	v_pk_fma_f32 v[72:73], v[6:7], v[6:7], v[72:73]
	v_pk_fma_f32 v[70:71], v[8:9], v[8:9], v[70:71]
	v_pk_fma_f32 v[72:73], v[10:11], v[10:11], v[72:73]
	v_pk_fma_f32 v[70:71], v[12:13], v[12:13], v[70:71]
	v_pk_fma_f32 v[72:73], v[14:15], v[14:15], v[72:73]
	s_nop 0
	v_pk_add_f32 v[70:71], v[70:71], v[72:73]
	s_nop 0
	v_add_f32_e32 v68, v70, v71
	s_nop 1
	v_add_f32_dpp v68, v68, v68 quad_perm:[1,0,3,2] row_mask:0xf bank_mask:0xf bound_ctrl:1
	s_nop 1
	v_add_f32_dpp v68, v68, v68 quad_perm:[2,3,0,1] row_mask:0xf bank_mask:0xf bound_ctrl:1
	s_nop 1
	v_add_f32_dpp v68, v68, v68 row_half_mirror row_mask:0xf bank_mask:0xf bound_ctrl:1
	s_nop 1
	v_add_f32_dpp v68, v68, v68 row_mirror row_mask:0xf bank_mask:0xf bound_ctrl:1
	s_nop 1
	v_add_f32_dpp v68, v68, v68 row_bcast:15 row_mask:0xa bank_mask:0xf
	s_nop 1
	v_add_f32_dpp v68, v68, v68 row_bcast:31 row_mask:0xc bank_mask:0xf
	s_nop 1
	v_readlane_b32 s1, v68, 63
	s_nop 3
	v_mov_b32_e32 v68, s1
	v_fmamk_f32 v68, v68, 0x3a800000, v74
	v_rsq_f32_e32 v68, v68
	s_nop 0
	v_pk_mul_f32 v[0:1], v[0:1], v[68:69] op_sel_hi:[1,0]
	v_pk_mul_f32 v[2:3], v[2:3], v[68:69] op_sel_hi:[1,0]
	v_pk_mul_f32 v[4:5], v[4:5], v[68:69] op_sel_hi:[1,0]
	v_pk_mul_f32 v[6:7], v[6:7], v[68:69] op_sel_hi:[1,0]
	v_pk_mul_f32 v[8:9], v[8:9], v[68:69] op_sel_hi:[1,0]
	v_pk_mul_f32 v[10:11], v[10:11], v[68:69] op_sel_hi:[1,0]
	v_pk_mul_f32 v[12:13], v[12:13], v[68:69] op_sel_hi:[1,0]
	v_pk_mul_f32 v[14:15], v[14:15], v[68:69] op_sel_hi:[1,0]
	v_pk_fma_f32 v[0:1], v[50:51], v[0:1], v[78:79]
	v_pk_fma_f32 v[2:3], v[52:53], v[2:3], v[80:81]
	v_pk_fma_f32 v[4:5], v[54:55], v[4:5], v[82:83]
	v_pk_fma_f32 v[6:7], v[56:57], v[6:7], v[84:85]
	v_pk_fma_f32 v[8:9], v[58:59], v[8:9], v[86:87]
	v_pk_fma_f32 v[10:11], v[60:61], v[10:11], v[88:89]
	v_pk_fma_f32 v[12:13], v[62:63], v[12:13], v[90:91]
	v_pk_fma_f32 v[14:15], v[64:65], v[14:15], v[92:93]
	v_cvt_pk_bf16_f32 v0, v0, v1
	v_cvt_pk_bf16_f32 v1, v2, v3
	v_cvt_pk_bf16_f32 v4, v4, v5
	v_cvt_pk_bf16_f32 v5, v6, v7
	v_cvt_pk_bf16_f32 v8, v8, v9
	v_cvt_pk_bf16_f32 v9, v10, v11
	v_cvt_pk_bf16_f32 v12, v12, v13
	v_cvt_pk_bf16_f32 v13, v14, v15
	global_store_dwordx2 v67, v[0:1], s[6:7] offset:0
	global_store_dwordx2 v67, v[4:5], s[6:7] offset:512
	global_store_dwordx2 v67, v[8:9], s[6:7] offset:1024
	global_store_dwordx2 v67, v[12:13], s[6:7] offset:1536
	s_add_u32 s6, s6, 0x800
	s_addc_u32 s7, s7, 0
	global_load_dwordx4 v[0:3], v66, s[4:5] offset:0
	global_load_dwordx4 v[4:7], v66, s[4:5] offset:1024
	global_load_dwordx4 v[8:11], v66, s[4:5] offset:2048
	global_load_dwordx4 v[12:15], v66, s[4:5] offset:3072
	s_add_u32 s4, s4, 0x1000
	s_addc_u32 s5, s5, 0
	s_waitcnt vmcnt(16)
	v_pk_mul_f32 v[70:71], v[16:17], v[16:17]
	v_pk_mul_f32 v[72:73], v[18:19], v[18:19]
	v_pk_fma_f32 v[70:71], v[20:21], v[20:21], v[70:71]
	v_pk_fma_f32 v[72:73], v[22:23], v[22:23], v[72:73]
	v_pk_fma_f32 v[70:71], v[24:25], v[24:25], v[70:71]
	v_pk_fma_f32 v[72:73], v[26:27], v[26:27], v[72:73]
	v_pk_fma_f32 v[70:71], v[28:29], v[28:29], v[70:71]
	v_pk_fma_f32 v[72:73], v[30:31], v[30:31], v[72:73]
	s_nop 0
	v_pk_add_f32 v[70:71], v[70:71], v[72:73]
	s_nop 0
	v_add_f32_e32 v68, v70, v71
	s_nop 1
	v_add_f32_dpp v68, v68, v68 quad_perm:[1,0,3,2] row_mask:0xf bank_mask:0xf bound_ctrl:1
	s_nop 1
	v_add_f32_dpp v68, v68, v68 quad_perm:[2,3,0,1] row_mask:0xf bank_mask:0xf bound_ctrl:1
	s_nop 1
	v_add_f32_dpp v68, v68, v68 row_half_mirror row_mask:0xf bank_mask:0xf bound_ctrl:1
	s_nop 1
	v_add_f32_dpp v68, v68, v68 row_mirror row_mask:0xf bank_mask:0xf bound_ctrl:1
	s_nop 1
	v_add_f32_dpp v68, v68, v68 row_bcast:15 row_mask:0xa bank_mask:0xf
	s_nop 1
	v_add_f32_dpp v68, v68, v68 row_bcast:31 row_mask:0xc bank_mask:0xf
	s_nop 1
	v_readlane_b32 s1, v68, 63
	s_nop 3
	v_mov_b32_e32 v68, s1
	v_fmamk_f32 v68, v68, 0x3a800000, v74
	v_rsq_f32_e32 v68, v68
	s_nop 0
	v_pk_mul_f32 v[16:17], v[16:17], v[68:69] op_sel_hi:[1,0]
	v_pk_mul_f32 v[18:19], v[18:19], v[68:69] op_sel_hi:[1,0]
	v_pk_mul_f32 v[20:21], v[20:21], v[68:69] op_sel_hi:[1,0]
	v_pk_mul_f32 v[22:23], v[22:23], v[68:69] op_sel_hi:[1,0]
	v_pk_mul_f32 v[24:25], v[24:25], v[68:69] op_sel_hi:[1,0]
	v_pk_mul_f32 v[26:27], v[26:27], v[68:69] op_sel_hi:[1,0]
	v_pk_mul_f32 v[28:29], v[28:29], v[68:69] op_sel_hi:[1,0]
	v_pk_mul_f32 v[30:31], v[30:31], v[68:69] op_sel_hi:[1,0]
	v_pk_fma_f32 v[16:17], v[50:51], v[16:17], v[78:79]
	v_pk_fma_f32 v[18:19], v[52:53], v[18:19], v[80:81]
	v_pk_fma_f32 v[20:21], v[54:55], v[20:21], v[82:83]
	v_pk_fma_f32 v[22:23], v[56:57], v[22:23], v[84:85]
	v_pk_fma_f32 v[24:25], v[58:59], v[24:25], v[86:87]
	v_pk_fma_f32 v[26:27], v[60:61], v[26:27], v[88:89]
	v_pk_fma_f32 v[28:29], v[62:63], v[28:29], v[90:91]
	v_pk_fma_f32 v[30:31], v[64:65], v[30:31], v[92:93]
	v_cvt_pk_bf16_f32 v16, v16, v17
	v_cvt_pk_bf16_f32 v17, v18, v19
	v_cvt_pk_bf16_f32 v20, v20, v21
	v_cvt_pk_bf16_f32 v21, v22, v23
	v_cvt_pk_bf16_f32 v24, v24, v25
	v_cvt_pk_bf16_f32 v25, v26, v27
	v_cvt_pk_bf16_f32 v28, v28, v29
	v_cvt_pk_bf16_f32 v29, v30, v31
	global_store_dwordx2 v67, v[16:17], s[6:7] offset:0
	global_store_dwordx2 v67, v[20:21], s[6:7] offset:512
	global_store_dwordx2 v67, v[24:25], s[6:7] offset:1024
	global_store_dwordx2 v67, v[28:29], s[6:7] offset:1536
	s_add_u32 s6, s6, 0x800
	s_addc_u32 s7, s7, 0
	s_waitcnt vmcnt(12)
	v_pk_mul_f32 v[70:71], v[32:33], v[32:33]
	v_pk_mul_f32 v[72:73], v[34:35], v[34:35]
	v_pk_fma_f32 v[70:71], v[36:37], v[36:37], v[70:71]
	v_pk_fma_f32 v[72:73], v[38:39], v[38:39], v[72:73]
	v_pk_fma_f32 v[70:71], v[40:41], v[40:41], v[70:71]
	v_pk_fma_f32 v[72:73], v[42:43], v[42:43], v[72:73]
	v_pk_fma_f32 v[70:71], v[44:45], v[44:45], v[70:71]
	v_pk_fma_f32 v[72:73], v[46:47], v[46:47], v[72:73]
	s_nop 0
	v_pk_add_f32 v[70:71], v[70:71], v[72:73]
	s_nop 0
	v_add_f32_e32 v68, v70, v71
	s_nop 1
	v_add_f32_dpp v68, v68, v68 quad_perm:[1,0,3,2] row_mask:0xf bank_mask:0xf bound_ctrl:1
	s_nop 1
	v_add_f32_dpp v68, v68, v68 quad_perm:[2,3,0,1] row_mask:0xf bank_mask:0xf bound_ctrl:1
	s_nop 1
	v_add_f32_dpp v68, v68, v68 row_half_mirror row_mask:0xf bank_mask:0xf bound_ctrl:1
	s_nop 1
	v_add_f32_dpp v68, v68, v68 row_mirror row_mask:0xf bank_mask:0xf bound_ctrl:1
	s_nop 1
	v_add_f32_dpp v68, v68, v68 row_bcast:15 row_mask:0xa bank_mask:0xf
	s_nop 1
	v_add_f32_dpp v68, v68, v68 row_bcast:31 row_mask:0xc bank_mask:0xf
	s_nop 1
	v_readlane_b32 s1, v68, 63
	s_nop 3
	v_mov_b32_e32 v68, s1
	v_fmamk_f32 v68, v68, 0x3a800000, v74
	v_rsq_f32_e32 v68, v68
	s_nop 0
	v_pk_mul_f32 v[32:33], v[32:33], v[68:69] op_sel_hi:[1,0]
	v_pk_mul_f32 v[34:35], v[34:35], v[68:69] op_sel_hi:[1,0]
	v_pk_mul_f32 v[36:37], v[36:37], v[68:69] op_sel_hi:[1,0]
	v_pk_mul_f32 v[38:39], v[38:39], v[68:69] op_sel_hi:[1,0]
	v_pk_mul_f32 v[40:41], v[40:41], v[68:69] op_sel_hi:[1,0]
	v_pk_mul_f32 v[42:43], v[42:43], v[68:69] op_sel_hi:[1,0]
	v_pk_mul_f32 v[44:45], v[44:45], v[68:69] op_sel_hi:[1,0]
	v_pk_mul_f32 v[46:47], v[46:47], v[68:69] op_sel_hi:[1,0]
	v_pk_fma_f32 v[32:33], v[50:51], v[32:33], v[78:79]
	v_pk_fma_f32 v[34:35], v[52:53], v[34:35], v[80:81]
	v_pk_fma_f32 v[36:37], v[54:55], v[36:37], v[82:83]
	v_pk_fma_f32 v[38:39], v[56:57], v[38:39], v[84:85]
	v_pk_fma_f32 v[40:41], v[58:59], v[40:41], v[86:87]
	v_pk_fma_f32 v[42:43], v[60:61], v[42:43], v[88:89]
	v_pk_fma_f32 v[44:45], v[62:63], v[44:45], v[90:91]
	v_pk_fma_f32 v[46:47], v[64:65], v[46:47], v[92:93]
	v_cvt_pk_bf16_f32 v32, v32, v33
	v_cvt_pk_bf16_f32 v33, v34, v35
	v_cvt_pk_bf16_f32 v36, v36, v37
	v_cvt_pk_bf16_f32 v37, v38, v39
	v_cvt_pk_bf16_f32 v40, v40, v41
	v_cvt_pk_bf16_f32 v41, v42, v43
	v_cvt_pk_bf16_f32 v44, v44, v45
	v_cvt_pk_bf16_f32 v45, v46, v47
	global_store_dwordx2 v67, v[32:33], s[6:7] offset:0
	global_store_dwordx2 v67, v[36:37], s[6:7] offset:512
	global_store_dwordx2 v67, v[40:41], s[6:7] offset:1024
	global_store_dwordx2 v67, v[44:45], s[6:7] offset:1536
	s_add_u32 s6, s6, 0x800
	s_addc_u32 s7, s7, 0
	s_waitcnt vmcnt(8)
	v_pk_mul_f32 v[70:71], v[0:1], v[0:1]
	v_pk_mul_f32 v[72:73], v[2:3], v[2:3]
	v_pk_fma_f32 v[70:71], v[4:5], v[4:5], v[70:71]
	v_pk_fma_f32 v[72:73], v[6:7], v[6:7], v[72:73]
	v_pk_fma_f32 v[70:71], v[8:9], v[8:9], v[70:71]
	v_pk_fma_f32 v[72:73], v[10:11], v[10:11], v[72:73]
	v_pk_fma_f32 v[70:71], v[12:13], v[12:13], v[70:71]
	v_pk_fma_f32 v[72:73], v[14:15], v[14:15], v[72:73]
	s_nop 0
	v_pk_add_f32 v[70:71], v[70:71], v[72:73]
	s_nop 0
	v_add_f32_e32 v68, v70, v71
	s_nop 1
	v_add_f32_dpp v68, v68, v68 quad_perm:[1,0,3,2] row_mask:0xf bank_mask:0xf bound_ctrl:1
	s_nop 1
	v_add_f32_dpp v68, v68, v68 quad_perm:[2,3,0,1] row_mask:0xf bank_mask:0xf bound_ctrl:1
	s_nop 1
	v_add_f32_dpp v68, v68, v68 row_half_mirror row_mask:0xf bank_mask:0xf bound_ctrl:1
	s_nop 1
	v_add_f32_dpp v68, v68, v68 row_mirror row_mask:0xf bank_mask:0xf bound_ctrl:1
	s_nop 1
	v_add_f32_dpp v68, v68, v68 row_bcast:15 row_mask:0xa bank_mask:0xf
	s_nop 1
	v_add_f32_dpp v68, v68, v68 row_bcast:31 row_mask:0xc bank_mask:0xf
	s_nop 1
	v_readlane_b32 s1, v68, 63
	s_nop 3
	v_mov_b32_e32 v68, s1
	v_fmamk_f32 v68, v68, 0x3a800000, v74
	v_rsq_f32_e32 v68, v68
	s_nop 0
	v_pk_mul_f32 v[0:1], v[0:1], v[68:69] op_sel_hi:[1,0]
	v_pk_mul_f32 v[2:3], v[2:3], v[68:69] op_sel_hi:[1,0]
	v_pk_mul_f32 v[4:5], v[4:5], v[68:69] op_sel_hi:[1,0]
	v_pk_mul_f32 v[6:7], v[6:7], v[68:69] op_sel_hi:[1,0]
	v_pk_mul_f32 v[8:9], v[8:9], v[68:69] op_sel_hi:[1,0]
	v_pk_mul_f32 v[10:11], v[10:11], v[68:69] op_sel_hi:[1,0]
	v_pk_mul_f32 v[12:13], v[12:13], v[68:69] op_sel_hi:[1,0]
	v_pk_mul_f32 v[14:15], v[14:15], v[68:69] op_sel_hi:[1,0]
	v_pk_fma_f32 v[0:1], v[50:51], v[0:1], v[78:79]
	v_pk_fma_f32 v[2:3], v[52:53], v[2:3], v[80:81]
	v_pk_fma_f32 v[4:5], v[54:55], v[4:5], v[82:83]
	v_pk_fma_f32 v[6:7], v[56:57], v[6:7], v[84:85]
	v_pk_fma_f32 v[8:9], v[58:59], v[8:9], v[86:87]
	v_pk_fma_f32 v[10:11], v[60:61], v[10:11], v[88:89]
	v_pk_fma_f32 v[12:13], v[62:63], v[12:13], v[90:91]
	v_pk_fma_f32 v[14:15], v[64:65], v[14:15], v[92:93]
	v_cvt_pk_bf16_f32 v0, v0, v1
	v_cvt_pk_bf16_f32 v1, v2, v3
	v_cvt_pk_bf16_f32 v4, v4, v5
	v_cvt_pk_bf16_f32 v5, v6, v7
	v_cvt_pk_bf16_f32 v8, v8, v9
	v_cvt_pk_bf16_f32 v9, v10, v11
	v_cvt_pk_bf16_f32 v12, v12, v13
	v_cvt_pk_bf16_f32 v13, v14, v15
	global_store_dwordx2 v67, v[0:1], s[6:7] offset:0
	global_store_dwordx2 v67, v[4:5], s[6:7] offset:512
	global_store_dwordx2 v67, v[8:9], s[6:7] offset:1024
	global_store_dwordx2 v67, v[12:13], s[6:7] offset:1536
	s_add_u32 s6, s6, 0x800
	s_addc_u32 s7, s7, 0
	s_branch .LBB0_1269
.Lnorm_orig_3:
	s_load_dwordx2 s[6:7], s[4:5], 0xd8
	v_ashrrev_i32_e32 v49, 31, v48
	v_lshlrev_b32_e32 v0, 4, v16
	v_lshlrev_b64 v[18:19], 12, v[48:49]
	v_and_b32_e32 v60, 0x3f0, v0
	s_waitcnt lgkmcnt(0)
	v_lshl_add_u64 v[0:1], s[6:7], 0, v[18:19]
	v_mov_b32_e32 v61, 0
	v_lshl_add_u64 v[0:1], v[0:1], 0, v[60:61]
	global_load_dwordx4 v[12:15], v[0:1], off
	global_load_dwordx4 v[8:11], v[0:1], off offset:1024
	global_load_dwordx4 v[4:7], v[0:1], off offset:2048
	s_nop 0
	global_load_dwordx4 v[0:3], v[0:1], off offset:3072
	s_load_dwordx2 s[4:5], s[4:5], 0xa8
	v_cmp_lt_i32_e32 vcc, v171, v165
	v_lshl_add_u64 v[20:21], s[0:1], 0, v[60:61]
	v_and_b32_e32 v22, 63, v16
	v_cndmask_b32_e32 v17, v164, v171, vcc
	v_cmp_lt_i32_e32 vcc, v170, v165
	v_lshlrev_b32_e32 v77, 2, v17
	s_waitcnt lgkmcnt(0)
	v_lshl_add_u64 v[50:51], s[4:5], 0, v[60:61]
	v_cndmask_b32_e32 v17, v164, v170, vcc
	v_cmp_lt_i32_e32 vcc, v169, v165
	v_lshlrev_b32_e32 v78, 2, v17
	s_mov_b64 s[4:5], 0x784000
	v_cndmask_b32_e32 v17, v164, v169, vcc
	v_cmp_lt_i32_e32 vcc, v168, v165
	v_lshlrev_b32_e32 v79, 2, v17
	v_lshl_add_u64 v[52:53], v[20:21], 0, s[4:5]
	v_cndmask_b32_e32 v17, v164, v168, vcc
	v_cmp_lt_i32_e32 vcc, v167, v165
	s_mov_b64 s[4:5], 0x783000
	v_lshlrev_b32_e32 v80, 2, v17
	v_cndmask_b32_e32 v17, v164, v167, vcc
	v_cmp_lt_i32_e32 vcc, v166, v165
	v_lshl_add_u64 v[54:55], v[20:21], 0, s[4:5]
	v_lshlrev_b64 v[20:21], 11, v[48:49]
	v_lshlrev_b32_e32 v81, 2, v17
	v_cndmask_b32_e32 v17, v164, v166, vcc
	v_lshl_or_b32 v20, v22, 3, v20
	v_lshlrev_b32_e32 v82, 2, v17
	v_lshl_add_u64 v[16:17], s[0:1], 0, v[20:21]
	s_mov_b64 s[0:1], 0x1c00000
	v_lshl_or_b32 v18, v22, 4, v18
	v_lshl_add_u64 v[56:57], v[16:17], 0, s[0:1]
	v_lshl_add_u64 v[16:17], s[6:7], 0, v[18:19]
	s_mov_b64 s[0:1], 0x1c00
	v_mov_b32_e32 v83, -1
	v_lshl_add_u64 v[58:59], v[16:17], 0, s[0:1]
	s_mov_b64 s[4:5], 0
	v_mov_b32_e32 v49, 0x358637bd
	s_mov_b32 s12, 0x800000
	s_mov_b64 s[6:7], 0x800
	s_mov_b64 s[8:9], 0x1000
	v_mov_b32_e32 v60, v61
	v_mov_b32_e32 v62, v61
	v_mov_b32_e32 v63, v61
	v_mov_b32_e32 v64, v61
	v_mov_b32_e32 v65, v61
	v_mov_b32_e32 v66, v61
	v_mov_b32_e32 v67, v61
	v_mov_b32_e32 v68, v61
	v_mov_b32_e32 v69, v61
	v_mov_b32_e32 v70, v61
	v_mov_b32_e32 v71, v61
	v_mov_b32_e32 v72, v61
	v_mov_b32_e32 v73, v61
	v_mov_b32_e32 v74, v61
	v_mov_b32_e32 v75, v61
	s_branch .LBB0_1265

.LBB0_1711:
	s_cmp_lt_i32 s20, s42
	s_cselect_b64 s[0:1], -1, 0
	s_cmp_ge_i32 s20, s43
	s_cselect_b64 s[2:3], -1, 0
	s_or_b64 s[0:1], s[0:1], s[2:3]
	s_and_b64 vcc, exec, s[0:1]
	s_cbranch_vccnz .LBB0_1773
	v_readlane_b32 s6, v254, 0
	v_readlane_b32 s7, v254, 1
	v_readlane_b32 s1, v254, 2
	v_readlane_b32 s0, v255, 9
	s_waitcnt vmcnt(0)
	v_mbcnt_lo_u32_b32 v16, -1, 0
	v_mbcnt_hi_u32_b32 v16, -1, v16
	s_addk_i32 s0, 0x7fff
	v_lshl_add_u32 v0, s1, 6, v16
	v_ashrrev_i32_e32 v0, 6, v0
	v_readlane_b32 s1, v254, 9
	v_readlane_b32 s2, v255, 8
	v_readlane_b32 s5, v255, 11
	v_add_u32_e32 v0, s1, v0
	s_ashr_i32 s1, s0, 31
	s_xor_b32 s1, s1, s2
	s_abs_i32 s0, s0
	v_readlane_b32 s2, v255, 10
	s_mul_hi_u32 s2, s0, s2
	s_mul_i32 s3, s2, s5
	s_sub_i32 s0, s0, s3
	s_add_i32 s3, s2, 1
	s_sub_i32 s4, s0, s5
	s_cmp_ge_u32 s0, s5
	s_cselect_b32 s2, s3, s2
	s_cselect_b32 s0, s4, s0
	s_add_i32 s3, s2, 1
	s_cmp_ge_u32 s0, s5
	s_cselect_b32 s0, s3, s2
	s_xor_b32 s0, s0, s1
	s_sub_i32 s0, s0, s1
	v_mul_lo_u32 v48, v0, s0
	v_add_u32_e32 v0, s0, v48
	v_min_i32_e32 v54, 0x8000, v0
	v_cmp_lt_i32_e32 vcc, v48, v54
	s_and_saveexec_b64 s[4:5], vcc
	s_cbranch_execz .LBB0_1719
	s_cmp_lg_u32 s80, 0x100
	s_cbranch_scc1 .Lnorm_orig_4
	v_readlane_b32 s0, v254, 0
	v_readlane_b32 s1, v254, 1
	v_readfirstlane_b32 s100, v48
	s_nop 3
	s_load_dwordx2 s[2:3], s[0:1], 0xd8
	s_load_dwordx2 s[98:99], s[0:1], 0xd0
	s_load_dwordx2 s[6:7], s[0:1], 0xd8
	v_mbcnt_lo_u32_b32 v72, -1, 0
	v_mbcnt_hi_u32_b32 v72, -1, v72
	v_lshlrev_b32_e32 v72, 4, v72
	v_mov_b32_e32 v73, 0x358637bd
	s_waitcnt lgkmcnt(0)
	s_mov_b32 s0, s100
	s_add_u32 s1, s0, 0
	s_lshl_b32 s1, s1, 12
	s_add_u32 s2, s2, s1
	s_addc_u32 s3, s3, 0
	global_load_dwordx4 v[56:59], v72, s[98:99] offset:0
	global_load_dwordx4 v[60:63], v72, s[98:99] offset:1024
	global_load_dwordx4 v[64:67], v72, s[98:99] offset:2048
	global_load_dwordx4 v[68:71], v72, s[98:99] offset:3072
	s_lshl_b32 s1, s0, 12
	s_add_u32 s6, s6, s1
	s_addc_u32 s7, s7, 0
	global_load_dwordx4 v[0:3], v72, s[2:3] offset:0
	global_load_dwordx4 v[4:7], v72, s[2:3] offset:1024
	global_load_dwordx4 v[8:11], v72, s[2:3] offset:2048
	global_load_dwordx4 v[12:15], v72, s[2:3] offset:3072
	s_add_u32 s2, s2, 0x1000
	s_addc_u32 s3, s3, 0
	global_load_dwordx4 v[16:19], v72, s[2:3] offset:0
	global_load_dwordx4 v[20:23], v72, s[2:3] offset:1024
	global_load_dwordx4 v[24:27], v72, s[2:3] offset:2048
	global_load_dwordx4 v[28:31], v72, s[2:3] offset:3072
	s_add_u32 s2, s2, 0x1000
	s_addc_u32 s3, s3, 0
	s_waitcnt vmcnt(8)
	global_load_dwordx4 v[32:35], v72, s[2:3] offset:0
	global_load_dwordx4 v[36:39], v72, s[2:3] offset:1024
	global_load_dwordx4 v[40:43], v72, s[2:3] offset:2048
	global_load_dwordx4 v[44:47], v72, s[2:3] offset:3072
	s_add_u32 s2, s2, 0x1000
	s_addc_u32 s3, s3, 0
	s_waitcnt vmcnt(8)
	v_pk_mul_f32 v[76:77], v[0:1], v[0:1]
	v_pk_mul_f32 v[78:79], v[2:3], v[2:3]
	v_pk_fma_f32 v[76:77], v[4:5], v[4:5], v[76:77]
	v_pk_fma_f32 v[78:79], v[6:7], v[6:7], v[78:79]
	v_pk_fma_f32 v[76:77], v[8:9], v[8:9], v[76:77]
	v_pk_fma_f32 v[78:79], v[10:11], v[10:11], v[78:79]
	v_pk_fma_f32 v[76:77], v[12:13], v[12:13], v[76:77]
	v_pk_fma_f32 v[78:79], v[14:15], v[14:15], v[78:79]
	s_nop 0
	v_pk_add_f32 v[76:77], v[76:77], v[78:79]
	s_nop 0
	v_add_f32_e32 v74, v76, v77
	s_nop 1
	v_add_f32_dpp v74, v74, v74 quad_perm:[1,0,3,2] row_mask:0xf bank_mask:0xf bound_ctrl:1
	s_nop 1
	v_add_f32_dpp v74, v74, v74 quad_perm:[2,3,0,1] row_mask:0xf bank_mask:0xf bound_ctrl:1
	s_nop 1
	v_add_f32_dpp v74, v74, v74 row_half_mirror row_mask:0xf bank_mask:0xf bound_ctrl:1
	s_nop 1
	v_add_f32_dpp v74, v74, v74 row_mirror row_mask:0xf bank_mask:0xf bound_ctrl:1
	s_nop 1
	v_add_f32_dpp v74, v74, v74 row_bcast:15 row_mask:0xa bank_mask:0xf
	s_nop 1
	v_add_f32_dpp v74, v74, v74 row_bcast:31 row_mask:0xc bank_mask:0xf
	s_nop 1
	v_readlane_b32 s1, v74, 63
	s_nop 3
	v_mov_b32_e32 v74, s1
	v_fmamk_f32 v74, v74, 0x3a800000, v73
	v_rsq_f32_e32 v74, v74
	s_nop 0
	v_pk_mul_f32 v[0:1], v[0:1], v[74:75] op_sel_hi:[1,0]
	v_pk_mul_f32 v[2:3], v[2:3], v[74:75] op_sel_hi:[1,0]
	v_pk_mul_f32 v[4:5], v[4:5], v[74:75] op_sel_hi:[1,0]
	v_pk_mul_f32 v[6:7], v[6:7], v[74:75] op_sel_hi:[1,0]
	v_pk_mul_f32 v[8:9], v[8:9], v[74:75] op_sel_hi:[1,0]
	v_pk_mul_f32 v[10:11], v[10:11], v[74:75] op_sel_hi:[1,0]
	v_pk_mul_f32 v[12:13], v[12:13], v[74:75] op_sel_hi:[1,0]
	v_pk_mul_f32 v[14:15], v[14:15], v[74:75] op_sel_hi:[1,0]
	v_pk_mul_f32 v[0:1], v[56:57], v[0:1]
	v_pk_mul_f32 v[2:3], v[58:59], v[2:3]
	v_pk_mul_f32 v[4:5], v[60:61], v[4:5]
	v_pk_mul_f32 v[6:7], v[62:63], v[6:7]
	v_pk_mul_f32 v[8:9], v[64:65], v[8:9]
	v_pk_mul_f32 v[10:11], v[66:67], v[10:11]
	v_pk_mul_f32 v[12:13], v[68:69], v[12:13]
	v_pk_mul_f32 v[14:15], v[70:71], v[14:15]
	global_store_dwordx4 v72, v[0:3], s[6:7] offset:0
	global_store_dwordx4 v72, v[4:7], s[6:7] offset:1024
	global_store_dwordx4 v72, v[8:11], s[6:7] offset:2048
	global_store_dwordx4 v72, v[12:15], s[6:7] offset:3072
	s_add_u32 s6, s6, 0x1000
	s_addc_u32 s7, s7, 0
	global_load_dwordx4 v[0:3], v72, s[2:3] offset:0
	global_load_dwordx4 v[4:7], v72, s[2:3] offset:1024
	global_load_dwordx4 v[8:11], v72, s[2:3] offset:2048
	global_load_dwordx4 v[12:15], v72, s[2:3] offset:3072
	s_add_u32 s2, s2, 0x1000
	s_addc_u32 s3, s3, 0
	s_waitcnt vmcnt(12)
	v_pk_mul_f32 v[76:77], v[16:17], v[16:17]
	v_pk_mul_f32 v[78:79], v[18:19], v[18:19]
	v_pk_fma_f32 v[76:77], v[20:21], v[20:21], v[76:77]
	v_pk_fma_f32 v[78:79], v[22:23], v[22:23], v[78:79]
	v_pk_fma_f32 v[76:77], v[24:25], v[24:25], v[76:77]
	v_pk_fma_f32 v[78:79], v[26:27], v[26:27], v[78:79]
	v_pk_fma_f32 v[76:77], v[28:29], v[28:29], v[76:77]
	v_pk_fma_f32 v[78:79], v[30:31], v[30:31], v[78:79]
	s_nop 0
	v_pk_add_f32 v[76:77], v[76:77], v[78:79]
	s_nop 0
	v_add_f32_e32 v74, v76, v77
	s_nop 1
	v_add_f32_dpp v74, v74, v74 quad_perm:[1,0,3,2] row_mask:0xf bank_mask:0xf bound_ctrl:1
	s_nop 1
	v_add_f32_dpp v74, v74, v74 quad_perm:[2,3,0,1] row_mask:0xf bank_mask:0xf bound_ctrl:1
	s_nop 1
	v_add_f32_dpp v74, v74, v74 row_half_mirror row_mask:0xf bank_mask:0xf bound_ctrl:1
	s_nop 1
	v_add_f32_dpp v74, v74, v74 row_mirror row_mask:0xf bank_mask:0xf bound_ctrl:1
	s_nop 1
	v_add_f32_dpp v74, v74, v74 row_bcast:15 row_mask:0xa bank_mask:0xf
	s_nop 1
	v_add_f32_dpp v74, v74, v74 row_bcast:31 row_mask:0xc bank_mask:0xf
	s_nop 1
	v_readlane_b32 s1, v74, 63
	s_nop 3
	v_mov_b32_e32 v74, s1
	v_fmamk_f32 v74, v74, 0x3a800000, v73
	v_rsq_f32_e32 v74, v74
	s_nop 0
	v_pk_mul_f32 v[16:17], v[16:17], v[74:75] op_sel_hi:[1,0]
	v_pk_mul_f32 v[18:19], v[18:19], v[74:75] op_sel_hi:[1,0]
	v_pk_mul_f32 v[20:21], v[20:21], v[74:75] op_sel_hi:[1,0]
	v_pk_mul_f32 v[22:23], v[22:23], v[74:75] op_sel_hi:[1,0]
	v_pk_mul_f32 v[24:25], v[24:25], v[74:75] op_sel_hi:[1,0]
	v_pk_mul_f32 v[26:27], v[26:27], v[74:75] op_sel_hi:[1,0]
	v_pk_mul_f32 v[28:29], v[28:29], v[74:75] op_sel_hi:[1,0]
	v_pk_mul_f32 v[30:31], v[30:31], v[74:75] op_sel_hi:[1,0]
	v_pk_mul_f32 v[16:17], v[56:57], v[16:17]
	v_pk_mul_f32 v[18:19], v[58:59], v[18:19]
	v_pk_mul_f32 v[20:21], v[60:61], v[20:21]
	v_pk_mul_f32 v[22:23], v[62:63], v[22:23]
	v_pk_mul_f32 v[24:25], v[64:65], v[24:25]
	v_pk_mul_f32 v[26:27], v[66:67], v[26:27]
	v_pk_mul_f32 v[28:29], v[68:69], v[28:29]
	v_pk_mul_f32 v[30:31], v[70:71], v[30:31]
	global_store_dwordx4 v72, v[16:19], s[6:7] offset:0
	global_store_dwordx4 v72, v[20:23], s[6:7] offset:1024
	global_store_dwordx4 v72, v[24:27], s[6:7] offset:2048
	global_store_dwordx4 v72, v[28:31], s[6:7] offset:3072
	s_add_u32 s6, s6, 0x1000
	s_addc_u32 s7, s7, 0
	global_load_dwordx4 v[16:19], v72, s[2:3] offset:0
	global_load_dwordx4 v[20:23], v72, s[2:3] offset:1024
	global_load_dwordx4 v[24:27], v72, s[2:3] offset:2048
	global_load_dwordx4 v[28:31], v72, s[2:3] offset:3072
	s_add_u32 s2, s2, 0x1000
	s_addc_u32 s3, s3, 0
	s_waitcnt vmcnt(16)
	v_pk_mul_f32 v[76:77], v[32:33], v[32:33]
	v_pk_mul_f32 v[78:79], v[34:35], v[34:35]
	v_pk_fma_f32 v[76:77], v[36:37], v[36:37], v[76:77]
	v_pk_fma_f32 v[78:79], v[38:39], v[38:39], v[78:79]
	v_pk_fma_f32 v[76:77], v[40:41], v[40:41], v[76:77]
	v_pk_fma_f32 v[78:79], v[42:43], v[42:43], v[78:79]
	v_pk_fma_f32 v[76:77], v[44:45], v[44:45], v[76:77]
	v_pk_fma_f32 v[78:79], v[46:47], v[46:47], v[78:79]
	s_nop 0
	v_pk_add_f32 v[76:77], v[76:77], v[78:79]
	s_nop 0
	v_add_f32_e32 v74, v76, v77
	s_nop 1
	v_add_f32_dpp v74, v74, v74 quad_perm:[1,0,3,2] row_mask:0xf bank_mask:0xf bound_ctrl:1
	s_nop 1
	v_add_f32_dpp v74, v74, v74 quad_perm:[2,3,0,1] row_mask:0xf bank_mask:0xf bound_ctrl:1
	s_nop 1
	v_add_f32_dpp v74, v74, v74 row_half_mirror row_mask:0xf bank_mask:0xf bound_ctrl:1
	s_nop 1
	v_add_f32_dpp v74, v74, v74 row_mirror row_mask:0xf bank_mask:0xf bound_ctrl:1
	s_nop 1
	v_add_f32_dpp v74, v74, v74 row_bcast:15 row_mask:0xa bank_mask:0xf
	s_nop 1
	v_add_f32_dpp v74, v74, v74 row_bcast:31 row_mask:0xc bank_mask:0xf
	s_nop 1
	v_readlane_b32 s1, v74, 63
	s_nop 3
	v_mov_b32_e32 v74, s1
	v_fmamk_f32 v74, v74, 0x3a800000, v73
	v_rsq_f32_e32 v74, v74
	s_nop 0
	v_pk_mul_f32 v[32:33], v[32:33], v[74:75] op_sel_hi:[1,0]
	v_pk_mul_f32 v[34:35], v[34:35], v[74:75] op_sel_hi:[1,0]
	v_pk_mul_f32 v[36:37], v[36:37], v[74:75] op_sel_hi:[1,0]
	v_pk_mul_f32 v[38:39], v[38:39], v[74:75] op_sel_hi:[1,0]
	v_pk_mul_f32 v[40:41], v[40:41], v[74:75] op_sel_hi:[1,0]
	v_pk_mul_f32 v[42:43], v[42:43], v[74:75] op_sel_hi:[1,0]
	v_pk_mul_f32 v[44:45], v[44:45], v[74:75] op_sel_hi:[1,0]
	v_pk_mul_f32 v[46:47], v[46:47], v[74:75] op_sel_hi:[1,0]
	v_pk_mul_f32 v[32:33], v[56:57], v[32:33]
	v_pk_mul_f32 v[34:35], v[58:59], v[34:35]
	v_pk_mul_f32 v[36:37], v[60:61], v[36:37]
	v_pk_mul_f32 v[38:39], v[62:63], v[38:39]
	v_pk_mul_f32 v[40:41], v[64:65], v[40:41]
	v_pk_mul_f32 v[42:43], v[66:67], v[42:43]
	v_pk_mul_f32 v[44:45], v[68:69], v[44:45]
	v_pk_mul_f32 v[46:47], v[70:71], v[46:47]
	global_store_dwordx4 v72, v[32:35], s[6:7] offset:0
	global_store_dwordx4 v72, v[36:39], s[6:7] offset:1024
	global_store_dwordx4 v72, v[40:43], s[6:7] offset:2048
	global_store_dwordx4 v72, v[44:47], s[6:7] offset:3072
	s_add_u32 s6, s6, 0x1000
	s_addc_u32 s7, s7, 0
	global_load_dwordx4 v[32:35], v72, s[2:3] offset:0
	global_load_dwordx4 v[36:39], v72, s[2:3] offset:1024
	global_load_dwordx4 v[40:43], v72, s[2:3] offset:2048
	global_load_dwordx4 v[44:47], v72, s[2:3] offset:3072
	s_add_u32 s2, s2, 0x1000
	s_addc_u32 s3, s3, 0
	s_waitcnt vmcnt(16)
	v_pk_mul_f32 v[76:77], v[0:1], v[0:1]
	v_pk_mul_f32 v[78:79], v[2:3], v[2:3]
	v_pk_fma_f32 v[76:77], v[4:5], v[4:5], v[76:77]
	v_pk_fma_f32 v[78:79], v[6:7], v[6:7], v[78:79]
	v_pk_fma_f32 v[76:77], v[8:9], v[8:9], v[76:77]
	v_pk_fma_f32 v[78:79], v[10:11], v[10:11], v[78:79]
	v_pk_fma_f32 v[76:77], v[12:13], v[12:13], v[76:77]
	v_pk_fma_f32 v[78:79], v[14:15], v[14:15], v[78:79]
	s_nop 0
	v_pk_add_f32 v[76:77], v[76:77], v[78:79]
	s_nop 0
	v_add_f32_e32 v74, v76, v77
	s_nop 1
	v_add_f32_dpp v74, v74, v74 quad_perm:[1,0,3,2] row_mask:0xf bank_mask:0xf bound_ctrl:1
	s_nop 1
	v_add_f32_dpp v74, v74, v74 quad_perm:[2,3,0,1] row_mask:0xf bank_mask:0xf bound_ctrl:1
	s_nop 1
	v_add_f32_dpp v74, v74, v74 row_half_mirror row_mask:0xf bank_mask:0xf bound_ctrl:1
	s_nop 1
	v_add_f32_dpp v74, v74, v74 row_mirror row_mask:0xf bank_mask:0xf bound_ctrl:1
	s_nop 1
	v_add_f32_dpp v74, v74, v74 row_bcast:15 row_mask:0xa bank_mask:0xf
	s_nop 1
	v_add_f32_dpp v74, v74, v74 row_bcast:31 row_mask:0xc bank_mask:0xf
	s_nop 1
	v_readlane_b32 s1, v74, 63
	s_nop 3
	v_mov_b32_e32 v74, s1
	v_fmamk_f32 v74, v74, 0x3a800000, v73
	v_rsq_f32_e32 v74, v74
	s_nop 0
	v_pk_mul_f32 v[0:1], v[0:1], v[74:75] op_sel_hi:[1,0]
	v_pk_mul_f32 v[2:3], v[2:3], v[74:75] op_sel_hi:[1,0]
	v_pk_mul_f32 v[4:5], v[4:5], v[74:75] op_sel_hi:[1,0]
	v_pk_mul_f32 v[6:7], v[6:7], v[74:75] op_sel_hi:[1,0]
	v_pk_mul_f32 v[8:9], v[8:9], v[74:75] op_sel_hi:[1,0]
	v_pk_mul_f32 v[10:11], v[10:11], v[74:75] op_sel_hi:[1,0]
	v_pk_mul_f32 v[12:13], v[12:13], v[74:75] op_sel_hi:[1,0]
	v_pk_mul_f32 v[14:15], v[14:15], v[74:75] op_sel_hi:[1,0]
	v_pk_mul_f32 v[0:1], v[56:57], v[0:1]
	v_pk_mul_f32 v[2:3], v[58:59], v[2:3]
	v_pk_mul_f32 v[4:5], v[60:61], v[4:5]
	v_pk_mul_f32 v[6:7], v[62:63], v[6:7]
	v_pk_mul_f32 v[8:9], v[64:65], v[8:9]
	v_pk_mul_f32 v[10:11], v[66:67], v[10:11]
	v_pk_mul_f32 v[12:13], v[68:69], v[12:13]
	v_pk_mul_f32 v[14:15], v[70:71], v[14:15]
	global_store_dwordx4 v72, v[0:3], s[6:7] offset:0
	global_store_dwordx4 v72, v[4:7], s[6:7] offset:1024
	global_store_dwordx4 v72, v[8:11], s[6:7] offset:2048
	global_store_dwordx4 v72, v[12:15], s[6:7] offset:3072
	s_add_u32 s6, s6, 0x1000
	s_addc_u32 s7, s7, 0
	global_load_dwordx4 v[0:3], v72, s[2:3] offset:0
	global_load_dwordx4 v[4:7], v72, s[2:3] offset:1024
	global_load_dwordx4 v[8:11], v72, s[2:3] offset:2048
	global_load_dwordx4 v[12:15], v72, s[2:3] offset:3072
	s_add_u32 s2, s2, 0x1000
	s_addc_u32 s3, s3, 0
	s_waitcnt vmcnt(16)
	v_pk_mul_f32 v[76:77], v[16:17], v[16:17]
	v_pk_mul_f32 v[78:79], v[18:19], v[18:19]
	v_pk_fma_f32 v[76:77], v[20:21], v[20:21], v[76:77]
	v_pk_fma_f32 v[78:79], v[22:23], v[22:23], v[78:79]
	v_pk_fma_f32 v[76:77], v[24:25], v[24:25], v[76:77]
	v_pk_fma_f32 v[78:79], v[26:27], v[26:27], v[78:79]
	v_pk_fma_f32 v[76:77], v[28:29], v[28:29], v[76:77]
	v_pk_fma_f32 v[78:79], v[30:31], v[30:31], v[78:79]
	s_nop 0
	v_pk_add_f32 v[76:77], v[76:77], v[78:79]
	s_nop 0
	v_add_f32_e32 v74, v76, v77
	s_nop 1
	v_add_f32_dpp v74, v74, v74 quad_perm:[1,0,3,2] row_mask:0xf bank_mask:0xf bound_ctrl:1
	s_nop 1
	v_add_f32_dpp v74, v74, v74 quad_perm:[2,3,0,1] row_mask:0xf bank_mask:0xf bound_ctrl:1
	s_nop 1
	v_add_f32_dpp v74, v74, v74 row_half_mirror row_mask:0xf bank_mask:0xf bound_ctrl:1
	s_nop 1
	v_add_f32_dpp v74, v74, v74 row_mirror row_mask:0xf bank_mask:0xf bound_ctrl:1
	s_nop 1
	v_add_f32_dpp v74, v74, v74 row_bcast:15 row_mask:0xa bank_mask:0xf
	s_nop 1
	v_add_f32_dpp v74, v74, v74 row_bcast:31 row_mask:0xc bank_mask:0xf
	s_nop 1
	v_readlane_b32 s1, v74, 63
	s_nop 3
	v_mov_b32_e32 v74, s1
	v_fmamk_f32 v74, v74, 0x3a800000, v73
	v_rsq_f32_e32 v74, v74
	s_nop 0
	v_pk_mul_f32 v[16:17], v[16:17], v[74:75] op_sel_hi:[1,0]
	v_pk_mul_f32 v[18:19], v[18:19], v[74:75] op_sel_hi:[1,0]
	v_pk_mul_f32 v[20:21], v[20:21], v[74:75] op_sel_hi:[1,0]
	v_pk_mul_f32 v[22:23], v[22:23], v[74:75] op_sel_hi:[1,0]
	v_pk_mul_f32 v[24:25], v[24:25], v[74:75] op_sel_hi:[1,0]
	v_pk_mul_f32 v[26:27], v[26:27], v[74:75] op_sel_hi:[1,0]
	v_pk_mul_f32 v[28:29], v[28:29], v[74:75] op_sel_hi:[1,0]
	v_pk_mul_f32 v[30:31], v[30:31], v[74:75] op_sel_hi:[1,0]
	v_pk_mul_f32 v[16:17], v[56:57], v[16:17]
	v_pk_mul_f32 v[18:19], v[58:59], v[18:19]
	v_pk_mul_f32 v[20:21], v[60:61], v[20:21]
	v_pk_mul_f32 v[22:23], v[62:63], v[22:23]
	v_pk_mul_f32 v[24:25], v[64:65], v[24:25]
	v_pk_mul_f32 v[26:27], v[66:67], v[26:27]
	v_pk_mul_f32 v[28:29], v[68:69], v[28:29]
	v_pk_mul_f32 v[30:31], v[70:71], v[30:31]
	global_store_dwordx4 v72, v[16:19], s[6:7] offset:0
	global_store_dwordx4 v72, v[20:23], s[6:7] offset:1024
	global_store_dwordx4 v72, v[24:27], s[6:7] offset:2048
	global_store_dwordx4 v72, v[28:31], s[6:7] offset:3072
	s_add_u32 s6, s6, 0x1000
	s_addc_u32 s7, s7, 0
	global_load_dwordx4 v[16:19], v72, s[2:3] offset:0
	global_load_dwordx4 v[20:23], v72, s[2:3] offset:1024
	global_load_dwordx4 v[24:27], v72, s[2:3] offset:2048
	global_load_dwordx4 v[28:31], v72, s[2:3] offset:3072
	s_add_u32 s2, s2, 0x1000
	s_addc_u32 s3, s3, 0
	s_waitcnt vmcnt(16)
	v_pk_mul_f32 v[76:77], v[32:33], v[32:33]
	v_pk_mul_f32 v[78:79], v[34:35], v[34:35]
	v_pk_fma_f32 v[76:77], v[36:37], v[36:37], v[76:77]
	v_pk_fma_f32 v[78:79], v[38:39], v[38:39], v[78:79]
	v_pk_fma_f32 v[76:77], v[40:41], v[40:41], v[76:77]
	v_pk_fma_f32 v[78:79], v[42:43], v[42:43], v[78:79]
	v_pk_fma_f32 v[76:77], v[44:45], v[44:45], v[76:77]
	v_pk_fma_f32 v[78:79], v[46:47], v[46:47], v[78:79]
	s_nop 0
	v_pk_add_f32 v[76:77], v[76:77], v[78:79]
	s_nop 0
	v_add_f32_e32 v74, v76, v77
	s_nop 1
	v_add_f32_dpp v74, v74, v74 quad_perm:[1,0,3,2] row_mask:0xf bank_mask:0xf bound_ctrl:1
	s_nop 1
	v_add_f32_dpp v74, v74, v74 quad_perm:[2,3,0,1] row_mask:0xf bank_mask:0xf bound_ctrl:1
	s_nop 1
	v_add_f32_dpp v74, v74, v74 row_half_mirror row_mask:0xf bank_mask:0xf bound_ctrl:1
	s_nop 1
	v_add_f32_dpp v74, v74, v74 row_mirror row_mask:0xf bank_mask:0xf bound_ctrl:1
	s_nop 1
	v_add_f32_dpp v74, v74, v74 row_bcast:15 row_mask:0xa bank_mask:0xf
	s_nop 1
	v_add_f32_dpp v74, v74, v74 row_bcast:31 row_mask:0xc bank_mask:0xf
	s_nop 1
	v_readlane_b32 s1, v74, 63
	s_nop 3
	v_mov_b32_e32 v74, s1
	v_fmamk_f32 v74, v74, 0x3a800000, v73
	v_rsq_f32_e32 v74, v74
	s_nop 0
	v_pk_mul_f32 v[32:33], v[32:33], v[74:75] op_sel_hi:[1,0]
	v_pk_mul_f32 v[34:35], v[34:35], v[74:75] op_sel_hi:[1,0]
	v_pk_mul_f32 v[36:37], v[36:37], v[74:75] op_sel_hi:[1,0]
	v_pk_mul_f32 v[38:39], v[38:39], v[74:75] op_sel_hi:[1,0]
	v_pk_mul_f32 v[40:41], v[40:41], v[74:75] op_sel_hi:[1,0]
	v_pk_mul_f32 v[42:43], v[42:43], v[74:75] op_sel_hi:[1,0]
	v_pk_mul_f32 v[44:45], v[44:45], v[74:75] op_sel_hi:[1,0]
	v_pk_mul_f32 v[46:47], v[46:47], v[74:75] op_sel_hi:[1,0]
	v_pk_mul_f32 v[32:33], v[56:57], v[32:33]
	v_pk_mul_f32 v[34:35], v[58:59], v[34:35]
	v_pk_mul_f32 v[36:37], v[60:61], v[36:37]
	v_pk_mul_f32 v[38:39], v[62:63], v[38:39]
	v_pk_mul_f32 v[40:41], v[64:65], v[40:41]
	v_pk_mul_f32 v[42:43], v[66:67], v[42:43]
	v_pk_mul_f32 v[44:45], v[68:69], v[44:45]
	v_pk_mul_f32 v[46:47], v[70:71], v[46:47]
	global_store_dwordx4 v72, v[32:35], s[6:7] offset:0
	global_store_dwordx4 v72, v[36:39], s[6:7] offset:1024
	global_store_dwordx4 v72, v[40:43], s[6:7] offset:2048
	global_store_dwordx4 v72, v[44:47], s[6:7] offset:3072
	s_add_u32 s6, s6, 0x1000
	s_addc_u32 s7, s7, 0
	global_load_dwordx4 v[32:35], v72, s[2:3] offset:0
	global_load_dwordx4 v[36:39], v72, s[2:3] offset:1024
	global_load_dwordx4 v[40:43], v72, s[2:3] offset:2048
	global_load_dwordx4 v[44:47], v72, s[2:3] offset:3072
	s_add_u32 s2, s2, 0x1000
	s_addc_u32 s3, s3, 0
	s_waitcnt vmcnt(16)
	v_pk_mul_f32 v[76:77], v[0:1], v[0:1]
	v_pk_mul_f32 v[78:79], v[2:3], v[2:3]
	v_pk_fma_f32 v[76:77], v[4:5], v[4:5], v[76:77]
	v_pk_fma_f32 v[78:79], v[6:7], v[6:7], v[78:79]
	v_pk_fma_f32 v[76:77], v[8:9], v[8:9], v[76:77]
	v_pk_fma_f32 v[78:79], v[10:11], v[10:11], v[78:79]
	v_pk_fma_f32 v[76:77], v[12:13], v[12:13], v[76:77]
	v_pk_fma_f32 v[78:79], v[14:15], v[14:15], v[78:79]
	s_nop 0
	v_pk_add_f32 v[76:77], v[76:77], v[78:79]
	s_nop 0
	v_add_f32_e32 v74, v76, v77
	s_nop 1
	v_add_f32_dpp v74, v74, v74 quad_perm:[1,0,3,2] row_mask:0xf bank_mask:0xf bound_ctrl:1
	s_nop 1
	v_add_f32_dpp v74, v74, v74 quad_perm:[2,3,0,1] row_mask:0xf bank_mask:0xf bound_ctrl:1
	s_nop 1
	v_add_f32_dpp v74, v74, v74 row_half_mirror row_mask:0xf bank_mask:0xf bound_ctrl:1
	s_nop 1
	v_add_f32_dpp v74, v74, v74 row_mirror row_mask:0xf bank_mask:0xf bound_ctrl:1
	s_nop 1
	v_add_f32_dpp v74, v74, v74 row_bcast:15 row_mask:0xa bank_mask:0xf
	s_nop 1
	v_add_f32_dpp v74, v74, v74 row_bcast:31 row_mask:0xc bank_mask:0xf
	s_nop 1
	v_readlane_b32 s1, v74, 63
	s_nop 3
	v_mov_b32_e32 v74, s1
	v_fmamk_f32 v74, v74, 0x3a800000, v73
	v_rsq_f32_e32 v74, v74
	s_nop 0
	v_pk_mul_f32 v[0:1], v[0:1], v[74:75] op_sel_hi:[1,0]
	v_pk_mul_f32 v[2:3], v[2:3], v[74:75] op_sel_hi:[1,0]
	v_pk_mul_f32 v[4:5], v[4:5], v[74:75] op_sel_hi:[1,0]
	v_pk_mul_f32 v[6:7], v[6:7], v[74:75] op_sel_hi:[1,0]
	v_pk_mul_f32 v[8:9], v[8:9], v[74:75] op_sel_hi:[1,0]
	v_pk_mul_f32 v[10:11], v[10:11], v[74:75] op_sel_hi:[1,0]
	v_pk_mul_f32 v[12:13], v[12:13], v[74:75] op_sel_hi:[1,0]
	v_pk_mul_f32 v[14:15], v[14:15], v[74:75] op_sel_hi:[1,0]
	v_pk_mul_f32 v[0:1], v[56:57], v[0:1]
	v_pk_mul_f32 v[2:3], v[58:59], v[2:3]
	v_pk_mul_f32 v[4:5], v[60:61], v[4:5]
	v_pk_mul_f32 v[6:7], v[62:63], v[6:7]
	v_pk_mul_f32 v[8:9], v[64:65], v[8:9]
	v_pk_mul_f32 v[10:11], v[66:67], v[10:11]
	v_pk_mul_f32 v[12:13], v[68:69], v[12:13]
	v_pk_mul_f32 v[14:15], v[70:71], v[14:15]
	global_store_dwordx4 v72, v[0:3], s[6:7] offset:0
	global_store_dwordx4 v72, v[4:7], s[6:7] offset:1024
	global_store_dwordx4 v72, v[8:11], s[6:7] offset:2048
	global_store_dwordx4 v72, v[12:15], s[6:7] offset:3072
	s_add_u32 s6, s6, 0x1000
	s_addc_u32 s7, s7, 0
	global_load_dwordx4 v[0:3], v72, s[2:3] offset:0
	global_load_dwordx4 v[4:7], v72, s[2:3] offset:1024
	global_load_dwordx4 v[8:11], v72, s[2:3] offset:2048
	global_load_dwordx4 v[12:15], v72, s[2:3] offset:3072
	s_add_u32 s2, s2, 0x1000
	s_addc_u32 s3, s3, 0
	s_waitcnt vmcnt(16)
	v_pk_mul_f32 v[76:77], v[16:17], v[16:17]
	v_pk_mul_f32 v[78:79], v[18:19], v[18:19]
	v_pk_fma_f32 v[76:77], v[20:21], v[20:21], v[76:77]
	v_pk_fma_f32 v[78:79], v[22:23], v[22:23], v[78:79]
	v_pk_fma_f32 v[76:77], v[24:25], v[24:25], v[76:77]
	v_pk_fma_f32 v[78:79], v[26:27], v[26:27], v[78:79]
	v_pk_fma_f32 v[76:77], v[28:29], v[28:29], v[76:77]
	v_pk_fma_f32 v[78:79], v[30:31], v[30:31], v[78:79]
	s_nop 0
	v_pk_add_f32 v[76:77], v[76:77], v[78:79]
	s_nop 0
	v_add_f32_e32 v74, v76, v77
	s_nop 1
	v_add_f32_dpp v74, v74, v74 quad_perm:[1,0,3,2] row_mask:0xf bank_mask:0xf bound_ctrl:1
	s_nop 1
	v_add_f32_dpp v74, v74, v74 quad_perm:[2,3,0,1] row_mask:0xf bank_mask:0xf bound_ctrl:1
	s_nop 1
	v_add_f32_dpp v74, v74, v74 row_half_mirror row_mask:0xf bank_mask:0xf bound_ctrl:1
	s_nop 1
	v_add_f32_dpp v74, v74, v74 row_mirror row_mask:0xf bank_mask:0xf bound_ctrl:1
	s_nop 1
	v_add_f32_dpp v74, v74, v74 row_bcast:15 row_mask:0xa bank_mask:0xf
	s_nop 1
	v_add_f32_dpp v74, v74, v74 row_bcast:31 row_mask:0xc bank_mask:0xf
	s_nop 1
	v_readlane_b32 s1, v74, 63
	s_nop 3
	v_mov_b32_e32 v74, s1
	v_fmamk_f32 v74, v74, 0x3a800000, v73
	v_rsq_f32_e32 v74, v74
	s_nop 0
	v_pk_mul_f32 v[16:17], v[16:17], v[74:75] op_sel_hi:[1,0]
	v_pk_mul_f32 v[18:19], v[18:19], v[74:75] op_sel_hi:[1,0]
	v_pk_mul_f32 v[20:21], v[20:21], v[74:75] op_sel_hi:[1,0]
	v_pk_mul_f32 v[22:23], v[22:23], v[74:75] op_sel_hi:[1,0]
	v_pk_mul_f32 v[24:25], v[24:25], v[74:75] op_sel_hi:[1,0]
	v_pk_mul_f32 v[26:27], v[26:27], v[74:75] op_sel_hi:[1,0]
	v_pk_mul_f32 v[28:29], v[28:29], v[74:75] op_sel_hi:[1,0]
	v_pk_mul_f32 v[30:31], v[30:31], v[74:75] op_sel_hi:[1,0]
	v_pk_mul_f32 v[16:17], v[56:57], v[16:17]
	v_pk_mul_f32 v[18:19], v[58:59], v[18:19]
	v_pk_mul_f32 v[20:21], v[60:61], v[20:21]
	v_pk_mul_f32 v[22:23], v[62:63], v[22:23]
	v_pk_mul_f32 v[24:25], v[64:65], v[24:25]
	v_pk_mul_f32 v[26:27], v[66:67], v[26:27]
	v_pk_mul_f32 v[28:29], v[68:69], v[28:29]
	v_pk_mul_f32 v[30:31], v[70:71], v[30:31]
	global_store_dwordx4 v72, v[16:19], s[6:7] offset:0
	global_store_dwordx4 v72, v[20:23], s[6:7] offset:1024
	global_store_dwordx4 v72, v[24:27], s[6:7] offset:2048
	global_store_dwordx4 v72, v[28:31], s[6:7] offset:3072
	s_add_u32 s6, s6, 0x1000
	s_addc_u32 s7, s7, 0
	global_load_dwordx4 v[16:19], v72, s[2:3] offset:0
	global_load_dwordx4 v[20:23], v72, s[2:3] offset:1024
	global_load_dwordx4 v[24:27], v72, s[2:3] offset:2048
	global_load_dwordx4 v[28:31], v72, s[2:3] offset:3072
	s_add_u32 s2, s2, 0x1000
	s_addc_u32 s3, s3, 0
	s_waitcnt vmcnt(16)
	v_pk_mul_f32 v[76:77], v[32:33], v[32:33]
	v_pk_mul_f32 v[78:79], v[34:35], v[34:35]
	v_pk_fma_f32 v[76:77], v[36:37], v[36:37], v[76:77]
	v_pk_fma_f32 v[78:79], v[38:39], v[38:39], v[78:79]
	v_pk_fma_f32 v[76:77], v[40:41], v[40:41], v[76:77]
	v_pk_fma_f32 v[78:79], v[42:43], v[42:43], v[78:79]
	v_pk_fma_f32 v[76:77], v[44:45], v[44:45], v[76:77]
	v_pk_fma_f32 v[78:79], v[46:47], v[46:47], v[78:79]
	s_nop 0
	v_pk_add_f32 v[76:77], v[76:77], v[78:79]
	s_nop 0
	v_add_f32_e32 v74, v76, v77
	s_nop 1
	v_add_f32_dpp v74, v74, v74 quad_perm:[1,0,3,2] row_mask:0xf bank_mask:0xf bound_ctrl:1
	s_nop 1
	v_add_f32_dpp v74, v74, v74 quad_perm:[2,3,0,1] row_mask:0xf bank_mask:0xf bound_ctrl:1
	s_nop 1
	v_add_f32_dpp v74, v74, v74 row_half_mirror row_mask:0xf bank_mask:0xf bound_ctrl:1
	s_nop 1
	v_add_f32_dpp v74, v74, v74 row_mirror row_mask:0xf bank_mask:0xf bound_ctrl:1
	s_nop 1
	v_add_f32_dpp v74, v74, v74 row_bcast:15 row_mask:0xa bank_mask:0xf
	s_nop 1
	v_add_f32_dpp v74, v74, v74 row_bcast:31 row_mask:0xc bank_mask:0xf
	s_nop 1
	v_readlane_b32 s1, v74, 63
	s_nop 3
	v_mov_b32_e32 v74, s1
	v_fmamk_f32 v74, v74, 0x3a800000, v73
	v_rsq_f32_e32 v74, v74
	s_nop 0
	v_pk_mul_f32 v[32:33], v[32:33], v[74:75] op_sel_hi:[1,0]
	v_pk_mul_f32 v[34:35], v[34:35], v[74:75] op_sel_hi:[1,0]
	v_pk_mul_f32 v[36:37], v[36:37], v[74:75] op_sel_hi:[1,0]
	v_pk_mul_f32 v[38:39], v[38:39], v[74:75] op_sel_hi:[1,0]
	v_pk_mul_f32 v[40:41], v[40:41], v[74:75] op_sel_hi:[1,0]
	v_pk_mul_f32 v[42:43], v[42:43], v[74:75] op_sel_hi:[1,0]
	v_pk_mul_f32 v[44:45], v[44:45], v[74:75] op_sel_hi:[1,0]
	v_pk_mul_f32 v[46:47], v[46:47], v[74:75] op_sel_hi:[1,0]
	v_pk_mul_f32 v[32:33], v[56:57], v[32:33]
	v_pk_mul_f32 v[34:35], v[58:59], v[34:35]
	v_pk_mul_f32 v[36:37], v[60:61], v[36:37]
	v_pk_mul_f32 v[38:39], v[62:63], v[38:39]
	v_pk_mul_f32 v[40:41], v[64:65], v[40:41]
	v_pk_mul_f32 v[42:43], v[66:67], v[42:43]
	v_pk_mul_f32 v[44:45], v[68:69], v[44:45]
	v_pk_mul_f32 v[46:47], v[70:71], v[46:47]
	global_store_dwordx4 v72, v[32:35], s[6:7] offset:0
	global_store_dwordx4 v72, v[36:39], s[6:7] offset:1024
	global_store_dwordx4 v72, v[40:43], s[6:7] offset:2048
	global_store_dwordx4 v72, v[44:47], s[6:7] offset:3072
	s_add_u32 s6, s6, 0x1000
	s_addc_u32 s7, s7, 0
	global_load_dwordx4 v[32:35], v72, s[2:3] offset:0
	global_load_dwordx4 v[36:39], v72, s[2:3] offset:1024
	global_load_dwordx4 v[40:43], v72, s[2:3] offset:2048
	global_load_dwordx4 v[44:47], v72, s[2:3] offset:3072
	s_add_u32 s2, s2, 0x1000
	s_addc_u32 s3, s3, 0
	s_waitcnt vmcnt(16)
	v_pk_mul_f32 v[76:77], v[0:1], v[0:1]
	v_pk_mul_f32 v[78:79], v[2:3], v[2:3]
	v_pk_fma_f32 v[76:77], v[4:5], v[4:5], v[76:77]
	v_pk_fma_f32 v[78:79], v[6:7], v[6:7], v[78:79]
	v_pk_fma_f32 v[76:77], v[8:9], v[8:9], v[76:77]
	v_pk_fma_f32 v[78:79], v[10:11], v[10:11], v[78:79]
	v_pk_fma_f32 v[76:77], v[12:13], v[12:13], v[76:77]
	v_pk_fma_f32 v[78:79], v[14:15], v[14:15], v[78:79]
	s_nop 0
	v_pk_add_f32 v[76:77], v[76:77], v[78:79]
	s_nop 0
	v_add_f32_e32 v74, v76, v77
	s_nop 1
	v_add_f32_dpp v74, v74, v74 quad_perm:[1,0,3,2] row_mask:0xf bank_mask:0xf bound_ctrl:1
	s_nop 1
	v_add_f32_dpp v74, v74, v74 quad_perm:[2,3,0,1] row_mask:0xf bank_mask:0xf bound_ctrl:1
	s_nop 1
	v_add_f32_dpp v74, v74, v74 row_half_mirror row_mask:0xf bank_mask:0xf bound_ctrl:1
	s_nop 1
	v_add_f32_dpp v74, v74, v74 row_mirror row_mask:0xf bank_mask:0xf bound_ctrl:1
	s_nop 1
	v_add_f32_dpp v74, v74, v74 row_bcast:15 row_mask:0xa bank_mask:0xf
	s_nop 1
	v_add_f32_dpp v74, v74, v74 row_bcast:31 row_mask:0xc bank_mask:0xf
	s_nop 1
	v_readlane_b32 s1, v74, 63
	s_nop 3
	v_mov_b32_e32 v74, s1
	v_fmamk_f32 v74, v74, 0x3a800000, v73
	v_rsq_f32_e32 v74, v74
	s_nop 0
	v_pk_mul_f32 v[0:1], v[0:1], v[74:75] op_sel_hi:[1,0]
	v_pk_mul_f32 v[2:3], v[2:3], v[74:75] op_sel_hi:[1,0]
	v_pk_mul_f32 v[4:5], v[4:5], v[74:75] op_sel_hi:[1,0]
	v_pk_mul_f32 v[6:7], v[6:7], v[74:75] op_sel_hi:[1,0]
	v_pk_mul_f32 v[8:9], v[8:9], v[74:75] op_sel_hi:[1,0]
	v_pk_mul_f32 v[10:11], v[10:11], v[74:75] op_sel_hi:[1,0]
	v_pk_mul_f32 v[12:13], v[12:13], v[74:75] op_sel_hi:[1,0]
	v_pk_mul_f32 v[14:15], v[14:15], v[74:75] op_sel_hi:[1,0]
	v_pk_mul_f32 v[0:1], v[56:57], v[0:1]
	v_pk_mul_f32 v[2:3], v[58:59], v[2:3]
	v_pk_mul_f32 v[4:5], v[60:61], v[4:5]
	v_pk_mul_f32 v[6:7], v[62:63], v[6:7]
	v_pk_mul_f32 v[8:9], v[64:65], v[8:9]
	v_pk_mul_f32 v[10:11], v[66:67], v[10:11]
	v_pk_mul_f32 v[12:13], v[68:69], v[12:13]
	v_pk_mul_f32 v[14:15], v[70:71], v[14:15]
	global_store_dwordx4 v72, v[0:3], s[6:7] offset:0
	global_store_dwordx4 v72, v[4:7], s[6:7] offset:1024
	global_store_dwordx4 v72, v[8:11], s[6:7] offset:2048
	global_store_dwordx4 v72, v[12:15], s[6:7] offset:3072
	s_add_u32 s6, s6, 0x1000
	s_addc_u32 s7, s7, 0
	global_load_dwordx4 v[0:3], v72, s[2:3] offset:0
	global_load_dwordx4 v[4:7], v72, s[2:3] offset:1024
	global_load_dwordx4 v[8:11], v72, s[2:3] offset:2048
	global_load_dwordx4 v[12:15], v72, s[2:3] offset:3072
	s_add_u32 s2, s2, 0x1000
	s_addc_u32 s3, s3, 0
	s_waitcnt vmcnt(16)
	v_pk_mul_f32 v[76:77], v[16:17], v[16:17]
	v_pk_mul_f32 v[78:79], v[18:19], v[18:19]
	v_pk_fma_f32 v[76:77], v[20:21], v[20:21], v[76:77]
	v_pk_fma_f32 v[78:79], v[22:23], v[22:23], v[78:79]
	v_pk_fma_f32 v[76:77], v[24:25], v[24:25], v[76:77]
	v_pk_fma_f32 v[78:79], v[26:27], v[26:27], v[78:79]
	v_pk_fma_f32 v[76:77], v[28:29], v[28:29], v[76:77]
	v_pk_fma_f32 v[78:79], v[30:31], v[30:31], v[78:79]
	s_nop 0
	v_pk_add_f32 v[76:77], v[76:77], v[78:79]
	s_nop 0
	v_add_f32_e32 v74, v76, v77
	s_nop 1
	v_add_f32_dpp v74, v74, v74 quad_perm:[1,0,3,2] row_mask:0xf bank_mask:0xf bound_ctrl:1
	s_nop 1
	v_add_f32_dpp v74, v74, v74 quad_perm:[2,3,0,1] row_mask:0xf bank_mask:0xf bound_ctrl:1
	s_nop 1
	v_add_f32_dpp v74, v74, v74 row_half_mirror row_mask:0xf bank_mask:0xf bound_ctrl:1
	s_nop 1
	v_add_f32_dpp v74, v74, v74 row_mirror row_mask:0xf bank_mask:0xf bound_ctrl:1
	s_nop 1
	v_add_f32_dpp v74, v74, v74 row_bcast:15 row_mask:0xa bank_mask:0xf
	s_nop 1
	v_add_f32_dpp v74, v74, v74 row_bcast:31 row_mask:0xc bank_mask:0xf
	s_nop 1
	v_readlane_b32 s1, v74, 63
	s_nop 3
	v_mov_b32_e32 v74, s1
	v_fmamk_f32 v74, v74, 0x3a800000, v73
	v_rsq_f32_e32 v74, v74
	s_nop 0
	v_pk_mul_f32 v[16:17], v[16:17], v[74:75] op_sel_hi:[1,0]
	v_pk_mul_f32 v[18:19], v[18:19], v[74:75] op_sel_hi:[1,0]
	v_pk_mul_f32 v[20:21], v[20:21], v[74:75] op_sel_hi:[1,0]
	v_pk_mul_f32 v[22:23], v[22:23], v[74:75] op_sel_hi:[1,0]
	v_pk_mul_f32 v[24:25], v[24:25], v[74:75] op_sel_hi:[1,0]
	v_pk_mul_f32 v[26:27], v[26:27], v[74:75] op_sel_hi:[1,0]
	v_pk_mul_f32 v[28:29], v[28:29], v[74:75] op_sel_hi:[1,0]
	v_pk_mul_f32 v[30:31], v[30:31], v[74:75] op_sel_hi:[1,0]
	v_pk_mul_f32 v[16:17], v[56:57], v[16:17]
	v_pk_mul_f32 v[18:19], v[58:59], v[18:19]
	v_pk_mul_f32 v[20:21], v[60:61], v[20:21]
	v_pk_mul_f32 v[22:23], v[62:63], v[22:23]
	v_pk_mul_f32 v[24:25], v[64:65], v[24:25]
	v_pk_mul_f32 v[26:27], v[66:67], v[26:27]
	v_pk_mul_f32 v[28:29], v[68:69], v[28:29]
	v_pk_mul_f32 v[30:31], v[70:71], v[30:31]
	global_store_dwordx4 v72, v[16:19], s[6:7] offset:0
	global_store_dwordx4 v72, v[20:23], s[6:7] offset:1024
	global_store_dwordx4 v72, v[24:27], s[6:7] offset:2048
	global_store_dwordx4 v72, v[28:31], s[6:7] offset:3072
	s_add_u32 s6, s6, 0x1000
	s_addc_u32 s7, s7, 0
	global_load_dwordx4 v[16:19], v72, s[2:3] offset:0
	global_load_dwordx4 v[20:23], v72, s[2:3] offset:1024
	global_load_dwordx4 v[24:27], v72, s[2:3] offset:2048
	global_load_dwordx4 v[28:31], v72, s[2:3] offset:3072
	s_add_u32 s2, s2, 0x1000
	s_addc_u32 s3, s3, 0
	s_waitcnt vmcnt(16)
	v_pk_mul_f32 v[76:77], v[32:33], v[32:33]
	v_pk_mul_f32 v[78:79], v[34:35], v[34:35]
	v_pk_fma_f32 v[76:77], v[36:37], v[36:37], v[76:77]
	v_pk_fma_f32 v[78:79], v[38:39], v[38:39], v[78:79]
	v_pk_fma_f32 v[76:77], v[40:41], v[40:41], v[76:77]
	v_pk_fma_f32 v[78:79], v[42:43], v[42:43], v[78:79]
	v_pk_fma_f32 v[76:77], v[44:45], v[44:45], v[76:77]
	v_pk_fma_f32 v[78:79], v[46:47], v[46:47], v[78:79]
	s_nop 0
	v_pk_add_f32 v[76:77], v[76:77], v[78:79]
	s_nop 0
	v_add_f32_e32 v74, v76, v77
	s_nop 1
	v_add_f32_dpp v74, v74, v74 quad_perm:[1,0,3,2] row_mask:0xf bank_mask:0xf bound_ctrl:1
	s_nop 1
	v_add_f32_dpp v74, v74, v74 quad_perm:[2,3,0,1] row_mask:0xf bank_mask:0xf bound_ctrl:1
	s_nop 1
	v_add_f32_dpp v74, v74, v74 row_half_mirror row_mask:0xf bank_mask:0xf bound_ctrl:1
	s_nop 1
	v_add_f32_dpp v74, v74, v74 row_mirror row_mask:0xf bank_mask:0xf bound_ctrl:1
	s_nop 1
	v_add_f32_dpp v74, v74, v74 row_bcast:15 row_mask:0xa bank_mask:0xf
	s_nop 1
	v_add_f32_dpp v74, v74, v74 row_bcast:31 row_mask:0xc bank_mask:0xf
	s_nop 1
	v_readlane_b32 s1, v74, 63
	s_nop 3
	v_mov_b32_e32 v74, s1
	v_fmamk_f32 v74, v74, 0x3a800000, v73
	v_rsq_f32_e32 v74, v74
	s_nop 0
	v_pk_mul_f32 v[32:33], v[32:33], v[74:75] op_sel_hi:[1,0]
	v_pk_mul_f32 v[34:35], v[34:35], v[74:75] op_sel_hi:[1,0]
	v_pk_mul_f32 v[36:37], v[36:37], v[74:75] op_sel_hi:[1,0]
	v_pk_mul_f32 v[38:39], v[38:39], v[74:75] op_sel_hi:[1,0]
	v_pk_mul_f32 v[40:41], v[40:41], v[74:75] op_sel_hi:[1,0]
	v_pk_mul_f32 v[42:43], v[42:43], v[74:75] op_sel_hi:[1,0]
	v_pk_mul_f32 v[44:45], v[44:45], v[74:75] op_sel_hi:[1,0]
	v_pk_mul_f32 v[46:47], v[46:47], v[74:75] op_sel_hi:[1,0]
	v_pk_mul_f32 v[32:33], v[56:57], v[32:33]
	v_pk_mul_f32 v[34:35], v[58:59], v[34:35]
	v_pk_mul_f32 v[36:37], v[60:61], v[36:37]
	v_pk_mul_f32 v[38:39], v[62:63], v[38:39]
	v_pk_mul_f32 v[40:41], v[64:65], v[40:41]
	v_pk_mul_f32 v[42:43], v[66:67], v[42:43]
	v_pk_mul_f32 v[44:45], v[68:69], v[44:45]
	v_pk_mul_f32 v[46:47], v[70:71], v[46:47]
	global_store_dwordx4 v72, v[32:35], s[6:7] offset:0
	global_store_dwordx4 v72, v[36:39], s[6:7] offset:1024
	global_store_dwordx4 v72, v[40:43], s[6:7] offset:2048
	global_store_dwordx4 v72, v[44:47], s[6:7] offset:3072
	s_add_u32 s6, s6, 0x1000
	s_addc_u32 s7, s7, 0
	global_load_dwordx4 v[32:35], v72, s[2:3] offset:0
	global_load_dwordx4 v[36:39], v72, s[2:3] offset:1024
	global_load_dwordx4 v[40:43], v72, s[2:3] offset:2048
	global_load_dwordx4 v[44:47], v72, s[2:3] offset:3072
	s_add_u32 s2, s2, 0x1000
	s_addc_u32 s3, s3, 0
	s_waitcnt vmcnt(16)
	v_pk_mul_f32 v[76:77], v[0:1], v[0:1]
	v_pk_mul_f32 v[78:79], v[2:3], v[2:3]
	v_pk_fma_f32 v[76:77], v[4:5], v[4:5], v[76:77]
	v_pk_fma_f32 v[78:79], v[6:7], v[6:7], v[78:79]
	v_pk_fma_f32 v[76:77], v[8:9], v[8:9], v[76:77]
	v_pk_fma_f32 v[78:79], v[10:11], v[10:11], v[78:79]
	v_pk_fma_f32 v[76:77], v[12:13], v[12:13], v[76:77]
	v_pk_fma_f32 v[78:79], v[14:15], v[14:15], v[78:79]
	s_nop 0
	v_pk_add_f32 v[76:77], v[76:77], v[78:79]
	s_nop 0
	v_add_f32_e32 v74, v76, v77
	s_nop 1
	v_add_f32_dpp v74, v74, v74 quad_perm:[1,0,3,2] row_mask:0xf bank_mask:0xf bound_ctrl:1
	s_nop 1
	v_add_f32_dpp v74, v74, v74 quad_perm:[2,3,0,1] row_mask:0xf bank_mask:0xf bound_ctrl:1
	s_nop 1
	v_add_f32_dpp v74, v74, v74 row_half_mirror row_mask:0xf bank_mask:0xf bound_ctrl:1
	s_nop 1
	v_add_f32_dpp v74, v74, v74 row_mirror row_mask:0xf bank_mask:0xf bound_ctrl:1
	s_nop 1
	v_add_f32_dpp v74, v74, v74 row_bcast:15 row_mask:0xa bank_mask:0xf
	s_nop 1
	v_add_f32_dpp v74, v74, v74 row_bcast:31 row_mask:0xc bank_mask:0xf
	s_nop 1
	v_readlane_b32 s1, v74, 63
	s_nop 3
	v_mov_b32_e32 v74, s1
	v_fmamk_f32 v74, v74, 0x3a800000, v73
	v_rsq_f32_e32 v74, v74
	s_nop 0
	v_pk_mul_f32 v[0:1], v[0:1], v[74:75] op_sel_hi:[1,0]
	v_pk_mul_f32 v[2:3], v[2:3], v[74:75] op_sel_hi:[1,0]
	v_pk_mul_f32 v[4:5], v[4:5], v[74:75] op_sel_hi:[1,0]
	v_pk_mul_f32 v[6:7], v[6:7], v[74:75] op_sel_hi:[1,0]
	v_pk_mul_f32 v[8:9], v[8:9], v[74:75] op_sel_hi:[1,0]
	v_pk_mul_f32 v[10:11], v[10:11], v[74:75] op_sel_hi:[1,0]
	v_pk_mul_f32 v[12:13], v[12:13], v[74:75] op_sel_hi:[1,0]
	v_pk_mul_f32 v[14:15], v[14:15], v[74:75] op_sel_hi:[1,0]
	v_pk_mul_f32 v[0:1], v[56:57], v[0:1]
	v_pk_mul_f32 v[2:3], v[58:59], v[2:3]
	v_pk_mul_f32 v[4:5], v[60:61], v[4:5]
	v_pk_mul_f32 v[6:7], v[62:63], v[6:7]
	v_pk_mul_f32 v[8:9], v[64:65], v[8:9]
	v_pk_mul_f32 v[10:11], v[66:67], v[10:11]
	v_pk_mul_f32 v[12:13], v[68:69], v[12:13]
	v_pk_mul_f32 v[14:15], v[70:71], v[14:15]
	global_store_dwordx4 v72, v[0:3], s[6:7] offset:0
	global_store_dwordx4 v72, v[4:7], s[6:7] offset:1024
	global_store_dwordx4 v72, v[8:11], s[6:7] offset:2048
	global_store_dwordx4 v72, v[12:15], s[6:7] offset:3072
	s_add_u32 s6, s6, 0x1000
	s_addc_u32 s7, s7, 0
	global_load_dwordx4 v[0:3], v72, s[2:3] offset:0
	global_load_dwordx4 v[4:7], v72, s[2:3] offset:1024
	global_load_dwordx4 v[8:11], v72, s[2:3] offset:2048
	global_load_dwordx4 v[12:15], v72, s[2:3] offset:3072
	s_add_u32 s2, s2, 0x1000
	s_addc_u32 s3, s3, 0
	s_waitcnt vmcnt(16)
	v_pk_mul_f32 v[76:77], v[16:17], v[16:17]
	v_pk_mul_f32 v[78:79], v[18:19], v[18:19]
	v_pk_fma_f32 v[76:77], v[20:21], v[20:21], v[76:77]
	v_pk_fma_f32 v[78:79], v[22:23], v[22:23], v[78:79]
	v_pk_fma_f32 v[76:77], v[24:25], v[24:25], v[76:77]
	v_pk_fma_f32 v[78:79], v[26:27], v[26:27], v[78:79]
	v_pk_fma_f32 v[76:77], v[28:29], v[28:29], v[76:77]
	v_pk_fma_f32 v[78:79], v[30:31], v[30:31], v[78:79]
	s_nop 0
	v_pk_add_f32 v[76:77], v[76:77], v[78:79]
	s_nop 0
	v_add_f32_e32 v74, v76, v77
	s_nop 1
	v_add_f32_dpp v74, v74, v74 quad_perm:[1,0,3,2] row_mask:0xf bank_mask:0xf bound_ctrl:1
	s_nop 1
	v_add_f32_dpp v74, v74, v74 quad_perm:[2,3,0,1] row_mask:0xf bank_mask:0xf bound_ctrl:1
	s_nop 1
	v_add_f32_dpp v74, v74, v74 row_half_mirror row_mask:0xf bank_mask:0xf bound_ctrl:1
	s_nop 1
	v_add_f32_dpp v74, v74, v74 row_mirror row_mask:0xf bank_mask:0xf bound_ctrl:1
	s_nop 1
	v_add_f32_dpp v74, v74, v74 row_bcast:15 row_mask:0xa bank_mask:0xf
	s_nop 1
	v_add_f32_dpp v74, v74, v74 row_bcast:31 row_mask:0xc bank_mask:0xf
	s_nop 1
	v_readlane_b32 s1, v74, 63
	s_nop 3
	v_mov_b32_e32 v74, s1
	v_fmamk_f32 v74, v74, 0x3a800000, v73
	v_rsq_f32_e32 v74, v74
	s_nop 0
	v_pk_mul_f32 v[16:17], v[16:17], v[74:75] op_sel_hi:[1,0]
	v_pk_mul_f32 v[18:19], v[18:19], v[74:75] op_sel_hi:[1,0]
	v_pk_mul_f32 v[20:21], v[20:21], v[74:75] op_sel_hi:[1,0]
	v_pk_mul_f32 v[22:23], v[22:23], v[74:75] op_sel_hi:[1,0]
	v_pk_mul_f32 v[24:25], v[24:25], v[74:75] op_sel_hi:[1,0]
	v_pk_mul_f32 v[26:27], v[26:27], v[74:75] op_sel_hi:[1,0]
	v_pk_mul_f32 v[28:29], v[28:29], v[74:75] op_sel_hi:[1,0]
	v_pk_mul_f32 v[30:31], v[30:31], v[74:75] op_sel_hi:[1,0]
	v_pk_mul_f32 v[16:17], v[56:57], v[16:17]
	v_pk_mul_f32 v[18:19], v[58:59], v[18:19]
	v_pk_mul_f32 v[20:21], v[60:61], v[20:21]
	v_pk_mul_f32 v[22:23], v[62:63], v[22:23]
	v_pk_mul_f32 v[24:25], v[64:65], v[24:25]
	v_pk_mul_f32 v[26:27], v[66:67], v[26:27]
	v_pk_mul_f32 v[28:29], v[68:69], v[28:29]
	v_pk_mul_f32 v[30:31], v[70:71], v[30:31]
	global_store_dwordx4 v72, v[16:19], s[6:7] offset:0
	global_store_dwordx4 v72, v[20:23], s[6:7] offset:1024
	global_store_dwordx4 v72, v[24:27], s[6:7] offset:2048
	global_store_dwordx4 v72, v[28:31], s[6:7] offset:3072
	s_add_u32 s6, s6, 0x1000
	s_addc_u32 s7, s7, 0
	s_waitcnt vmcnt(12)
	v_pk_mul_f32 v[76:77], v[32:33], v[32:33]
	v_pk_mul_f32 v[78:79], v[34:35], v[34:35]
	v_pk_fma_f32 v[76:77], v[36:37], v[36:37], v[76:77]
	v_pk_fma_f32 v[78:79], v[38:39], v[38:39], v[78:79]
	v_pk_fma_f32 v[76:77], v[40:41], v[40:41], v[76:77]
	v_pk_fma_f32 v[78:79], v[42:43], v[42:43], v[78:79]
	v_pk_fma_f32 v[76:77], v[44:45], v[44:45], v[76:77]
	v_pk_fma_f32 v[78:79], v[46:47], v[46:47], v[78:79]
	s_nop 0
	v_pk_add_f32 v[76:77], v[76:77], v[78:79]
	s_nop 0
	v_add_f32_e32 v74, v76, v77
	s_nop 1
	v_add_f32_dpp v74, v74, v74 quad_perm:[1,0,3,2] row_mask:0xf bank_mask:0xf bound_ctrl:1
	s_nop 1
	v_add_f32_dpp v74, v74, v74 quad_perm:[2,3,0,1] row_mask:0xf bank_mask:0xf bound_ctrl:1
	s_nop 1
	v_add_f32_dpp v74, v74, v74 row_half_mirror row_mask:0xf bank_mask:0xf bound_ctrl:1
	s_nop 1
	v_add_f32_dpp v74, v74, v74 row_mirror row_mask:0xf bank_mask:0xf bound_ctrl:1
	s_nop 1
	v_add_f32_dpp v74, v74, v74 row_bcast:15 row_mask:0xa bank_mask:0xf
	s_nop 1
	v_add_f32_dpp v74, v74, v74 row_bcast:31 row_mask:0xc bank_mask:0xf
	s_nop 1
	v_readlane_b32 s1, v74, 63
	s_nop 3
	v_mov_b32_e32 v74, s1
	v_fmamk_f32 v74, v74, 0x3a800000, v73
	v_rsq_f32_e32 v74, v74
	s_nop 0
	v_pk_mul_f32 v[32:33], v[32:33], v[74:75] op_sel_hi:[1,0]
	v_pk_mul_f32 v[34:35], v[34:35], v[74:75] op_sel_hi:[1,0]
	v_pk_mul_f32 v[36:37], v[36:37], v[74:75] op_sel_hi:[1,0]
	v_pk_mul_f32 v[38:39], v[38:39], v[74:75] op_sel_hi:[1,0]
	v_pk_mul_f32 v[40:41], v[40:41], v[74:75] op_sel_hi:[1,0]
	v_pk_mul_f32 v[42:43], v[42:43], v[74:75] op_sel_hi:[1,0]
	v_pk_mul_f32 v[44:45], v[44:45], v[74:75] op_sel_hi:[1,0]
	v_pk_mul_f32 v[46:47], v[46:47], v[74:75] op_sel_hi:[1,0]
	v_pk_mul_f32 v[32:33], v[56:57], v[32:33]
	v_pk_mul_f32 v[34:35], v[58:59], v[34:35]
	v_pk_mul_f32 v[36:37], v[60:61], v[36:37]
	v_pk_mul_f32 v[38:39], v[62:63], v[38:39]
	v_pk_mul_f32 v[40:41], v[64:65], v[40:41]
	v_pk_mul_f32 v[42:43], v[66:67], v[42:43]
	v_pk_mul_f32 v[44:45], v[68:69], v[44:45]
	v_pk_mul_f32 v[46:47], v[70:71], v[46:47]
	global_store_dwordx4 v72, v[32:35], s[6:7] offset:0
	global_store_dwordx4 v72, v[36:39], s[6:7] offset:1024
	global_store_dwordx4 v72, v[40:43], s[6:7] offset:2048
	global_store_dwordx4 v72, v[44:47], s[6:7] offset:3072
	s_add_u32 s6, s6, 0x1000
	s_addc_u32 s7, s7, 0
	s_waitcnt vmcnt(8)
	v_pk_mul_f32 v[76:77], v[0:1], v[0:1]
	v_pk_mul_f32 v[78:79], v[2:3], v[2:3]
	v_pk_fma_f32 v[76:77], v[4:5], v[4:5], v[76:77]
	v_pk_fma_f32 v[78:79], v[6:7], v[6:7], v[78:79]
	v_pk_fma_f32 v[76:77], v[8:9], v[8:9], v[76:77]
	v_pk_fma_f32 v[78:79], v[10:11], v[10:11], v[78:79]
	v_pk_fma_f32 v[76:77], v[12:13], v[12:13], v[76:77]
	v_pk_fma_f32 v[78:79], v[14:15], v[14:15], v[78:79]
	s_nop 0
	v_pk_add_f32 v[76:77], v[76:77], v[78:79]
	s_nop 0
	v_add_f32_e32 v74, v76, v77
	s_nop 1
	v_add_f32_dpp v74, v74, v74 quad_perm:[1,0,3,2] row_mask:0xf bank_mask:0xf bound_ctrl:1
	s_nop 1
	v_add_f32_dpp v74, v74, v74 quad_perm:[2,3,0,1] row_mask:0xf bank_mask:0xf bound_ctrl:1
	s_nop 1
	v_add_f32_dpp v74, v74, v74 row_half_mirror row_mask:0xf bank_mask:0xf bound_ctrl:1
	s_nop 1
	v_add_f32_dpp v74, v74, v74 row_mirror row_mask:0xf bank_mask:0xf bound_ctrl:1
	s_nop 1
	v_add_f32_dpp v74, v74, v74 row_bcast:15 row_mask:0xa bank_mask:0xf
	s_nop 1
	v_add_f32_dpp v74, v74, v74 row_bcast:31 row_mask:0xc bank_mask:0xf
	s_nop 1
	v_readlane_b32 s1, v74, 63
	s_nop 3
	v_mov_b32_e32 v74, s1
	v_fmamk_f32 v74, v74, 0x3a800000, v73
	v_rsq_f32_e32 v74, v74
	s_nop 0
	v_pk_mul_f32 v[0:1], v[0:1], v[74:75] op_sel_hi:[1,0]
	v_pk_mul_f32 v[2:3], v[2:3], v[74:75] op_sel_hi:[1,0]
	v_pk_mul_f32 v[4:5], v[4:5], v[74:75] op_sel_hi:[1,0]
	v_pk_mul_f32 v[6:7], v[6:7], v[74:75] op_sel_hi:[1,0]
	v_pk_mul_f32 v[8:9], v[8:9], v[74:75] op_sel_hi:[1,0]
	v_pk_mul_f32 v[10:11], v[10:11], v[74:75] op_sel_hi:[1,0]
	v_pk_mul_f32 v[12:13], v[12:13], v[74:75] op_sel_hi:[1,0]
	v_pk_mul_f32 v[14:15], v[14:15], v[74:75] op_sel_hi:[1,0]
	v_pk_mul_f32 v[0:1], v[56:57], v[0:1]
	v_pk_mul_f32 v[2:3], v[58:59], v[2:3]
	v_pk_mul_f32 v[4:5], v[60:61], v[4:5]
	v_pk_mul_f32 v[6:7], v[62:63], v[6:7]
	v_pk_mul_f32 v[8:9], v[64:65], v[8:9]
	v_pk_mul_f32 v[10:11], v[66:67], v[10:11]
	v_pk_mul_f32 v[12:13], v[68:69], v[12:13]
	v_pk_mul_f32 v[14:15], v[70:71], v[14:15]
	global_store_dwordx4 v72, v[0:3], s[6:7] offset:0
	global_store_dwordx4 v72, v[4:7], s[6:7] offset:1024
	global_store_dwordx4 v72, v[8:11], s[6:7] offset:2048
	global_store_dwordx4 v72, v[12:15], s[6:7] offset:3072
	s_add_u32 s6, s6, 0x1000
	s_addc_u32 s7, s7, 0
	s_branch .LBB0_1719
.Lnorm_orig_4:
	s_load_dwordx4 s[0:3], s[6:7], 0xd0
	v_ashrrev_i32_e32 v49, 31, v48
	v_lshlrev_b32_e32 v0, 4, v16
	v_lshlrev_b64 v[18:19], 12, v[48:49]
	v_and_b32_e32 v20, 0x3f0, v0
	s_waitcnt lgkmcnt(0)
	v_lshl_add_u64 v[0:1], s[2:3], 0, v[18:19]
	v_mov_b32_e32 v21, 0
	v_lshl_add_u64 v[0:1], v[0:1], 0, v[20:21]
	global_load_dwordx4 v[12:15], v[0:1], off
	global_load_dwordx4 v[8:11], v[0:1], off offset:1024
	global_load_dwordx4 v[4:7], v[0:1], off offset:2048
	s_nop 0
	global_load_dwordx4 v[0:3], v[0:1], off offset:3072
	v_cmp_lt_i32_e32 vcc, v171, v165
	v_and_b32_e32 v16, 63, v16
	v_lshl_or_b32 v18, v16, 4, v18
	v_cndmask_b32_e32 v17, v164, v171, vcc
	v_cmp_lt_i32_e32 vcc, v170, v165
	v_lshlrev_b32_e32 v49, 2, v17
	v_mov_b32_e32 v56, -1
	v_cndmask_b32_e32 v17, v164, v170, vcc
	v_cmp_lt_i32_e32 vcc, v169, v165
	v_lshlrev_b32_e32 v55, 2, v17
	v_lshl_add_u64 v[50:51], s[0:1], 0, v[20:21]
	v_cndmask_b32_e32 v17, v164, v169, vcc
	v_cmp_lt_i32_e32 vcc, v168, v165
	v_lshlrev_b32_e32 v57, 2, v17
	s_mov_b64 s[6:7], 0
	v_cndmask_b32_e32 v17, v164, v168, vcc
	v_cmp_lt_i32_e32 vcc, v167, v165
	v_lshlrev_b32_e32 v58, 2, v17
	v_mov_b32_e32 v61, 0x358637bd
	v_cndmask_b32_e32 v17, v164, v167, vcc
	v_cmp_lt_i32_e32 vcc, v166, v165
	v_lshlrev_b32_e32 v59, 2, v17
	s_mov_b32 s10, 0x800000
	v_cndmask_b32_e32 v17, v164, v166, vcc
	v_lshlrev_b32_e32 v60, 2, v17
	v_lshl_add_u64 v[16:17], s[2:3], 0, v[18:19]
	s_mov_b64 s[2:3], 0x1000
	v_lshl_add_u64 v[52:53], v[16:17], 0, s[2:3]
	s_branch .LBB0_1715
